# P0 loads hoisted to entry + XCD-local column blocks + b_ada prefetch; nsa V^T transposes with all loads in flight over all waves; cmp-branch K/V staging de-serialized
# speedup vs baseline: 1.0668x; 1.0049x over previous
_Z14fwd_megakernel4Args:
	s_mov_b32 s80, s2
	s_load_dwordx2 s[76:77], s[0:1], 0xb0
	s_load_dword s2, s[0:1], 0xb8
	s_load_dwordx2 s[98:99], s[0:1], 0x18
	s_load_dwordx2 s[100:101], s[0:1], 0x20
	v_and_b32_e32 v1, 0x3ff, v0
	s_add_u32 s10, s0, 0xb0
	v_readfirstlane_b32 s75, v1
	s_addc_u32 s11, s1, 0
	s_waitcnt lgkmcnt(0)
	v_writelane_b32 v247, s2, 0
	s_mov_b32 s2, -1
	s_nop 0
	v_mbcnt_lo_u32_b32 v2, s2, 0
	v_mbcnt_hi_u32_b32 v2, s2, v2
	s_and_b32 s2, s75, 0xffffffc0
	v_add_u32_e32 v2, s2, v2
	v_cmp_gt_i32_e32 vcc, 22, v2
	v_writelane_b32 v247, s2, 1
	s_and_saveexec_b64 s[2:3], vcc
	s_cbranch_execz .LBB0_6
	v_cmp_lt_i32_e32 vcc, 19, v2
	s_and_saveexec_b64 s[4:5], vcc
	s_xor_b64 s[4:5], exec, s[4:5]
	s_cbranch_execz .LBB0_3
	s_load_dwordx4 s[12:15], s[0:1], 0xa0
	v_cmp_eq_u32_e32 vcc, 20, v2
	s_waitcnt lgkmcnt(0)
	v_mov_b32_e32 v3, s15
	v_mov_b32_e32 v4, s13
	v_mov_b32_e32 v6, s14
	v_mov_b32_e32 v7, s12
	v_cndmask_b32_e32 v5, v3, v4, vcc
	v_cndmask_b32_e32 v4, v6, v7, vcc

.LBB0_6:
	s_or_b64 exec, exec, s[2:3]
	v_mul_u32_u24_e32 v150, 0xaab, v1
	v_lshrrev_b32_e32 v150, 16, v150
	v_mul_u32_u24_e32 v151, 24, v150
	v_sub_u32_e32 v151, v1, v151
	v_mul_u32_u24_e32 v166, 0x6000, v150
	v_lshl_add_u32 v166, v151, 2, v166
	s_and_b32 s4, s80, 7
	s_lshl_b32 s4, s4, 5
	s_lshr_b32 s5, s80, 3
	s_or_b32 s4, s4, s5
	s_cmpk_lg_i32 s76, 0x100
	s_cselect_b32 s4, s80, s4
	s_mul_i32 s4, s4, 0x60
	v_lshl_add_u32 v152, v151, 2, s4
	global_load_dword v149, v152, s[100:101]
	s_add_u32 s100, s98, s4
	s_addc_u32 s101, s99, 0
	global_load_dword v100, v166, s[100:101]
	s_add_u32 s100, s100, 0x7e000
	s_addc_u32 s101, s101, 0
	global_load_dword v101, v166, s[100:101]
	s_add_u32 s100, s100, 0x7e000
	s_addc_u32 s101, s101, 0
	global_load_dword v102, v166, s[100:101]
	s_add_u32 s100, s100, 0x7e000
	s_addc_u32 s101, s101, 0
	global_load_dword v103, v166, s[100:101]
	s_add_u32 s100, s100, 0x7e000
	s_addc_u32 s101, s101, 0
	global_load_dword v104, v166, s[100:101]
	s_add_u32 s100, s100, 0x7e000
	s_addc_u32 s101, s101, 0
	global_load_dword v105, v166, s[100:101]
	s_add_u32 s100, s100, 0x7e000
	s_addc_u32 s101, s101, 0
	global_load_dword v106, v166, s[100:101]
	s_add_u32 s100, s100, 0x7e000
	s_addc_u32 s101, s101, 0
	global_load_dword v107, v166, s[100:101]
	s_add_u32 s100, s100, 0x7e000
	s_addc_u32 s101, s101, 0
	global_load_dword v108, v166, s[100:101]
	s_add_u32 s100, s100, 0x7e000
	s_addc_u32 s101, s101, 0
	global_load_dword v109, v166, s[100:101]
	s_add_u32 s100, s100, 0x7e000
	s_addc_u32 s101, s101, 0
	global_load_dword v110, v166, s[100:101]
	s_add_u32 s100, s100, 0x7e000
	s_addc_u32 s101, s101, 0
	global_load_dword v111, v166, s[100:101]
	s_add_u32 s100, s100, 0x7e000
	s_addc_u32 s101, s101, 0
	global_load_dword v112, v166, s[100:101]
	s_add_u32 s100, s100, 0x7e000
	s_addc_u32 s101, s101, 0
	global_load_dword v113, v166, s[100:101]
	s_add_u32 s100, s100, 0x7e000
	s_addc_u32 s101, s101, 0
	global_load_dword v114, v166, s[100:101]
	s_add_u32 s100, s100, 0x7e000
	s_addc_u32 s101, s101, 0
	global_load_dword v115, v166, s[100:101]
	s_add_u32 s100, s100, 0x7e000
	s_addc_u32 s101, s101, 0
	global_load_dword v116, v166, s[100:101]
	s_add_u32 s100, s100, 0x7e000
	s_addc_u32 s101, s101, 0
	global_load_dword v117, v166, s[100:101]
	s_add_u32 s100, s100, 0x7e000
	s_addc_u32 s101, s101, 0
	global_load_dword v118, v166, s[100:101]
	s_add_u32 s100, s100, 0x7e000
	s_addc_u32 s101, s101, 0
	global_load_dword v119, v166, s[100:101]
	s_add_u32 s100, s100, 0x7e000
	s_addc_u32 s101, s101, 0
	global_load_dword v120, v166, s[100:101]
	s_add_u32 s100, s100, 0x7e000
	s_addc_u32 s101, s101, 0
	global_load_dword v121, v166, s[100:101]
	s_add_u32 s100, s100, 0x7e000
	s_addc_u32 s101, s101, 0
	global_load_dword v122, v166, s[100:101]
	s_add_u32 s100, s100, 0x7e000
	s_addc_u32 s101, s101, 0
	global_load_dword v123, v166, s[100:101]
	s_add_u32 s100, s100, 0x7e000
	s_addc_u32 s101, s101, 0
	global_load_dword v124, v166, s[100:101]
	s_add_u32 s100, s100, 0x7e000
	s_addc_u32 s101, s101, 0
	global_load_dword v125, v166, s[100:101]
	s_add_u32 s100, s100, 0x7e000
	s_addc_u32 s101, s101, 0
	global_load_dword v126, v166, s[100:101]
	s_add_u32 s100, s100, 0x7e000
	s_addc_u32 s101, s101, 0
	global_load_dword v127, v166, s[100:101]
	s_add_u32 s100, s100, 0x7e000
	s_addc_u32 s101, s101, 0
	global_load_dword v128, v166, s[100:101]
	s_add_u32 s100, s100, 0x7e000
	s_addc_u32 s101, s101, 0
	global_load_dword v129, v166, s[100:101]
	s_add_u32 s100, s100, 0x7e000
	s_addc_u32 s101, s101, 0
	global_load_dword v130, v166, s[100:101]
	s_add_u32 s100, s100, 0x7e000
	s_addc_u32 s101, s101, 0
	global_load_dword v131, v166, s[100:101]
	s_add_u32 s100, s100, 0x7e000
	s_addc_u32 s101, s101, 0
	global_load_dword v132, v166, s[100:101]
	s_add_u32 s100, s100, 0x7e000
	s_addc_u32 s101, s101, 0
	global_load_dword v133, v166, s[100:101]
	s_add_u32 s100, s100, 0x7e000
	s_addc_u32 s101, s101, 0
	global_load_dword v134, v166, s[100:101]
	s_add_u32 s100, s100, 0x7e000
	s_addc_u32 s101, s101, 0
	global_load_dword v135, v166, s[100:101]
	s_add_u32 s100, s100, 0x7e000
	s_addc_u32 s101, s101, 0
	global_load_dword v136, v166, s[100:101]
	s_add_u32 s100, s100, 0x7e000
	s_addc_u32 s101, s101, 0
	global_load_dword v137, v166, s[100:101]
	s_add_u32 s100, s100, 0x7e000
	s_addc_u32 s101, s101, 0
	global_load_dword v138, v166, s[100:101]
	s_add_u32 s100, s100, 0x7e000
	s_addc_u32 s101, s101, 0
	global_load_dword v139, v166, s[100:101]
	s_add_u32 s100, s100, 0x7e000
	s_addc_u32 s101, s101, 0
	global_load_dword v140, v166, s[100:101]
	s_add_u32 s100, s100, 0x7e000
	s_addc_u32 s101, s101, 0
	global_load_dword v141, v166, s[100:101]
	s_add_u32 s100, s100, 0x7e000
	s_addc_u32 s101, s101, 0
	global_load_dword v142, v166, s[100:101]
	s_add_u32 s100, s100, 0x7e000
	s_addc_u32 s101, s101, 0
	global_load_dword v143, v166, s[100:101]
	s_add_u32 s100, s100, 0x7e000
	s_addc_u32 s101, s101, 0
	global_load_dword v144, v166, s[100:101]
	s_add_u32 s100, s100, 0x7e000
	s_addc_u32 s101, s101, 0
	global_load_dword v145, v166, s[100:101]
	s_add_u32 s100, s100, 0x7e000
	s_addc_u32 s101, s101, 0
	global_load_dword v146, v166, s[100:101]
	s_add_u32 s100, s100, 0x7e000
	s_addc_u32 s101, s101, 0
	global_load_dword v147, v166, s[100:101]
	s_add_u32 s100, s100, 0x7e000
	s_addc_u32 s101, s101, 0
	v_cmp_gt_u32_e32 vcc, 16, v150
	s_and_saveexec_b64 s[4:5], vcc
	s_cbranch_execz .Lp0h_skip
	global_load_dword v148, v166, s[100:101]
.Lp0h_skip:
	s_mov_b64 exec, s[4:5]
	v_cmp_eq_u32_e64 s[82:83], 0, v2
	s_and_saveexec_b64 s[2:3], s[82:83]
	s_cbranch_execz .LBB0_8
	s_add_i32 s4, 0, 0x23fc0
	v_mov_b32_e32 v2, 0
	v_mov_b32_e32 v3, v2
	v_mov_b32_e32 v4, v2
	v_mov_b32_e32 v5, s4
	ds_write_b96 v5, v[2:4]

.LBB0_11:
	s_or_b64 exec, exec, s[0:1]
	s_add_i32 s1, 0, 0x23f08
	s_mov_b32 s0, -1
	v_mov_b32_e32 v2, s1
	ds_read_b64 v[4:5], v2
	v_mbcnt_lo_u32_b32 v2, s0, 0
	v_mbcnt_hi_u32_b32 v2, s0, v2
	v_readlane_b32 s0, v247, 1
	s_movk_i32 s33, 0x6000
	s_waitcnt lgkmcnt(0)
	v_readfirstlane_b32 s1, v5
	v_add_u32_e32 v2, s0, v2
	v_readfirstlane_b32 s0, v4
	v_mov_b32_e32 v5, s1
	v_ashrrev_i32_e32 v3, 31, v2
	v_mov_b32_e32 v4, s0
	v_lshl_add_u64 v[8:9], v[2:3], 2, v[4:5]
	s_movk_i32 s0, 0x1000
	v_add_co_u32_e32 v4, vcc, s0, v8
	s_movk_i32 s0, 0x2000
	s_nop 0
	v_addc_co_u32_e32 v5, vcc, 0, v9, vcc
	global_load_dword v3, v[8:9], off
	global_load_dword v14, v[8:9], off offset:2048
	v_add_co_u32_e32 v6, vcc, s0, v8
	s_movk_i32 s1, 0x4000
	s_nop 0
	v_addc_co_u32_e32 v7, vcc, 0, v9, vcc
	global_load_dword v15, v[6:7], off offset:-4096
	global_load_dword v16, v[4:5], off offset:2048
	global_load_dword v17, v[6:7], off
	v_add_co_u32_e32 v4, vcc, s1, v8
	s_movk_i32 s0, 0x3000
	global_load_dword v18, v[6:7], off offset:2048
	v_addc_co_u32_e32 v5, vcc, 0, v9, vcc
	global_load_dword v19, v[4:5], off offset:-4096
	v_add_co_u32_e32 v6, vcc, s0, v8
	s_movk_i32 s1, 0x5000
	s_nop 0
	v_addc_co_u32_e32 v7, vcc, 0, v9, vcc
	global_load_dword v20, v[6:7], off offset:2048
	global_load_dword v21, v[4:5], off
	global_load_dword v22, v[4:5], off offset:2048
	v_add_co_u32_e32 v10, vcc, s33, v8
	s_movk_i32 s2, 0x7000
	s_nop 0
	v_addc_co_u32_e32 v11, vcc, 0, v9, vcc
	global_load_dword v23, v[10:11], off offset:-4096
	global_load_dword v25, v[10:11], off
	v_add_co_u32_e32 v4, vcc, s1, v8
	s_add_i32 s0, 0, 0x23fa8
	s_nop 0
	v_addc_co_u32_e32 v5, vcc, 0, v9, vcc
	global_load_dword v24, v[4:5], off offset:2048
	v_add_co_u32_e32 v8, vcc, s2, v8
	v_mov_b32_e32 v6, s0
	s_add_i32 s0, 0, 0x23f18
	v_addc_co_u32_e32 v9, vcc, 0, v9, vcc
	global_load_dword v10, v[10:11], off offset:2048
	ds_read_b64 v[12:13], v6
	global_load_dword v11, v[8:9], off
	v_mov_b32_e32 v4, s0
	ds_read2_b64 v[4:7], v4 offset1:1
	v_lshl_add_u32 v26, v2, 2, 0
	s_cmpk_lt_i32 s80, 0x100
	s_cselect_b64 s[8:9], -1, 0
	s_cmpk_gt_i32 s80, 0xff
	s_waitcnt lgkmcnt(0)
	v_readfirstlane_b32 s12, v4
	global_load_dword v4, v[8:9], off offset:2048
	v_readfirstlane_b32 s13, v5
	v_readfirstlane_b32 s14, v6
	v_readfirstlane_b32 s15, v7
	s_cselect_b64 s[22:23], -1, 0
	v_readfirstlane_b32 s0, v12
	v_readfirstlane_b32 s1, v13
	s_and_b64 vcc, exec, s[22:23]
	s_waitcnt vmcnt(15)
	v_mul_f32_e32 v5, 0xbfb8aa3b, v3
	s_waitcnt vmcnt(14)
	v_mul_f32_e32 v6, 0xbfb8aa3b, v14
	v_exp_f32_e32 v5, v5
	v_exp_f32_e32 v6, v6
	s_waitcnt vmcnt(13)
	v_mul_f32_e32 v7, 0xbfb8aa3b, v15
	s_waitcnt vmcnt(12)
	v_mul_f32_e32 v8, 0xbfb8aa3b, v16
	v_exp_f32_e32 v7, v7
	v_exp_f32_e32 v8, v8
	v_add_f32_e32 v5, 1.0, v5
	v_add_f32_e32 v6, 1.0, v6
	v_rcp_f32_e32 v5, v5
	v_rcp_f32_e32 v6, v6
	v_add_f32_e32 v7, 1.0, v7
	v_add_f32_e32 v8, 1.0, v8
	v_rcp_f32_e32 v7, v7
	v_rcp_f32_e32 v8, v8
	v_mul_f32_e32 v3, v3, v5
	v_mul_f32_e32 v5, v14, v6
	s_waitcnt vmcnt(11)
	v_mul_f32_e32 v9, 0xbfb8aa3b, v17
	ds_write2st64_b32 v26, v3, v5 offset1:8
	v_mul_f32_e32 v3, v15, v7
	s_waitcnt vmcnt(10)
	v_mul_f32_e32 v5, 0xbfb8aa3b, v18
	v_mul_f32_e32 v6, v16, v8
	v_exp_f32_e32 v9, v9
	v_exp_f32_e32 v5, v5
	ds_write2st64_b32 v26, v3, v6 offset0:16 offset1:24
	s_waitcnt vmcnt(9)
	v_mul_f32_e32 v6, 0xbfb8aa3b, v19
	s_waitcnt vmcnt(8)
	v_mul_f32_e32 v7, 0xbfb8aa3b, v20
	v_exp_f32_e32 v6, v6
	v_exp_f32_e32 v7, v7
	v_add_f32_e32 v9, 1.0, v9
	v_add_f32_e32 v5, 1.0, v5
	v_rcp_f32_e32 v9, v9
	v_rcp_f32_e32 v5, v5
	v_add_f32_e32 v6, 1.0, v6
	v_add_f32_e32 v7, 1.0, v7
	v_rcp_f32_e32 v6, v6
	v_rcp_f32_e32 v7, v7
	v_mul_f32_e32 v3, v17, v9
	v_mul_f32_e32 v5, v18, v5
	ds_write2st64_b32 v26, v3, v5 offset0:32 offset1:40
	v_mul_f32_e32 v3, v19, v6
	v_mul_f32_e32 v5, v20, v7
	s_waitcnt vmcnt(7)
	v_mul_f32_e32 v6, 0xbfb8aa3b, v21
	s_waitcnt vmcnt(6)
	v_mul_f32_e32 v7, 0xbfb8aa3b, v22
	v_exp_f32_e32 v6, v6
	v_exp_f32_e32 v7, v7
	ds_write2st64_b32 v26, v3, v5 offset0:48 offset1:56
	v_add_f32_e32 v3, 1.0, v6
	v_add_f32_e32 v5, 1.0, v7
	v_rcp_f32_e32 v3, v3
	v_rcp_f32_e32 v5, v5
	s_waitcnt vmcnt(5)
	v_mul_f32_e32 v6, 0xbfb8aa3b, v23
	v_exp_f32_e32 v6, v6
	v_mul_f32_e32 v3, v21, v3
	v_mul_f32_e32 v5, v22, v5
	ds_write2st64_b32 v26, v3, v5 offset0:64 offset1:72
	s_waitcnt vmcnt(3)
	v_mul_f32_e32 v5, 0xbfb8aa3b, v24
	v_add_f32_e32 v3, 1.0, v6
	v_exp_f32_e32 v5, v5
	v_mul_f32_e32 v6, 0xbfb8aa3b, v25
	v_exp_f32_e32 v6, v6
	v_rcp_f32_e32 v3, v3
	v_add_f32_e32 v5, 1.0, v5
	v_rcp_f32_e32 v5, v5
	v_add_f32_e32 v6, 1.0, v6
	s_waitcnt vmcnt(2)
	v_mul_f32_e32 v7, 0xbfb8aa3b, v10
	v_rcp_f32_e32 v6, v6
	v_exp_f32_e32 v7, v7
	v_mul_f32_e32 v3, v23, v3
	v_mul_f32_e32 v5, v24, v5
	ds_write2st64_b32 v26, v3, v5 offset0:80 offset1:88
	v_mul_f32_e32 v3, v25, v6
	v_add_f32_e32 v5, 1.0, v7
	s_waitcnt vmcnt(1)
	v_mul_f32_e32 v6, 0xbfb8aa3b, v11
	s_waitcnt vmcnt(0)
	v_mul_f32_e32 v7, 0xbfb8aa3b, v4
	v_exp_f32_e32 v6, v6
	v_exp_f32_e32 v7, v7
	v_rcp_f32_e32 v5, v5
	v_add_f32_e32 v6, 1.0, v6
	v_add_f32_e32 v7, 1.0, v7
	v_rcp_f32_e32 v6, v6
	v_rcp_f32_e32 v7, v7
	v_mul_f32_e32 v5, v10, v5
	ds_write2st64_b32 v26, v3, v5 offset0:96 offset1:104
	v_mul_f32_e32 v3, v11, v6
	v_mul_f32_e32 v4, v4, v7
	ds_write2st64_b32 v26, v3, v4 offset0:112 offset1:120
	s_waitcnt lgkmcnt(0)
	s_barrier
	s_cbranch_vccnz .LBB0_26
	s_add_u32 s16, s0, 0x1c00000
	s_mov_b32 s0, 0x2aaaaaab
	v_mul_hi_i32 v3, v2, s0
	v_lshrrev_b32_e32 v4, 31, v3
	v_ashrrev_i32_e32 v3, 2, v3
	v_add_u32_e32 v36, v3, v4
	s_movk_i32 s2, 0x1800
	s_movk_i32 s0, 0x1f8
	v_mul_lo_u32 v38, v36, s2
	s_movk_i32 s2, 0x5e08
	v_mul_lo_u32 v5, v36, 24
	v_cmp_gt_i32_e32 vcc, s0, v2
	s_movk_i32 s0, 0xc0
	v_cmp_gt_i32_e64 s[2:3], s2, v2
	s_addc_u32 s17, s1, 0
	v_sub_u32_e32 v10, v2, v5
	v_cmp_gt_i32_e64 s[0:1], s0, v2
	v_lshlrev_b32_e32 v5, 5, v2
	v_max_i32_e32 v7, 0x3eb, v36
	v_addc_co_u32_e64 v2, s[4:5], v3, v4, s[2:3]
	v_sub_u32_e32 v2, v7, v2
	s_mov_b32 s4, 0x86186187
	v_mul_hi_u32 v3, v2, s4
	v_sub_u32_e32 v2, v2, v3
	v_lshrrev_b32_e32 v2, 1, v2
	v_add_u32_e32 v2, v2, v3
	v_lshrrev_b32_e32 v2, 4, v2
	v_addc_co_u32_e64 v2, s[2:3], 0, v2, s[2:3]
	s_mov_b32 s2, 0x24924925
	s_nop 0
	v_mul_hi_u32 v3, v2, s2
	v_mul_lo_u32 v3, v3, 7
	v_sub_u32_e32 v3, v2, v3
	v_ashrrev_i32_e32 v11, 31, v10
	v_add_u32_e32 v3, 1, v3
	v_cmp_ne_u32_e64 s[2:3], 7, v3
	v_lshlrev_b64 v[12:13], 2, v[10:11]
	v_lshl_add_u32 v37, v36, 2, 0
	v_lshlrev_b32_e32 v6, 5, v10
	v_cndmask_b32_e64 v39, 0, v3, s[2:3]
	v_cmp_lt_u32_e64 s[4:5], 5, v2
	v_mad_i64_i32 v[2:3], s[6:7], v36, s33, v[12:13]
	v_lshl_add_u64 v[14:15], s[12:13], 0, v[2:3]
	s_and_b32 s101, s80, 7
	s_lshl_b32 s101, s101, 5
	s_lshr_b32 s100, s80, 3
	s_or_b32 s101, s101, s100
	s_cmpk_lg_i32 s76, 0x100
	s_cselect_b32 s101, s80, s101
	s_mul_i32 s18, s101, 24
	s_mul_i32 s36, s76, 24
	s_mov_b64 s[20:21], 0x7e000
	s_mov_b64 s[24:25], 0x372000
	s_movk_i32 s37, 0x36c
	v_add_u32_e32 v11, 0, v5
	v_add_u32_e32 v40, v37, v6
	v_mov_b32_e32 v16, 0
	s_mov_b32 s38, s101
	s_branch .LBB0_14

.LBB0_14:
	s_and_saveexec_b64 s[26:27], vcc
	s_cbranch_execz .LBB0_24
	s_ashr_i32 s19, s18, 31
	s_lshl_b64 s[30:31], s[18:19], 2
	s_add_u32 s34, s12, s30
	s_addc_u32 s35, s13, s31
	v_mul_u32_u24_e32 v166, 0x6000, v36
	v_lshl_add_u32 v166, v10, 2, v166
	v_cmp_gt_u32_e64 s[28:29], 16, v36
	s_cmp_eq_u32 s38, s101
	s_cbranch_scc1 .Lp0_hoisted
	global_load_dword v100, v166, s[34:35]
	s_add_u32 s34, s34, 0x7e000
	s_addc_u32 s35, s35, 0
	global_load_dword v101, v166, s[34:35]
	s_add_u32 s34, s34, 0x7e000
	s_addc_u32 s35, s35, 0
	global_load_dword v102, v166, s[34:35]
	s_add_u32 s34, s34, 0x7e000
	s_addc_u32 s35, s35, 0
	global_load_dword v103, v166, s[34:35]
	s_add_u32 s34, s34, 0x7e000
	s_addc_u32 s35, s35, 0
	global_load_dword v104, v166, s[34:35]
	s_add_u32 s34, s34, 0x7e000
	s_addc_u32 s35, s35, 0
	global_load_dword v105, v166, s[34:35]
	s_add_u32 s34, s34, 0x7e000
	s_addc_u32 s35, s35, 0
	global_load_dword v106, v166, s[34:35]
	s_add_u32 s34, s34, 0x7e000
	s_addc_u32 s35, s35, 0
	global_load_dword v107, v166, s[34:35]
	s_add_u32 s34, s34, 0x7e000
	s_addc_u32 s35, s35, 0
	global_load_dword v108, v166, s[34:35]
	s_add_u32 s34, s34, 0x7e000
	s_addc_u32 s35, s35, 0
	global_load_dword v109, v166, s[34:35]
	s_add_u32 s34, s34, 0x7e000
	s_addc_u32 s35, s35, 0
	global_load_dword v110, v166, s[34:35]
	s_add_u32 s34, s34, 0x7e000
	s_addc_u32 s35, s35, 0
	global_load_dword v111, v166, s[34:35]
	s_add_u32 s34, s34, 0x7e000
	s_addc_u32 s35, s35, 0
	global_load_dword v112, v166, s[34:35]
	s_add_u32 s34, s34, 0x7e000
	s_addc_u32 s35, s35, 0
	global_load_dword v113, v166, s[34:35]
	s_add_u32 s34, s34, 0x7e000
	s_addc_u32 s35, s35, 0
	global_load_dword v114, v166, s[34:35]
	s_add_u32 s34, s34, 0x7e000
	s_addc_u32 s35, s35, 0
	global_load_dword v115, v166, s[34:35]
	s_add_u32 s34, s34, 0x7e000
	s_addc_u32 s35, s35, 0
	global_load_dword v116, v166, s[34:35]
	s_add_u32 s34, s34, 0x7e000
	s_addc_u32 s35, s35, 0
	global_load_dword v117, v166, s[34:35]
	s_add_u32 s34, s34, 0x7e000
	s_addc_u32 s35, s35, 0
	global_load_dword v118, v166, s[34:35]
	s_add_u32 s34, s34, 0x7e000
	s_addc_u32 s35, s35, 0
	global_load_dword v119, v166, s[34:35]
	s_add_u32 s34, s34, 0x7e000
	s_addc_u32 s35, s35, 0
	global_load_dword v120, v166, s[34:35]
	s_add_u32 s34, s34, 0x7e000
	s_addc_u32 s35, s35, 0
	global_load_dword v121, v166, s[34:35]
	s_add_u32 s34, s34, 0x7e000
	s_addc_u32 s35, s35, 0
	global_load_dword v122, v166, s[34:35]
	s_add_u32 s34, s34, 0x7e000
	s_addc_u32 s35, s35, 0
	global_load_dword v123, v166, s[34:35]
	s_add_u32 s34, s34, 0x7e000
	s_addc_u32 s35, s35, 0
	global_load_dword v124, v166, s[34:35]
	s_add_u32 s34, s34, 0x7e000
	s_addc_u32 s35, s35, 0
	global_load_dword v125, v166, s[34:35]
	s_add_u32 s34, s34, 0x7e000
	s_addc_u32 s35, s35, 0
	global_load_dword v126, v166, s[34:35]
	s_add_u32 s34, s34, 0x7e000
	s_addc_u32 s35, s35, 0
	global_load_dword v127, v166, s[34:35]
	s_add_u32 s34, s34, 0x7e000
	s_addc_u32 s35, s35, 0
	global_load_dword v128, v166, s[34:35]
	s_add_u32 s34, s34, 0x7e000
	s_addc_u32 s35, s35, 0
	global_load_dword v129, v166, s[34:35]
	s_add_u32 s34, s34, 0x7e000
	s_addc_u32 s35, s35, 0
	global_load_dword v130, v166, s[34:35]
	s_add_u32 s34, s34, 0x7e000
	s_addc_u32 s35, s35, 0
	global_load_dword v131, v166, s[34:35]
	s_add_u32 s34, s34, 0x7e000
	s_addc_u32 s35, s35, 0
	global_load_dword v132, v166, s[34:35]
	s_add_u32 s34, s34, 0x7e000
	s_addc_u32 s35, s35, 0
	global_load_dword v133, v166, s[34:35]
	s_add_u32 s34, s34, 0x7e000
	s_addc_u32 s35, s35, 0
	global_load_dword v134, v166, s[34:35]
	s_add_u32 s34, s34, 0x7e000
	s_addc_u32 s35, s35, 0
	global_load_dword v135, v166, s[34:35]
	s_add_u32 s34, s34, 0x7e000
	s_addc_u32 s35, s35, 0
	global_load_dword v136, v166, s[34:35]
	s_add_u32 s34, s34, 0x7e000
	s_addc_u32 s35, s35, 0
	global_load_dword v137, v166, s[34:35]
	s_add_u32 s34, s34, 0x7e000
	s_addc_u32 s35, s35, 0
	global_load_dword v138, v166, s[34:35]
	s_add_u32 s34, s34, 0x7e000
	s_addc_u32 s35, s35, 0
	global_load_dword v139, v166, s[34:35]
	s_add_u32 s34, s34, 0x7e000
	s_addc_u32 s35, s35, 0
	global_load_dword v140, v166, s[34:35]
	s_add_u32 s34, s34, 0x7e000
	s_addc_u32 s35, s35, 0
	global_load_dword v141, v166, s[34:35]
	s_add_u32 s34, s34, 0x7e000
	s_addc_u32 s35, s35, 0
	global_load_dword v142, v166, s[34:35]
	s_add_u32 s34, s34, 0x7e000
	s_addc_u32 s35, s35, 0
	global_load_dword v143, v166, s[34:35]
	s_add_u32 s34, s34, 0x7e000
	s_addc_u32 s35, s35, 0
	global_load_dword v144, v166, s[34:35]
	s_add_u32 s34, s34, 0x7e000
	s_addc_u32 s35, s35, 0
	global_load_dword v145, v166, s[34:35]
	s_add_u32 s34, s34, 0x7e000
	s_addc_u32 s35, s35, 0
	global_load_dword v146, v166, s[34:35]
	s_add_u32 s34, s34, 0x7e000
	s_addc_u32 s35, s35, 0
	global_load_dword v147, v166, s[34:35]
	s_add_u32 s34, s34, 0x7e000
	s_addc_u32 s35, s35, 0
	s_and_saveexec_b64 s[6:7], s[28:29]
	s_cbranch_execz .Lp0_skip49
	global_load_dword v148, v166, s[34:35]

.Lp0_hoisted:
	v_mov_b32_e32 v6, 0
	v_mov_b32_e32 v7, 0
	v_mov_b32_e32 v8, 0
	v_mov_b32_e32 v9, 0
	v_mov_b32_e32 v2, 0
	v_mov_b32_e32 v3, 0
	v_mov_b32_e32 v4, 0
	v_mov_b32_e32 v5, 0
	v_mov_b32_e32 v167, v37
	ds_read2st64_b32 v[150:151], v167 offset1:16
	ds_read2st64_b32 v[152:153], v167 offset0:32 offset1:48
	ds_read2st64_b32 v[154:155], v167 offset0:64 offset1:80
	ds_read2st64_b32 v[156:157], v167 offset0:96 offset1:112
	v_add_u32_e32 v168, 84, v37
	ds_read2st64_b32 v[158:159], v168 offset1:16
	ds_read2st64_b32 v[160:161], v168 offset0:32 offset1:48
	ds_read2st64_b32 v[162:163], v168 offset0:64 offset1:80
	ds_read2st64_b32 v[164:165], v168 offset0:96 offset1:112
	s_waitcnt vmcnt(47) lgkmcnt(4)
	v_fma_f32 v6, v100, v150, v6
	v_fma_f32 v7, v100, v151, v7
	v_fma_f32 v8, v100, v152, v8
	v_fma_f32 v9, v100, v153, v9
	v_fma_f32 v2, v100, v154, v2
	v_fma_f32 v3, v100, v155, v3
	v_fma_f32 v4, v100, v156, v4
	v_fma_f32 v5, v100, v157, v5
	v_add_u32_e32 v167, 168, v37
	ds_read2st64_b32 v[150:151], v167 offset1:16
	ds_read2st64_b32 v[152:153], v167 offset0:32 offset1:48
	ds_read2st64_b32 v[154:155], v167 offset0:64 offset1:80
	ds_read2st64_b32 v[156:157], v167 offset0:96 offset1:112
	s_waitcnt vmcnt(46) lgkmcnt(4)
	v_fma_f32 v6, v101, v158, v6
	v_fma_f32 v7, v101, v159, v7
	v_fma_f32 v8, v101, v160, v8
	v_fma_f32 v9, v101, v161, v9
	v_fma_f32 v2, v101, v162, v2
	v_fma_f32 v3, v101, v163, v3
	v_fma_f32 v4, v101, v164, v4
	v_fma_f32 v5, v101, v165, v5
	v_add_u32_e32 v168, 252, v37
	ds_read2st64_b32 v[158:159], v168 offset1:16
	ds_read2st64_b32 v[160:161], v168 offset0:32 offset1:48
	ds_read2st64_b32 v[162:163], v168 offset0:64 offset1:80
	ds_read2st64_b32 v[164:165], v168 offset0:96 offset1:112
	s_waitcnt vmcnt(45) lgkmcnt(4)
	v_fma_f32 v6, v102, v150, v6
	v_fma_f32 v7, v102, v151, v7
	v_fma_f32 v8, v102, v152, v8
	v_fma_f32 v9, v102, v153, v9
	v_fma_f32 v2, v102, v154, v2
	v_fma_f32 v3, v102, v155, v3
	v_fma_f32 v4, v102, v156, v4
	v_fma_f32 v5, v102, v157, v5
	v_add_u32_e32 v167, 336, v37
	ds_read2st64_b32 v[150:151], v167 offset1:16
	ds_read2st64_b32 v[152:153], v167 offset0:32 offset1:48
	ds_read2st64_b32 v[154:155], v167 offset0:64 offset1:80
	ds_read2st64_b32 v[156:157], v167 offset0:96 offset1:112
	s_waitcnt vmcnt(44) lgkmcnt(4)
	v_fma_f32 v6, v103, v158, v6
	v_fma_f32 v7, v103, v159, v7
	v_fma_f32 v8, v103, v160, v8
	v_fma_f32 v9, v103, v161, v9
	v_fma_f32 v2, v103, v162, v2
	v_fma_f32 v3, v103, v163, v3
	v_fma_f32 v4, v103, v164, v4
	v_fma_f32 v5, v103, v165, v5
	v_add_u32_e32 v168, 420, v37
	ds_read2st64_b32 v[158:159], v168 offset1:16
	ds_read2st64_b32 v[160:161], v168 offset0:32 offset1:48
	ds_read2st64_b32 v[162:163], v168 offset0:64 offset1:80
	ds_read2st64_b32 v[164:165], v168 offset0:96 offset1:112
	s_waitcnt vmcnt(43) lgkmcnt(4)
	v_fma_f32 v6, v104, v150, v6
	v_fma_f32 v7, v104, v151, v7
	v_fma_f32 v8, v104, v152, v8
	v_fma_f32 v9, v104, v153, v9
	v_fma_f32 v2, v104, v154, v2
	v_fma_f32 v3, v104, v155, v3
	v_fma_f32 v4, v104, v156, v4
	v_fma_f32 v5, v104, v157, v5
	v_add_u32_e32 v167, 504, v37
	ds_read2st64_b32 v[150:151], v167 offset1:16
	ds_read2st64_b32 v[152:153], v167 offset0:32 offset1:48
	ds_read2st64_b32 v[154:155], v167 offset0:64 offset1:80
	ds_read2st64_b32 v[156:157], v167 offset0:96 offset1:112
	s_waitcnt vmcnt(42) lgkmcnt(4)
	v_fma_f32 v6, v105, v158, v6
	v_fma_f32 v7, v105, v159, v7
	v_fma_f32 v8, v105, v160, v8
	v_fma_f32 v9, v105, v161, v9
	v_fma_f32 v2, v105, v162, v2
	v_fma_f32 v3, v105, v163, v3
	v_fma_f32 v4, v105, v164, v4
	v_fma_f32 v5, v105, v165, v5
	v_add_u32_e32 v168, 588, v37
	ds_read2st64_b32 v[158:159], v168 offset1:16
	ds_read2st64_b32 v[160:161], v168 offset0:32 offset1:48
	ds_read2st64_b32 v[162:163], v168 offset0:64 offset1:80
	ds_read2st64_b32 v[164:165], v168 offset0:96 offset1:112
	s_waitcnt vmcnt(41) lgkmcnt(4)
	v_fma_f32 v6, v106, v150, v6
	v_fma_f32 v7, v106, v151, v7
	v_fma_f32 v8, v106, v152, v8
	v_fma_f32 v9, v106, v153, v9
	v_fma_f32 v2, v106, v154, v2
	v_fma_f32 v3, v106, v155, v3
	v_fma_f32 v4, v106, v156, v4
	v_fma_f32 v5, v106, v157, v5
	v_add_u32_e32 v167, 672, v37
	ds_read2st64_b32 v[150:151], v167 offset1:16
	ds_read2st64_b32 v[152:153], v167 offset0:32 offset1:48
	ds_read2st64_b32 v[154:155], v167 offset0:64 offset1:80
	ds_read2st64_b32 v[156:157], v167 offset0:96 offset1:112
	s_waitcnt vmcnt(40) lgkmcnt(4)
	v_fma_f32 v6, v107, v158, v6
	v_fma_f32 v7, v107, v159, v7
	v_fma_f32 v8, v107, v160, v8
	v_fma_f32 v9, v107, v161, v9
	v_fma_f32 v2, v107, v162, v2
	v_fma_f32 v3, v107, v163, v3
	v_fma_f32 v4, v107, v164, v4
	v_fma_f32 v5, v107, v165, v5
	v_add_u32_e32 v168, 756, v37
	ds_read2st64_b32 v[158:159], v168 offset1:16
	ds_read2st64_b32 v[160:161], v168 offset0:32 offset1:48
	ds_read2st64_b32 v[162:163], v168 offset0:64 offset1:80
	ds_read2st64_b32 v[164:165], v168 offset0:96 offset1:112
	s_waitcnt vmcnt(39) lgkmcnt(4)
	v_fma_f32 v6, v108, v150, v6
	v_fma_f32 v7, v108, v151, v7
	v_fma_f32 v8, v108, v152, v8
	v_fma_f32 v9, v108, v153, v9
	v_fma_f32 v2, v108, v154, v2
	v_fma_f32 v3, v108, v155, v3
	v_fma_f32 v4, v108, v156, v4
	v_fma_f32 v5, v108, v157, v5
	v_add_u32_e32 v167, 840, v37
	ds_read2st64_b32 v[150:151], v167 offset1:16
	ds_read2st64_b32 v[152:153], v167 offset0:32 offset1:48
	ds_read2st64_b32 v[154:155], v167 offset0:64 offset1:80
	ds_read2st64_b32 v[156:157], v167 offset0:96 offset1:112
	s_waitcnt vmcnt(38) lgkmcnt(4)
	v_fma_f32 v6, v109, v158, v6
	v_fma_f32 v7, v109, v159, v7
	v_fma_f32 v8, v109, v160, v8
	v_fma_f32 v9, v109, v161, v9
	v_fma_f32 v2, v109, v162, v2
	v_fma_f32 v3, v109, v163, v3
	v_fma_f32 v4, v109, v164, v4
	v_fma_f32 v5, v109, v165, v5
	v_add_u32_e32 v168, 924, v37
	ds_read2st64_b32 v[158:159], v168 offset1:16
	ds_read2st64_b32 v[160:161], v168 offset0:32 offset1:48
	ds_read2st64_b32 v[162:163], v168 offset0:64 offset1:80
	ds_read2st64_b32 v[164:165], v168 offset0:96 offset1:112
	s_waitcnt vmcnt(37) lgkmcnt(4)
	v_fma_f32 v6, v110, v150, v6
	v_fma_f32 v7, v110, v151, v7
	v_fma_f32 v8, v110, v152, v8
	v_fma_f32 v9, v110, v153, v9
	v_fma_f32 v2, v110, v154, v2
	v_fma_f32 v3, v110, v155, v3
	v_fma_f32 v4, v110, v156, v4
	v_fma_f32 v5, v110, v157, v5
	v_add_u32_e32 v167, 1008, v37
	ds_read2st64_b32 v[150:151], v167 offset1:16
	ds_read2st64_b32 v[152:153], v167 offset0:32 offset1:48
	ds_read2st64_b32 v[154:155], v167 offset0:64 offset1:80
	ds_read2st64_b32 v[156:157], v167 offset0:96 offset1:112
	s_waitcnt vmcnt(36) lgkmcnt(4)
	v_fma_f32 v6, v111, v158, v6
	v_fma_f32 v7, v111, v159, v7
	v_fma_f32 v8, v111, v160, v8
	v_fma_f32 v9, v111, v161, v9
	v_fma_f32 v2, v111, v162, v2
	v_fma_f32 v3, v111, v163, v3
	v_fma_f32 v4, v111, v164, v4
	v_fma_f32 v5, v111, v165, v5
	v_add_u32_e32 v168, 1092, v37
	ds_read2st64_b32 v[158:159], v168 offset1:16
	ds_read2st64_b32 v[160:161], v168 offset0:32 offset1:48
	ds_read2st64_b32 v[162:163], v168 offset0:64 offset1:80
	ds_read2st64_b32 v[164:165], v168 offset0:96 offset1:112
	s_waitcnt vmcnt(35) lgkmcnt(4)
	v_fma_f32 v6, v112, v150, v6
	v_fma_f32 v7, v112, v151, v7
	v_fma_f32 v8, v112, v152, v8
	v_fma_f32 v9, v112, v153, v9
	v_fma_f32 v2, v112, v154, v2
	v_fma_f32 v3, v112, v155, v3
	v_fma_f32 v4, v112, v156, v4
	v_fma_f32 v5, v112, v157, v5
	v_add_u32_e32 v167, 1176, v37
	ds_read2st64_b32 v[150:151], v167 offset1:16
	ds_read2st64_b32 v[152:153], v167 offset0:32 offset1:48
	ds_read2st64_b32 v[154:155], v167 offset0:64 offset1:80
	ds_read2st64_b32 v[156:157], v167 offset0:96 offset1:112
	s_waitcnt vmcnt(34) lgkmcnt(4)
	v_fma_f32 v6, v113, v158, v6
	v_fma_f32 v7, v113, v159, v7
	v_fma_f32 v8, v113, v160, v8
	v_fma_f32 v9, v113, v161, v9
	v_fma_f32 v2, v113, v162, v2
	v_fma_f32 v3, v113, v163, v3
	v_fma_f32 v4, v113, v164, v4
	v_fma_f32 v5, v113, v165, v5
	v_add_u32_e32 v168, 1260, v37
	ds_read2st64_b32 v[158:159], v168 offset1:16
	ds_read2st64_b32 v[160:161], v168 offset0:32 offset1:48
	ds_read2st64_b32 v[162:163], v168 offset0:64 offset1:80
	ds_read2st64_b32 v[164:165], v168 offset0:96 offset1:112
	s_waitcnt vmcnt(33) lgkmcnt(4)
	v_fma_f32 v6, v114, v150, v6
	v_fma_f32 v7, v114, v151, v7
	v_fma_f32 v8, v114, v152, v8
	v_fma_f32 v9, v114, v153, v9
	v_fma_f32 v2, v114, v154, v2
	v_fma_f32 v3, v114, v155, v3
	v_fma_f32 v4, v114, v156, v4
	v_fma_f32 v5, v114, v157, v5
	v_add_u32_e32 v167, 1344, v37
	ds_read2st64_b32 v[150:151], v167 offset1:16
	ds_read2st64_b32 v[152:153], v167 offset0:32 offset1:48
	ds_read2st64_b32 v[154:155], v167 offset0:64 offset1:80
	ds_read2st64_b32 v[156:157], v167 offset0:96 offset1:112
	s_waitcnt vmcnt(32) lgkmcnt(4)
	v_fma_f32 v6, v115, v158, v6
	v_fma_f32 v7, v115, v159, v7
	v_fma_f32 v8, v115, v160, v8
	v_fma_f32 v9, v115, v161, v9
	v_fma_f32 v2, v115, v162, v2
	v_fma_f32 v3, v115, v163, v3
	v_fma_f32 v4, v115, v164, v4
	v_fma_f32 v5, v115, v165, v5
	v_add_u32_e32 v168, 1428, v37
	ds_read2st64_b32 v[158:159], v168 offset1:16
	ds_read2st64_b32 v[160:161], v168 offset0:32 offset1:48
	ds_read2st64_b32 v[162:163], v168 offset0:64 offset1:80
	ds_read2st64_b32 v[164:165], v168 offset0:96 offset1:112
	s_waitcnt vmcnt(31) lgkmcnt(4)
	v_fma_f32 v6, v116, v150, v6
	v_fma_f32 v7, v116, v151, v7
	v_fma_f32 v8, v116, v152, v8
	v_fma_f32 v9, v116, v153, v9
	v_fma_f32 v2, v116, v154, v2
	v_fma_f32 v3, v116, v155, v3
	v_fma_f32 v4, v116, v156, v4
	v_fma_f32 v5, v116, v157, v5
	v_add_u32_e32 v167, 1512, v37
	ds_read2st64_b32 v[150:151], v167 offset1:16
	ds_read2st64_b32 v[152:153], v167 offset0:32 offset1:48
	ds_read2st64_b32 v[154:155], v167 offset0:64 offset1:80
	ds_read2st64_b32 v[156:157], v167 offset0:96 offset1:112
	s_waitcnt vmcnt(30) lgkmcnt(4)
	v_fma_f32 v6, v117, v158, v6
	v_fma_f32 v7, v117, v159, v7
	v_fma_f32 v8, v117, v160, v8
	v_fma_f32 v9, v117, v161, v9
	v_fma_f32 v2, v117, v162, v2
	v_fma_f32 v3, v117, v163, v3
	v_fma_f32 v4, v117, v164, v4
	v_fma_f32 v5, v117, v165, v5
	v_add_u32_e32 v168, 1596, v37
	ds_read2st64_b32 v[158:159], v168 offset1:16
	ds_read2st64_b32 v[160:161], v168 offset0:32 offset1:48
	ds_read2st64_b32 v[162:163], v168 offset0:64 offset1:80
	ds_read2st64_b32 v[164:165], v168 offset0:96 offset1:112
	s_waitcnt vmcnt(29) lgkmcnt(4)
	v_fma_f32 v6, v118, v150, v6
	v_fma_f32 v7, v118, v151, v7
	v_fma_f32 v8, v118, v152, v8
	v_fma_f32 v9, v118, v153, v9
	v_fma_f32 v2, v118, v154, v2
	v_fma_f32 v3, v118, v155, v3
	v_fma_f32 v4, v118, v156, v4
	v_fma_f32 v5, v118, v157, v5
	v_add_u32_e32 v167, 1680, v37
	ds_read2st64_b32 v[150:151], v167 offset1:16
	ds_read2st64_b32 v[152:153], v167 offset0:32 offset1:48
	ds_read2st64_b32 v[154:155], v167 offset0:64 offset1:80
	ds_read2st64_b32 v[156:157], v167 offset0:96 offset1:112
	s_waitcnt vmcnt(28) lgkmcnt(4)
	v_fma_f32 v6, v119, v158, v6
	v_fma_f32 v7, v119, v159, v7
	v_fma_f32 v8, v119, v160, v8
	v_fma_f32 v9, v119, v161, v9
	v_fma_f32 v2, v119, v162, v2
	v_fma_f32 v3, v119, v163, v3
	v_fma_f32 v4, v119, v164, v4
	v_fma_f32 v5, v119, v165, v5
	v_add_u32_e32 v168, 1764, v37
	ds_read2st64_b32 v[158:159], v168 offset1:16
	ds_read2st64_b32 v[160:161], v168 offset0:32 offset1:48
	ds_read2st64_b32 v[162:163], v168 offset0:64 offset1:80
	ds_read2st64_b32 v[164:165], v168 offset0:96 offset1:112
	s_waitcnt vmcnt(27) lgkmcnt(4)
	v_fma_f32 v6, v120, v150, v6
	v_fma_f32 v7, v120, v151, v7
	v_fma_f32 v8, v120, v152, v8
	v_fma_f32 v9, v120, v153, v9
	v_fma_f32 v2, v120, v154, v2
	v_fma_f32 v3, v120, v155, v3
	v_fma_f32 v4, v120, v156, v4
	v_fma_f32 v5, v120, v157, v5
	v_add_u32_e32 v167, 1848, v37
	ds_read2st64_b32 v[150:151], v167 offset1:16
	ds_read2st64_b32 v[152:153], v167 offset0:32 offset1:48
	ds_read2st64_b32 v[154:155], v167 offset0:64 offset1:80
	ds_read2st64_b32 v[156:157], v167 offset0:96 offset1:112
	s_waitcnt vmcnt(26) lgkmcnt(4)
	v_fma_f32 v6, v121, v158, v6
	v_fma_f32 v7, v121, v159, v7
	v_fma_f32 v8, v121, v160, v8
	v_fma_f32 v9, v121, v161, v9
	v_fma_f32 v2, v121, v162, v2
	v_fma_f32 v3, v121, v163, v3
	v_fma_f32 v4, v121, v164, v4
	v_fma_f32 v5, v121, v165, v5
	v_add_u32_e32 v168, 1932, v37
	ds_read2st64_b32 v[158:159], v168 offset1:16
	ds_read2st64_b32 v[160:161], v168 offset0:32 offset1:48
	ds_read2st64_b32 v[162:163], v168 offset0:64 offset1:80
	ds_read2st64_b32 v[164:165], v168 offset0:96 offset1:112
	s_waitcnt vmcnt(25) lgkmcnt(4)
	v_fma_f32 v6, v122, v150, v6
	v_fma_f32 v7, v122, v151, v7
	v_fma_f32 v8, v122, v152, v8
	v_fma_f32 v9, v122, v153, v9
	v_fma_f32 v2, v122, v154, v2
	v_fma_f32 v3, v122, v155, v3
	v_fma_f32 v4, v122, v156, v4
	v_fma_f32 v5, v122, v157, v5
	v_add_u32_e32 v167, 2016, v37
	ds_read2st64_b32 v[150:151], v167 offset1:16
	ds_read2st64_b32 v[152:153], v167 offset0:32 offset1:48
	ds_read2st64_b32 v[154:155], v167 offset0:64 offset1:80
	ds_read2st64_b32 v[156:157], v167 offset0:96 offset1:112
	s_waitcnt vmcnt(24) lgkmcnt(4)
	v_fma_f32 v6, v123, v158, v6
	v_fma_f32 v7, v123, v159, v7
	v_fma_f32 v8, v123, v160, v8
	v_fma_f32 v9, v123, v161, v9
	v_fma_f32 v2, v123, v162, v2
	v_fma_f32 v3, v123, v163, v3
	v_fma_f32 v4, v123, v164, v4
	v_fma_f32 v5, v123, v165, v5
	v_add_u32_e32 v168, 2100, v37
	ds_read2st64_b32 v[158:159], v168 offset1:16
	ds_read2st64_b32 v[160:161], v168 offset0:32 offset1:48
	ds_read2st64_b32 v[162:163], v168 offset0:64 offset1:80
	ds_read2st64_b32 v[164:165], v168 offset0:96 offset1:112
	s_waitcnt vmcnt(23) lgkmcnt(4)
	v_fma_f32 v6, v124, v150, v6
	v_fma_f32 v7, v124, v151, v7
	v_fma_f32 v8, v124, v152, v8
	v_fma_f32 v9, v124, v153, v9
	v_fma_f32 v2, v124, v154, v2
	v_fma_f32 v3, v124, v155, v3
	v_fma_f32 v4, v124, v156, v4
	v_fma_f32 v5, v124, v157, v5
	v_add_u32_e32 v167, 2184, v37
	ds_read2st64_b32 v[150:151], v167 offset1:16
	ds_read2st64_b32 v[152:153], v167 offset0:32 offset1:48
	ds_read2st64_b32 v[154:155], v167 offset0:64 offset1:80
	ds_read2st64_b32 v[156:157], v167 offset0:96 offset1:112
	s_waitcnt vmcnt(22) lgkmcnt(4)
	v_fma_f32 v6, v125, v158, v6
	v_fma_f32 v7, v125, v159, v7
	v_fma_f32 v8, v125, v160, v8
	v_fma_f32 v9, v125, v161, v9
	v_fma_f32 v2, v125, v162, v2
	v_fma_f32 v3, v125, v163, v3
	v_fma_f32 v4, v125, v164, v4
	v_fma_f32 v5, v125, v165, v5
	v_add_u32_e32 v168, 2268, v37
	ds_read2st64_b32 v[158:159], v168 offset1:16
	ds_read2st64_b32 v[160:161], v168 offset0:32 offset1:48
	ds_read2st64_b32 v[162:163], v168 offset0:64 offset1:80
	ds_read2st64_b32 v[164:165], v168 offset0:96 offset1:112
	s_waitcnt vmcnt(21) lgkmcnt(4)
	v_fma_f32 v6, v126, v150, v6
	v_fma_f32 v7, v126, v151, v7
	v_fma_f32 v8, v126, v152, v8
	v_fma_f32 v9, v126, v153, v9
	v_fma_f32 v2, v126, v154, v2
	v_fma_f32 v3, v126, v155, v3
	v_fma_f32 v4, v126, v156, v4
	v_fma_f32 v5, v126, v157, v5
	v_add_u32_e32 v167, 2352, v37
	ds_read2st64_b32 v[150:151], v167 offset1:16
	ds_read2st64_b32 v[152:153], v167 offset0:32 offset1:48
	ds_read2st64_b32 v[154:155], v167 offset0:64 offset1:80
	ds_read2st64_b32 v[156:157], v167 offset0:96 offset1:112
	s_waitcnt vmcnt(20) lgkmcnt(4)
	v_fma_f32 v6, v127, v158, v6
	v_fma_f32 v7, v127, v159, v7
	v_fma_f32 v8, v127, v160, v8
	v_fma_f32 v9, v127, v161, v9
	v_fma_f32 v2, v127, v162, v2
	v_fma_f32 v3, v127, v163, v3
	v_fma_f32 v4, v127, v164, v4
	v_fma_f32 v5, v127, v165, v5
	v_add_u32_e32 v168, 2436, v37
	ds_read2st64_b32 v[158:159], v168 offset1:16
	ds_read2st64_b32 v[160:161], v168 offset0:32 offset1:48
	ds_read2st64_b32 v[162:163], v168 offset0:64 offset1:80
	ds_read2st64_b32 v[164:165], v168 offset0:96 offset1:112
	s_waitcnt vmcnt(19) lgkmcnt(4)
	v_fma_f32 v6, v128, v150, v6
	v_fma_f32 v7, v128, v151, v7
	v_fma_f32 v8, v128, v152, v8
	v_fma_f32 v9, v128, v153, v9
	v_fma_f32 v2, v128, v154, v2
	v_fma_f32 v3, v128, v155, v3
	v_fma_f32 v4, v128, v156, v4
	v_fma_f32 v5, v128, v157, v5
	v_add_u32_e32 v167, 2520, v37
	ds_read2st64_b32 v[150:151], v167 offset1:16
	ds_read2st64_b32 v[152:153], v167 offset0:32 offset1:48
	ds_read2st64_b32 v[154:155], v167 offset0:64 offset1:80
	ds_read2st64_b32 v[156:157], v167 offset0:96 offset1:112
	s_waitcnt vmcnt(18) lgkmcnt(4)
	v_fma_f32 v6, v129, v158, v6
	v_fma_f32 v7, v129, v159, v7
	v_fma_f32 v8, v129, v160, v8
	v_fma_f32 v9, v129, v161, v9
	v_fma_f32 v2, v129, v162, v2
	v_fma_f32 v3, v129, v163, v3
	v_fma_f32 v4, v129, v164, v4
	v_fma_f32 v5, v129, v165, v5
	v_add_u32_e32 v168, 2604, v37
	ds_read2st64_b32 v[158:159], v168 offset1:16
	ds_read2st64_b32 v[160:161], v168 offset0:32 offset1:48
	ds_read2st64_b32 v[162:163], v168 offset0:64 offset1:80
	ds_read2st64_b32 v[164:165], v168 offset0:96 offset1:112
	s_waitcnt vmcnt(17) lgkmcnt(4)
	v_fma_f32 v6, v130, v150, v6
	v_fma_f32 v7, v130, v151, v7
	v_fma_f32 v8, v130, v152, v8
	v_fma_f32 v9, v130, v153, v9
	v_fma_f32 v2, v130, v154, v2
	v_fma_f32 v3, v130, v155, v3
	v_fma_f32 v4, v130, v156, v4
	v_fma_f32 v5, v130, v157, v5
	v_add_u32_e32 v167, 2688, v37
	ds_read2st64_b32 v[150:151], v167 offset1:16
	ds_read2st64_b32 v[152:153], v167 offset0:32 offset1:48
	ds_read2st64_b32 v[154:155], v167 offset0:64 offset1:80
	ds_read2st64_b32 v[156:157], v167 offset0:96 offset1:112
	s_waitcnt vmcnt(16) lgkmcnt(4)
	v_fma_f32 v6, v131, v158, v6
	v_fma_f32 v7, v131, v159, v7
	v_fma_f32 v8, v131, v160, v8
	v_fma_f32 v9, v131, v161, v9
	v_fma_f32 v2, v131, v162, v2
	v_fma_f32 v3, v131, v163, v3
	v_fma_f32 v4, v131, v164, v4
	v_fma_f32 v5, v131, v165, v5
	v_add_u32_e32 v168, 2772, v37
	ds_read2st64_b32 v[158:159], v168 offset1:16
	ds_read2st64_b32 v[160:161], v168 offset0:32 offset1:48
	ds_read2st64_b32 v[162:163], v168 offset0:64 offset1:80
	ds_read2st64_b32 v[164:165], v168 offset0:96 offset1:112
	s_waitcnt vmcnt(15) lgkmcnt(4)
	v_fma_f32 v6, v132, v150, v6
	v_fma_f32 v7, v132, v151, v7
	v_fma_f32 v8, v132, v152, v8
	v_fma_f32 v9, v132, v153, v9
	v_fma_f32 v2, v132, v154, v2
	v_fma_f32 v3, v132, v155, v3
	v_fma_f32 v4, v132, v156, v4
	v_fma_f32 v5, v132, v157, v5
	v_add_u32_e32 v167, 2856, v37
	ds_read2st64_b32 v[150:151], v167 offset1:16
	ds_read2st64_b32 v[152:153], v167 offset0:32 offset1:48
	ds_read2st64_b32 v[154:155], v167 offset0:64 offset1:80
	ds_read2st64_b32 v[156:157], v167 offset0:96 offset1:112
	s_waitcnt vmcnt(14) lgkmcnt(4)
	v_fma_f32 v6, v133, v158, v6
	v_fma_f32 v7, v133, v159, v7
	v_fma_f32 v8, v133, v160, v8
	v_fma_f32 v9, v133, v161, v9
	v_fma_f32 v2, v133, v162, v2
	v_fma_f32 v3, v133, v163, v3
	v_fma_f32 v4, v133, v164, v4
	v_fma_f32 v5, v133, v165, v5
	v_add_u32_e32 v168, 2940, v37
	ds_read2st64_b32 v[158:159], v168 offset1:16
	ds_read2st64_b32 v[160:161], v168 offset0:32 offset1:48
	ds_read2st64_b32 v[162:163], v168 offset0:64 offset1:80
	ds_read2st64_b32 v[164:165], v168 offset0:96 offset1:112
	s_waitcnt vmcnt(13) lgkmcnt(4)
	v_fma_f32 v6, v134, v150, v6
	v_fma_f32 v7, v134, v151, v7
	v_fma_f32 v8, v134, v152, v8
	v_fma_f32 v9, v134, v153, v9
	v_fma_f32 v2, v134, v154, v2
	v_fma_f32 v3, v134, v155, v3
	v_fma_f32 v4, v134, v156, v4
	v_fma_f32 v5, v134, v157, v5
	v_add_u32_e32 v167, 3024, v37
	ds_read2st64_b32 v[150:151], v167 offset1:16
	ds_read2st64_b32 v[152:153], v167 offset0:32 offset1:48
	ds_read2st64_b32 v[154:155], v167 offset0:64 offset1:80
	ds_read2st64_b32 v[156:157], v167 offset0:96 offset1:112
	s_waitcnt vmcnt(12) lgkmcnt(4)
	v_fma_f32 v6, v135, v158, v6
	v_fma_f32 v7, v135, v159, v7
	v_fma_f32 v8, v135, v160, v8
	v_fma_f32 v9, v135, v161, v9
	v_fma_f32 v2, v135, v162, v2
	v_fma_f32 v3, v135, v163, v3
	v_fma_f32 v4, v135, v164, v4
	v_fma_f32 v5, v135, v165, v5
	v_add_u32_e32 v168, 3108, v37
	ds_read2st64_b32 v[158:159], v168 offset1:16
	ds_read2st64_b32 v[160:161], v168 offset0:32 offset1:48
	ds_read2st64_b32 v[162:163], v168 offset0:64 offset1:80
	ds_read2st64_b32 v[164:165], v168 offset0:96 offset1:112
	s_waitcnt vmcnt(11) lgkmcnt(4)
	v_fma_f32 v6, v136, v150, v6
	v_fma_f32 v7, v136, v151, v7
	v_fma_f32 v8, v136, v152, v8
	v_fma_f32 v9, v136, v153, v9
	v_fma_f32 v2, v136, v154, v2
	v_fma_f32 v3, v136, v155, v3
	v_fma_f32 v4, v136, v156, v4
	v_fma_f32 v5, v136, v157, v5
	v_add_u32_e32 v167, 3192, v37
	ds_read2st64_b32 v[150:151], v167 offset1:16
	ds_read2st64_b32 v[152:153], v167 offset0:32 offset1:48
	ds_read2st64_b32 v[154:155], v167 offset0:64 offset1:80
	ds_read2st64_b32 v[156:157], v167 offset0:96 offset1:112
	s_waitcnt vmcnt(10) lgkmcnt(4)
	v_fma_f32 v6, v137, v158, v6
	v_fma_f32 v7, v137, v159, v7
	v_fma_f32 v8, v137, v160, v8
	v_fma_f32 v9, v137, v161, v9
	v_fma_f32 v2, v137, v162, v2
	v_fma_f32 v3, v137, v163, v3
	v_fma_f32 v4, v137, v164, v4
	v_fma_f32 v5, v137, v165, v5
	v_add_u32_e32 v168, 3276, v37
	ds_read2st64_b32 v[158:159], v168 offset1:16
	ds_read2st64_b32 v[160:161], v168 offset0:32 offset1:48
	ds_read2st64_b32 v[162:163], v168 offset0:64 offset1:80
	ds_read2st64_b32 v[164:165], v168 offset0:96 offset1:112
	s_waitcnt vmcnt(9) lgkmcnt(4)
	v_fma_f32 v6, v138, v150, v6
	v_fma_f32 v7, v138, v151, v7
	v_fma_f32 v8, v138, v152, v8
	v_fma_f32 v9, v138, v153, v9
	v_fma_f32 v2, v138, v154, v2
	v_fma_f32 v3, v138, v155, v3
	v_fma_f32 v4, v138, v156, v4
	v_fma_f32 v5, v138, v157, v5
	v_add_u32_e32 v167, 3360, v37
	ds_read2st64_b32 v[150:151], v167 offset1:16
	ds_read2st64_b32 v[152:153], v167 offset0:32 offset1:48
	ds_read2st64_b32 v[154:155], v167 offset0:64 offset1:80
	ds_read2st64_b32 v[156:157], v167 offset0:96 offset1:112
	s_waitcnt vmcnt(8) lgkmcnt(4)
	v_fma_f32 v6, v139, v158, v6
	v_fma_f32 v7, v139, v159, v7
	v_fma_f32 v8, v139, v160, v8
	v_fma_f32 v9, v139, v161, v9
	v_fma_f32 v2, v139, v162, v2
	v_fma_f32 v3, v139, v163, v3
	v_fma_f32 v4, v139, v164, v4
	v_fma_f32 v5, v139, v165, v5
	v_add_u32_e32 v168, 3444, v37
	ds_read2st64_b32 v[158:159], v168 offset1:16
	ds_read2st64_b32 v[160:161], v168 offset0:32 offset1:48
	ds_read2st64_b32 v[162:163], v168 offset0:64 offset1:80
	ds_read2st64_b32 v[164:165], v168 offset0:96 offset1:112
	s_waitcnt vmcnt(7) lgkmcnt(4)
	v_fma_f32 v6, v140, v150, v6
	v_fma_f32 v7, v140, v151, v7
	v_fma_f32 v8, v140, v152, v8
	v_fma_f32 v9, v140, v153, v9
	v_fma_f32 v2, v140, v154, v2
	v_fma_f32 v3, v140, v155, v3
	v_fma_f32 v4, v140, v156, v4
	v_fma_f32 v5, v140, v157, v5
	v_add_u32_e32 v167, 3528, v37
	ds_read2st64_b32 v[150:151], v167 offset1:16
	ds_read2st64_b32 v[152:153], v167 offset0:32 offset1:48
	ds_read2st64_b32 v[154:155], v167 offset0:64 offset1:80
	ds_read2st64_b32 v[156:157], v167 offset0:96 offset1:112
	s_waitcnt vmcnt(6) lgkmcnt(4)
	v_fma_f32 v6, v141, v158, v6
	v_fma_f32 v7, v141, v159, v7
	v_fma_f32 v8, v141, v160, v8
	v_fma_f32 v9, v141, v161, v9
	v_fma_f32 v2, v141, v162, v2
	v_fma_f32 v3, v141, v163, v3
	v_fma_f32 v4, v141, v164, v4
	v_fma_f32 v5, v141, v165, v5
	v_add_u32_e32 v168, 3612, v37
	ds_read2st64_b32 v[158:159], v168 offset1:16
	ds_read2st64_b32 v[160:161], v168 offset0:32 offset1:48
	ds_read2st64_b32 v[162:163], v168 offset0:64 offset1:80
	ds_read2st64_b32 v[164:165], v168 offset0:96 offset1:112
	s_waitcnt vmcnt(5) lgkmcnt(4)
	v_fma_f32 v6, v142, v150, v6
	v_fma_f32 v7, v142, v151, v7
	v_fma_f32 v8, v142, v152, v8
	v_fma_f32 v9, v142, v153, v9
	v_fma_f32 v2, v142, v154, v2
	v_fma_f32 v3, v142, v155, v3
	v_fma_f32 v4, v142, v156, v4
	v_fma_f32 v5, v142, v157, v5
	v_add_u32_e32 v167, 3696, v37
	ds_read2st64_b32 v[150:151], v167 offset1:16
	ds_read2st64_b32 v[152:153], v167 offset0:32 offset1:48
	ds_read2st64_b32 v[154:155], v167 offset0:64 offset1:80
	ds_read2st64_b32 v[156:157], v167 offset0:96 offset1:112
	s_waitcnt vmcnt(4) lgkmcnt(4)
	v_fma_f32 v6, v143, v158, v6
	v_fma_f32 v7, v143, v159, v7
	v_fma_f32 v8, v143, v160, v8
	v_fma_f32 v9, v143, v161, v9
	v_fma_f32 v2, v143, v162, v2
	v_fma_f32 v3, v143, v163, v3
	v_fma_f32 v4, v143, v164, v4
	v_fma_f32 v5, v143, v165, v5
	v_add_u32_e32 v168, 3780, v37
	ds_read2st64_b32 v[158:159], v168 offset1:16
	ds_read2st64_b32 v[160:161], v168 offset0:32 offset1:48
	ds_read2st64_b32 v[162:163], v168 offset0:64 offset1:80
	ds_read2st64_b32 v[164:165], v168 offset0:96 offset1:112
	s_waitcnt vmcnt(3) lgkmcnt(4)
	v_fma_f32 v6, v144, v150, v6
	v_fma_f32 v7, v144, v151, v7
	v_fma_f32 v8, v144, v152, v8
	v_fma_f32 v9, v144, v153, v9
	v_fma_f32 v2, v144, v154, v2
	v_fma_f32 v3, v144, v155, v3
	v_fma_f32 v4, v144, v156, v4
	v_fma_f32 v5, v144, v157, v5
	v_add_u32_e32 v167, 3864, v37
	ds_read2st64_b32 v[150:151], v167 offset1:16
	ds_read2st64_b32 v[152:153], v167 offset0:32 offset1:48
	ds_read2st64_b32 v[154:155], v167 offset0:64 offset1:80
	ds_read2st64_b32 v[156:157], v167 offset0:96 offset1:112
	s_waitcnt vmcnt(2) lgkmcnt(4)
	v_fma_f32 v6, v145, v158, v6
	v_fma_f32 v7, v145, v159, v7
	v_fma_f32 v8, v145, v160, v8
	v_fma_f32 v9, v145, v161, v9
	v_fma_f32 v2, v145, v162, v2
	v_fma_f32 v3, v145, v163, v3
	v_fma_f32 v4, v145, v164, v4
	v_fma_f32 v5, v145, v165, v5
	v_add_u32_e32 v168, 3948, v37
	ds_read2st64_b32 v[158:159], v168 offset1:16
	ds_read2st64_b32 v[160:161], v168 offset0:32 offset1:48
	ds_read2st64_b32 v[162:163], v168 offset0:64 offset1:80
	ds_read2st64_b32 v[164:165], v168 offset0:96 offset1:112
	s_waitcnt vmcnt(1) lgkmcnt(4)
	v_fma_f32 v6, v146, v150, v6
	v_fma_f32 v7, v146, v151, v7
	v_fma_f32 v8, v146, v152, v8
	v_fma_f32 v9, v146, v153, v9
	v_fma_f32 v2, v146, v154, v2
	v_fma_f32 v3, v146, v155, v3
	v_fma_f32 v4, v146, v156, v4
	v_fma_f32 v5, v146, v157, v5
	s_waitcnt vmcnt(0) lgkmcnt(0)
	v_fma_f32 v6, v147, v158, v6
	v_fma_f32 v7, v147, v159, v7
	v_fma_f32 v8, v147, v160, v8
	v_fma_f32 v9, v147, v161, v9
	v_fma_f32 v2, v147, v162, v2
	v_fma_f32 v3, v147, v163, v3
	v_fma_f32 v4, v147, v164, v4
	v_fma_f32 v5, v147, v165, v5
	s_and_saveexec_b64 s[6:7], s[28:29]
	s_cbranch_execz .Lp0_done
	v_add_u32_e32 v167, 4032, v37
	ds_read2st64_b32 v[150:151], v167 offset1:16
	ds_read2st64_b32 v[152:153], v167 offset0:32 offset1:48
	ds_read2st64_b32 v[154:155], v167 offset0:64 offset1:80
	ds_read2st64_b32 v[156:157], v167 offset0:96 offset1:112
	s_waitcnt vmcnt(0) lgkmcnt(0)
	v_fma_f32 v6, v148, v150, v6
	v_fma_f32 v7, v148, v151, v7
	v_fma_f32 v8, v148, v152, v8
	v_fma_f32 v9, v148, v153, v9
	v_fma_f32 v2, v148, v154, v2
	v_fma_f32 v3, v148, v155, v3
	v_fma_f32 v4, v148, v156, v4
	v_fma_f32 v5, v148, v157, v5

.LBB0_24:
	s_or_b64 exec, exec, s[26:27]
	s_waitcnt lgkmcnt(0)
	s_barrier
	s_and_saveexec_b64 s[6:7], s[0:1]
	s_cbranch_execz .LBB0_13
	v_mad_u64_u32 v[2:3], s[26:27], s38, 24, v[10:11]
	v_ashrrev_i32_e32 v3, 31, v2
	v_lshl_add_u64 v[4:5], v[2:3], 2, s[14:15]
	s_cmp_lg_u32 s38, s101
	s_cbranch_scc0 .Lp0_bh
	flat_load_dword v149, v[4:5]
.Lp0_bh:
	ds_read2st64_b32 v[4:5], v40 offset0:128 offset1:131
	ds_read2st64_b32 v[6:7], v40 offset0:134 offset1:137
	ds_read2st64_b32 v[8:9], v40 offset0:140 offset1:143
	ds_read2st64_b32 v[18:19], v40 offset0:146 offset1:149
	ds_read2st64_b32 v[20:21], v40 offset0:152 offset1:155
	ds_read2st64_b32 v[22:23], v40 offset0:158 offset1:161
	ds_read2st64_b32 v[24:25], v40 offset0:164 offset1:167
	ds_read2st64_b32 v[26:27], v40 offset0:170 offset1:173
	ds_read2st64_b32 v[28:29], v40 offset0:176 offset1:179
	ds_read2st64_b32 v[30:31], v40 offset0:182 offset1:185
	ds_read_b32 v32, v40 offset:48128
	v_add_u32_e32 v2, v2, v38
	v_ashrrev_i32_e32 v3, 31, v2
	v_lshl_add_u64 v[2:3], v[2:3], 2, s[16:17]
	s_waitcnt vmcnt(0) lgkmcnt(0)
	v_add_f32_e32 v4, v149, v4
	v_add_f32_e32 v4, v4, v5
	v_add_f32_e32 v4, v4, v6
	v_add_f32_e32 v4, v4, v7
	v_add_f32_e32 v4, v4, v8
	v_add_f32_e32 v4, v4, v9
	v_add_f32_e32 v4, v4, v18
	v_add_f32_e32 v4, v4, v19
	v_add_f32_e32 v4, v4, v20
	v_add_f32_e32 v4, v4, v21
	v_add_f32_e32 v4, v4, v22
	v_add_f32_e32 v4, v4, v23
	v_add_f32_e32 v4, v4, v24
	v_add_f32_e32 v4, v4, v25
	v_add_f32_e32 v4, v4, v26
	v_add_f32_e32 v4, v4, v27
	v_add_f32_e32 v4, v4, v28
	v_add_f32_e32 v4, v4, v29
	v_add_f32_e32 v4, v4, v30
	v_add_f32_e32 v4, v4, v31
	v_add_f32_e32 v4, v4, v32
	flat_store_dword v[2:3], v4
	s_branch .LBB0_13

.LBB0_275:
	s_or_b64 exec, exec, s[2:3]
	s_add_i32 s3, 0, 0x23fa8
	s_mov_b32 s2, -1
	v_mov_b32_e32 v0, s3
	s_barrier
	ds_read_b64 v[0:1], v0
	v_mbcnt_lo_u32_b32 v4, s2, 0
	v_mbcnt_hi_u32_b32 v4, s2, v4
	s_waitcnt lgkmcnt(0)
	v_readfirstlane_b32 s11, v0
	v_readfirstlane_b32 s20, v1
	s_add_u32 s21, s11, 0x4800000
	s_addc_u32 s24, s20, 0
	s_add_i32 s3, 0, 0x23f10
	v_mov_b32_e32 v0, s3
	s_add_i32 s3, 0, 0x23f48
	ds_read_b64 v[6:7], v0
	v_mov_b32_e32 v0, s3
	ds_read2_b64 v[0:3], v0 offset1:1
	s_andn2_b64 vcc, exec, s[0:1]
	s_waitcnt lgkmcnt(1)
	v_readfirstlane_b32 s25, v6
	v_readfirstlane_b32 s26, v7
	s_waitcnt lgkmcnt(0)
	v_readfirstlane_b32 s2, v0
	v_cndmask_b32_e64 v0, 0, 1, s[0:1]
	v_cmp_ne_u32_e64 s[6:7], 1, v0
	v_readfirstlane_b32 s3, v1
	v_mov_b32_e32 v1, 0
	v_readfirstlane_b32 s4, v2
	v_readfirstlane_b32 s5, v3
	v_writelane_b32 v247, s6, 12
	v_lshlrev_b32_e32 v0, 1, v4
	s_nop 0
	v_writelane_b32 v247, s7, 13
	s_cbranch_vccnz .LBB0_278
	s_cmpk_lg_i32 s76, 0x100
	s_cbranch_scc1 .Lnsp_generic
	s_mul_i32 s16, s84, 0x1c00
	s_add_u32 s0, s11, s16
	s_addc_u32 s1, s20, 0
	s_add_u32 s0, s0, 0x4801000
	s_addc_u32 s1, s1, 0
	s_lshl_b32 s16, s84, 7
	s_add_u32 s12, s11, s16
	s_addc_u32 s13, s20, 0
	s_add_u32 s6, s12, 0xb800000
	s_addc_u32 s7, s13, 0
	s_lshl_b32 s16, s84, 2
	s_add_u32 s14, s25, s16
	s_addc_u32 s15, s26, 0
	s_mov_b32 s10, 0x3c800000
	v_and_b32_e32 v9, 7, v4
	v_lshlrev_b32_e32 v5, 4, v4
	v_lshrrev_b32_e32 v13, 3, v4
	v_lshlrev_b32_e32 v7, 18, v13
	v_lshl_add_u32 v7, v9, 4, v7
	v_lshlrev_b32_e32 v14, 13, v13
	global_load_dword v11, v14, s[14:15]
	v_lshlrev_b32_e32 v14, 5, v9
	global_load_dwordx4 v[16:19], v14, s[2:3]
	global_load_dwordx4 v[20:23], v14, s[2:3] offset:16
	v_lshrrev_b32_e32 v8, 4, v4
	v_add_u32_e32 v10, -1, v8
	v_max_i32_e32 v10, 0, v10
	v_lshl_add_u32 v10, v10, 8, v14
	global_load_dwordx4 v[24:27], v10, s[4:5]
	global_load_dwordx4 v[28:31], v10, s[4:5] offset:16
	v_cmp_lt_u32_e64 s[16:17], 47, v4
	v_add_u32_e32 v6, 0x400, v5
	v_add_u32_e32 v14, 0x500, v5
	s_nop 0
	v_cndmask_b32_e64 v6, v6, v14, s[16:17]
	global_load_dwordx4 v[48:51], v5, s[0:1]
	global_load_dwordx4 v[52:55], v6, s[0:1]
	s_add_u32 s0, s0, 0xe00000
	s_addc_u32 s1, s1, 0
	global_load_dwordx4 v[56:59], v5, s[0:1]
	global_load_dwordx4 v[60:63], v6, s[0:1]
	s_add_u32 s0, s0, 0xe00000
	s_addc_u32 s1, s1, 0
	global_load_dwordx4 v[64:67], v5, s[0:1]
	global_load_dwordx4 v[68:71], v6, s[0:1]
	s_add_u32 s0, s0, 0xe00000
	s_addc_u32 s1, s1, 0
	global_load_dwordx4 v[72:75], v5, s[0:1]
	global_load_dwordx4 v[76:79], v6, s[0:1]
	s_add_u32 s0, s0, 0xe00000
	s_addc_u32 s1, s1, 0
	global_load_dwordx4 v[80:83], v5, s[0:1]
	global_load_dwordx4 v[84:87], v6, s[0:1]
	s_add_u32 s0, s0, 0xe00000
	s_addc_u32 s1, s1, 0
	global_load_dwordx4 v[88:91], v5, s[0:1]
	global_load_dwordx4 v[92:95], v6, s[0:1]
	s_add_u32 s0, s0, 0xe00000
	s_addc_u32 s1, s1, 0
	global_load_dwordx4 v[96:99], v5, s[0:1]
	global_load_dwordx4 v[100:103], v6, s[0:1]
	s_add_u32 s0, s0, 0xe00000
	s_addc_u32 s1, s1, 0
	global_load_dwordx4 v[104:107], v5, s[0:1]
	global_load_dwordx4 v[108:111], v6, s[0:1]
	s_add_u32 s0, s0, 0xe00000
	s_addc_u32 s1, s1, 0
	v_cmp_eq_u32_e64 s[16:17], 3, v8
	v_mul_u32_u24_e32 v14, 5, v8
	v_add_u32_e32 v14, 0xc8, v14
	v_cndmask_b32_e64 v10, 0, 5, s[16:17]
	v_add_u32_e32 v14, v14, v10
	v_lshlrev_b32_e32 v14, 20, v14
	v_and_b32_e32 v13, 1, v13
	v_lshl_add_u32 v14, v13, 18, v14
	v_cmp_eq_u32_e64 s[18:19], 1, v8
	v_lshl_add_u32 v8, v9, 4, v14
	v_cmp_eq_u32_e64 s[16:17], 0, v9
	v_mov_b32_e32 v10, 0
	v_mov_b32_e32 v15, 0x358637bd
	v_cndmask_b32_e64 v10, v10, -1.0, s[16:17]
	v_cmp_eq_u32_e64 s[16:17], 1, v9
	s_nop 1
	v_cndmask_b32_e64 v10, v10, 1.0, s[16:17]
	v_mov_b32_e32 v13, 1.0
	v_cmp_eq_u32_e32 vcc, 1, v9
	v_mov_b32_e32 v14, 0x3e4693af
	s_nop 0
	v_cndmask_b32_e32 v13, v13, v14, vcc
	v_cmp_eq_u32_e32 vcc, 2, v9
	v_mov_b32_e32 v14, 0x3d1a08c8
	s_nop 0
	v_cndmask_b32_e32 v13, v13, v14, vcc
	v_cmp_eq_u32_e32 vcc, 3, v9
	v_mov_b32_e32 v14, 0x3beef74e
	s_nop 0
	v_cndmask_b32_e32 v13, v13, v14, vcc
	v_cmp_eq_u32_e32 vcc, 4, v9
	v_mov_b32_e32 v14, 0x3ab95d22
	s_nop 0
	v_cndmask_b32_e32 v13, v13, v14, vcc
	v_cmp_eq_u32_e32 vcc, 5, v9
	v_mov_b32_e32 v14, 0x398fc8f8
	s_nop 0
	v_cndmask_b32_e32 v13, v13, v14, vcc
	v_cmp_eq_u32_e32 vcc, 6, v9
	v_mov_b32_e32 v14, 0x385f10c4
	s_nop 0
	v_cndmask_b32_e32 v13, v13, v14, vcc
	v_cmp_eq_u32_e32 vcc, 7, v9
	v_mov_b32_e32 v14, 0x372d07a7
	s_nop 0
	v_cndmask_b32_e32 v13, v13, v14, vcc
	s_waitcnt vmcnt(20)
	v_cvt_f32_i32_e32 v11, v11
	v_mul_f32_e32 v11, v13, v11
	v_mul_f32_e32 v14, 0.15915494, v11
	v_floor_f32_e32 v14, v14
	v_fma_f32 v14, v11, 0.15915494, -v14
	v_cos_f32_e32 v11, v14
	v_sin_f32_e32 v12, v14
	v_cmp_gt_u32_e32 vcc, 2, v9
	s_waitcnt vmcnt(16)
	s_waitcnt vmcnt(14)
	v_readlane_b32 s28, v11, 0
	v_readlane_b32 s38, v12, 0
	v_readlane_b32 s29, v11, 1
	v_readlane_b32 s39, v12, 1
	v_readlane_b32 s30, v11, 2
	v_readlane_b32 s40, v12, 2
	v_readlane_b32 s31, v11, 3
	v_readlane_b32 s41, v12, 3
	v_readlane_b32 s34, v11, 4
	v_readlane_b32 s42, v12, 4
	v_readlane_b32 s35, v11, 5
	v_readlane_b32 s43, v12, 5
	v_readlane_b32 s36, v11, 6
	v_readlane_b32 s44, v12, 6
	v_readlane_b32 s37, v11, 7
	v_readlane_b32 s45, v12, 7
	v_mul_f32_e32 v32, s38, v10
	v_mul_f32_e32 v33, s39, v10
	v_mul_f32_e32 v34, s40, v10
	v_mul_f32_e32 v35, s41, v10
	v_mul_f32_e32 v36, s42, v10
	v_mul_f32_e32 v37, s43, v10
	v_mul_f32_e32 v38, s44, v10
	v_mul_f32_e32 v39, s45, v10
	v_lshlrev_b32_e32 v112, 16, v48
	v_and_b32_e32 v113, 0xffff0000, v48
	v_lshlrev_b32_e32 v114, 16, v49
	v_and_b32_e32 v115, 0xffff0000, v49
	v_lshlrev_b32_e32 v116, 16, v50
	v_and_b32_e32 v117, 0xffff0000, v50
	v_lshlrev_b32_e32 v118, 16, v51
	v_and_b32_e32 v119, 0xffff0000, v51
	v_mul_f32_e32 v140, v112, v112
	v_mul_f32_e32 v141, v113, v113
	v_fmac_f32_e32 v140, v114, v114
	v_fmac_f32_e32 v141, v115, v115
	v_fmac_f32_e32 v140, v116, v116
	v_fmac_f32_e32 v141, v117, v117
	v_fmac_f32_e32 v140, v118, v118
	v_fmac_f32_e32 v141, v119, v119
	v_add_f32_e32 v140, v140, v141
	s_nop 1
	v_add_f32_dpp v140, v140, v140 quad_perm:[1,0,3,2] row_mask:0xf bank_mask:0xf bound_ctrl:1
	s_nop 1
	v_add_f32_dpp v140, v140, v140 quad_perm:[2,3,0,1] row_mask:0xf bank_mask:0xf bound_ctrl:1
	s_nop 1
	v_add_f32_dpp v140, v140, v140 row_half_mirror row_mask:0xf bank_mask:0xf bound_ctrl:1
	v_fma_f32 v141, v140, s10, v15
	v_rsq_f32_e32 v141, v141
	s_nop 0
	v_mul_f32_e32 v112, v112, v141
	v_mul_f32_e32 v113, v113, v141
	v_mul_f32_e32 v114, v114, v141
	v_mul_f32_e32 v115, v115, v141
	v_mul_f32_e32 v116, v116, v141
	v_mul_f32_e32 v117, v117, v141
	v_mul_f32_e32 v118, v118, v141
	v_mul_f32_e32 v119, v119, v141
	v_mul_f32_e32 v112, v112, v16
	v_mul_f32_e32 v113, v113, v17
	v_mul_f32_e32 v114, v114, v18
	v_mul_f32_e32 v115, v115, v19
	v_mul_f32_e32 v116, v116, v20
	v_mul_f32_e32 v117, v117, v21
	v_mul_f32_e32 v118, v118, v22
	v_mul_f32_e32 v119, v119, v23
	v_mov_b32_dpp v120, v112 quad_perm:[1,0,3,2] row_mask:0xf bank_mask:0xf
	v_mov_b32_dpp v121, v113 quad_perm:[1,0,3,2] row_mask:0xf bank_mask:0xf
	v_mov_b32_dpp v122, v114 quad_perm:[1,0,3,2] row_mask:0xf bank_mask:0xf
	v_mov_b32_dpp v123, v115 quad_perm:[1,0,3,2] row_mask:0xf bank_mask:0xf
	v_mov_b32_dpp v124, v116 quad_perm:[1,0,3,2] row_mask:0xf bank_mask:0xf
	v_mov_b32_dpp v125, v117 quad_perm:[1,0,3,2] row_mask:0xf bank_mask:0xf
	v_mov_b32_dpp v126, v118 quad_perm:[1,0,3,2] row_mask:0xf bank_mask:0xf
	v_mov_b32_dpp v127, v119 quad_perm:[1,0,3,2] row_mask:0xf bank_mask:0xf
	v_mul_f32_e32 v128, s28, v112
	v_mul_f32_e32 v129, s29, v113
	v_mul_f32_e32 v130, s30, v114
	v_mul_f32_e32 v131, s31, v115
	v_mul_f32_e32 v132, s34, v116
	v_mul_f32_e32 v133, s35, v117
	v_mul_f32_e32 v134, s36, v118
	v_mul_f32_e32 v135, s37, v119
	v_fmac_f32_e32 v128, v32, v120
	v_fmac_f32_e32 v129, v33, v121
	v_fmac_f32_e32 v130, v34, v122
	v_fmac_f32_e32 v131, v35, v123
	v_fmac_f32_e32 v132, v36, v124
	v_fmac_f32_e32 v133, v37, v125
	v_fmac_f32_e32 v134, v38, v126
	v_fmac_f32_e32 v135, v39, v127
	v_cndmask_b32_e32 v112, v112, v128, vcc
	v_cndmask_b32_e32 v113, v113, v129, vcc
	v_cndmask_b32_e32 v114, v114, v130, vcc
	v_cndmask_b32_e32 v115, v115, v131, vcc
	v_cndmask_b32_e32 v116, v116, v132, vcc
	v_cndmask_b32_e32 v117, v117, v133, vcc
	v_cndmask_b32_e32 v118, v118, v134, vcc
	v_cndmask_b32_e32 v119, v119, v135, vcc
	v_mul_f32_e32 v112, 0x3e38aa3b, v112
	v_mul_f32_e32 v113, 0x3e38aa3b, v113
	v_mul_f32_e32 v114, 0x3e38aa3b, v114
	v_mul_f32_e32 v115, 0x3e38aa3b, v115
	v_mul_f32_e32 v116, 0x3e38aa3b, v116
	v_mul_f32_e32 v117, 0x3e38aa3b, v117
	v_mul_f32_e32 v118, 0x3e38aa3b, v118
	v_mul_f32_e32 v119, 0x3e38aa3b, v119
	v_cvt_pk_bf16_f32 v136, v112, v113
	v_cvt_pk_bf16_f32 v137, v114, v115
	v_cvt_pk_bf16_f32 v138, v116, v117
	v_cvt_pk_bf16_f32 v139, v118, v119
	global_store_dwordx4 v7, v[136:139], s[6:7]
	s_nop 1
	v_lshlrev_b32_e32 v112, 16, v52
	v_and_b32_e32 v113, 0xffff0000, v52
	v_lshlrev_b32_e32 v114, 16, v53
	v_and_b32_e32 v115, 0xffff0000, v53
	v_lshlrev_b32_e32 v116, 16, v54
	v_and_b32_e32 v117, 0xffff0000, v54
	v_lshlrev_b32_e32 v118, 16, v55
	v_and_b32_e32 v119, 0xffff0000, v55
	v_mul_f32_e32 v140, v112, v112
	v_mul_f32_e32 v141, v113, v113
	v_fmac_f32_e32 v140, v114, v114
	v_fmac_f32_e32 v141, v115, v115
	v_fmac_f32_e32 v140, v116, v116
	v_fmac_f32_e32 v141, v117, v117
	v_fmac_f32_e32 v140, v118, v118
	v_fmac_f32_e32 v141, v119, v119
	v_add_f32_e32 v140, v140, v141
	s_nop 1
	v_add_f32_dpp v140, v140, v140 quad_perm:[1,0,3,2] row_mask:0xf bank_mask:0xf bound_ctrl:1
	s_nop 1
	v_add_f32_dpp v140, v140, v140 quad_perm:[2,3,0,1] row_mask:0xf bank_mask:0xf bound_ctrl:1
	s_nop 1
	v_add_f32_dpp v140, v140, v140 row_half_mirror row_mask:0xf bank_mask:0xf bound_ctrl:1
	v_fma_f32 v141, v140, s10, v15
	v_rsq_f32_e32 v141, v141
	s_nop 0
	v_mul_f32_e32 v112, v112, v141
	v_mul_f32_e32 v113, v113, v141
	v_mul_f32_e32 v114, v114, v141
	v_mul_f32_e32 v115, v115, v141
	v_mul_f32_e32 v116, v116, v141
	v_mul_f32_e32 v117, v117, v141
	v_mul_f32_e32 v118, v118, v141
	v_mul_f32_e32 v119, v119, v141
	v_mul_f32_e32 v112, v112, v24
	v_mul_f32_e32 v113, v113, v25
	v_mul_f32_e32 v114, v114, v26
	v_mul_f32_e32 v115, v115, v27
	v_mul_f32_e32 v116, v116, v28
	v_mul_f32_e32 v117, v117, v29
	v_mul_f32_e32 v118, v118, v30
	v_mul_f32_e32 v119, v119, v31
	v_mov_b32_dpp v120, v112 quad_perm:[1,0,3,2] row_mask:0xf bank_mask:0xf
	v_mov_b32_dpp v121, v113 quad_perm:[1,0,3,2] row_mask:0xf bank_mask:0xf
	v_mov_b32_dpp v122, v114 quad_perm:[1,0,3,2] row_mask:0xf bank_mask:0xf
	v_mov_b32_dpp v123, v115 quad_perm:[1,0,3,2] row_mask:0xf bank_mask:0xf
	v_mov_b32_dpp v124, v116 quad_perm:[1,0,3,2] row_mask:0xf bank_mask:0xf
	v_mov_b32_dpp v125, v117 quad_perm:[1,0,3,2] row_mask:0xf bank_mask:0xf
	v_mov_b32_dpp v126, v118 quad_perm:[1,0,3,2] row_mask:0xf bank_mask:0xf
	v_mov_b32_dpp v127, v119 quad_perm:[1,0,3,2] row_mask:0xf bank_mask:0xf
	v_mul_f32_e32 v128, s28, v112
	v_mul_f32_e32 v129, s29, v113
	v_mul_f32_e32 v130, s30, v114
	v_mul_f32_e32 v131, s31, v115
	v_mul_f32_e32 v132, s34, v116
	v_mul_f32_e32 v133, s35, v117
	v_mul_f32_e32 v134, s36, v118
	v_mul_f32_e32 v135, s37, v119
	v_fmac_f32_e32 v128, v32, v120
	v_fmac_f32_e32 v129, v33, v121
	v_fmac_f32_e32 v130, v34, v122
	v_fmac_f32_e32 v131, v35, v123
	v_fmac_f32_e32 v132, v36, v124
	v_fmac_f32_e32 v133, v37, v125
	v_fmac_f32_e32 v134, v38, v126
	v_fmac_f32_e32 v135, v39, v127
	v_cndmask_b32_e32 v112, v112, v128, vcc
	v_cndmask_b32_e32 v113, v113, v129, vcc
	v_cndmask_b32_e32 v114, v114, v130, vcc
	v_cndmask_b32_e32 v115, v115, v131, vcc
	v_cndmask_b32_e32 v116, v116, v132, vcc
	v_cndmask_b32_e32 v117, v117, v133, vcc
	v_cndmask_b32_e32 v118, v118, v134, vcc
	v_cndmask_b32_e32 v119, v119, v135, vcc
	v_cvt_pk_bf16_f32 v136, v112, v113
	v_cvt_pk_bf16_f32 v137, v114, v115
	v_cvt_pk_bf16_f32 v138, v116, v117
	v_cvt_pk_bf16_f32 v139, v118, v119
	v_cndmask_b32_e64 v136, v136, v52, s[18:19]
	v_cndmask_b32_e64 v137, v137, v53, s[18:19]
	v_cndmask_b32_e64 v138, v138, v54, s[18:19]
	v_cndmask_b32_e64 v139, v139, v55, s[18:19]
	global_store_dwordx4 v8, v[136:139], s[12:13]
	s_add_u32 s6, s6, 0x200000
	s_addc_u32 s7, s7, 0
	s_add_u32 s12, s12, 0x80000
	s_addc_u32 s13, s13, 0
	s_waitcnt vmcnt(14)
	v_readlane_b32 s28, v11, 8
	v_readlane_b32 s38, v12, 8
	v_readlane_b32 s29, v11, 9
	v_readlane_b32 s39, v12, 9
	v_readlane_b32 s30, v11, 10
	v_readlane_b32 s40, v12, 10
	v_readlane_b32 s31, v11, 11
	v_readlane_b32 s41, v12, 11
	v_readlane_b32 s34, v11, 12
	v_readlane_b32 s42, v12, 12
	v_readlane_b32 s35, v11, 13
	v_readlane_b32 s43, v12, 13
	v_readlane_b32 s36, v11, 14
	v_readlane_b32 s44, v12, 14
	v_readlane_b32 s37, v11, 15
	v_readlane_b32 s45, v12, 15
	v_mul_f32_e32 v32, s38, v10
	v_mul_f32_e32 v33, s39, v10
	v_mul_f32_e32 v34, s40, v10
	v_mul_f32_e32 v35, s41, v10
	v_mul_f32_e32 v36, s42, v10
	v_mul_f32_e32 v37, s43, v10
	v_mul_f32_e32 v38, s44, v10
	v_mul_f32_e32 v39, s45, v10
	v_lshlrev_b32_e32 v112, 16, v56
	v_and_b32_e32 v113, 0xffff0000, v56
	v_lshlrev_b32_e32 v114, 16, v57
	v_and_b32_e32 v115, 0xffff0000, v57
	v_lshlrev_b32_e32 v116, 16, v58
	v_and_b32_e32 v117, 0xffff0000, v58
	v_lshlrev_b32_e32 v118, 16, v59
	v_and_b32_e32 v119, 0xffff0000, v59
	v_mul_f32_e32 v140, v112, v112
	v_mul_f32_e32 v141, v113, v113
	v_fmac_f32_e32 v140, v114, v114
	v_fmac_f32_e32 v141, v115, v115
	v_fmac_f32_e32 v140, v116, v116
	v_fmac_f32_e32 v141, v117, v117
	v_fmac_f32_e32 v140, v118, v118
	v_fmac_f32_e32 v141, v119, v119
	v_add_f32_e32 v140, v140, v141
	s_nop 1
	v_add_f32_dpp v140, v140, v140 quad_perm:[1,0,3,2] row_mask:0xf bank_mask:0xf bound_ctrl:1
	s_nop 1
	v_add_f32_dpp v140, v140, v140 quad_perm:[2,3,0,1] row_mask:0xf bank_mask:0xf bound_ctrl:1
	s_nop 1
	v_add_f32_dpp v140, v140, v140 row_half_mirror row_mask:0xf bank_mask:0xf bound_ctrl:1
	v_fma_f32 v141, v140, s10, v15
	v_rsq_f32_e32 v141, v141
	s_nop 0
	v_mul_f32_e32 v112, v112, v141
	v_mul_f32_e32 v113, v113, v141
	v_mul_f32_e32 v114, v114, v141
	v_mul_f32_e32 v115, v115, v141
	v_mul_f32_e32 v116, v116, v141
	v_mul_f32_e32 v117, v117, v141
	v_mul_f32_e32 v118, v118, v141
	v_mul_f32_e32 v119, v119, v141
	v_mul_f32_e32 v112, v112, v16
	v_mul_f32_e32 v113, v113, v17
	v_mul_f32_e32 v114, v114, v18
	v_mul_f32_e32 v115, v115, v19
	v_mul_f32_e32 v116, v116, v20
	v_mul_f32_e32 v117, v117, v21
	v_mul_f32_e32 v118, v118, v22
	v_mul_f32_e32 v119, v119, v23
	v_mov_b32_dpp v120, v112 quad_perm:[1,0,3,2] row_mask:0xf bank_mask:0xf
	v_mov_b32_dpp v121, v113 quad_perm:[1,0,3,2] row_mask:0xf bank_mask:0xf
	v_mov_b32_dpp v122, v114 quad_perm:[1,0,3,2] row_mask:0xf bank_mask:0xf
	v_mov_b32_dpp v123, v115 quad_perm:[1,0,3,2] row_mask:0xf bank_mask:0xf
	v_mov_b32_dpp v124, v116 quad_perm:[1,0,3,2] row_mask:0xf bank_mask:0xf
	v_mov_b32_dpp v125, v117 quad_perm:[1,0,3,2] row_mask:0xf bank_mask:0xf
	v_mov_b32_dpp v126, v118 quad_perm:[1,0,3,2] row_mask:0xf bank_mask:0xf
	v_mov_b32_dpp v127, v119 quad_perm:[1,0,3,2] row_mask:0xf bank_mask:0xf
	v_mul_f32_e32 v128, s28, v112
	v_mul_f32_e32 v129, s29, v113
	v_mul_f32_e32 v130, s30, v114
	v_mul_f32_e32 v131, s31, v115
	v_mul_f32_e32 v132, s34, v116
	v_mul_f32_e32 v133, s35, v117
	v_mul_f32_e32 v134, s36, v118
	v_mul_f32_e32 v135, s37, v119
	v_fmac_f32_e32 v128, v32, v120
	v_fmac_f32_e32 v129, v33, v121
	v_fmac_f32_e32 v130, v34, v122
	v_fmac_f32_e32 v131, v35, v123
	v_fmac_f32_e32 v132, v36, v124
	v_fmac_f32_e32 v133, v37, v125
	v_fmac_f32_e32 v134, v38, v126
	v_fmac_f32_e32 v135, v39, v127
	v_cndmask_b32_e32 v112, v112, v128, vcc
	v_cndmask_b32_e32 v113, v113, v129, vcc
	v_cndmask_b32_e32 v114, v114, v130, vcc
	v_cndmask_b32_e32 v115, v115, v131, vcc
	v_cndmask_b32_e32 v116, v116, v132, vcc
	v_cndmask_b32_e32 v117, v117, v133, vcc
	v_cndmask_b32_e32 v118, v118, v134, vcc
	v_cndmask_b32_e32 v119, v119, v135, vcc
	v_mul_f32_e32 v112, 0x3e38aa3b, v112
	v_mul_f32_e32 v113, 0x3e38aa3b, v113
	v_mul_f32_e32 v114, 0x3e38aa3b, v114
	v_mul_f32_e32 v115, 0x3e38aa3b, v115
	v_mul_f32_e32 v116, 0x3e38aa3b, v116
	v_mul_f32_e32 v117, 0x3e38aa3b, v117
	v_mul_f32_e32 v118, 0x3e38aa3b, v118
	v_mul_f32_e32 v119, 0x3e38aa3b, v119
	v_cvt_pk_bf16_f32 v136, v112, v113
	v_cvt_pk_bf16_f32 v137, v114, v115
	v_cvt_pk_bf16_f32 v138, v116, v117
	v_cvt_pk_bf16_f32 v139, v118, v119
	global_store_dwordx4 v7, v[136:139], s[6:7]
	s_nop 1
	v_lshlrev_b32_e32 v112, 16, v60
	v_and_b32_e32 v113, 0xffff0000, v60
	v_lshlrev_b32_e32 v114, 16, v61
	v_and_b32_e32 v115, 0xffff0000, v61
	v_lshlrev_b32_e32 v116, 16, v62
	v_and_b32_e32 v117, 0xffff0000, v62
	v_lshlrev_b32_e32 v118, 16, v63
	v_and_b32_e32 v119, 0xffff0000, v63
	v_mul_f32_e32 v140, v112, v112
	v_mul_f32_e32 v141, v113, v113
	v_fmac_f32_e32 v140, v114, v114
	v_fmac_f32_e32 v141, v115, v115
	v_fmac_f32_e32 v140, v116, v116
	v_fmac_f32_e32 v141, v117, v117
	v_fmac_f32_e32 v140, v118, v118
	v_fmac_f32_e32 v141, v119, v119
	v_add_f32_e32 v140, v140, v141
	s_nop 1
	v_add_f32_dpp v140, v140, v140 quad_perm:[1,0,3,2] row_mask:0xf bank_mask:0xf bound_ctrl:1
	s_nop 1
	v_add_f32_dpp v140, v140, v140 quad_perm:[2,3,0,1] row_mask:0xf bank_mask:0xf bound_ctrl:1
	s_nop 1
	v_add_f32_dpp v140, v140, v140 row_half_mirror row_mask:0xf bank_mask:0xf bound_ctrl:1
	v_fma_f32 v141, v140, s10, v15
	v_rsq_f32_e32 v141, v141
	s_nop 0
	v_mul_f32_e32 v112, v112, v141
	v_mul_f32_e32 v113, v113, v141
	v_mul_f32_e32 v114, v114, v141
	v_mul_f32_e32 v115, v115, v141
	v_mul_f32_e32 v116, v116, v141
	v_mul_f32_e32 v117, v117, v141
	v_mul_f32_e32 v118, v118, v141
	v_mul_f32_e32 v119, v119, v141
	v_mul_f32_e32 v112, v112, v24
	v_mul_f32_e32 v113, v113, v25
	v_mul_f32_e32 v114, v114, v26
	v_mul_f32_e32 v115, v115, v27
	v_mul_f32_e32 v116, v116, v28
	v_mul_f32_e32 v117, v117, v29
	v_mul_f32_e32 v118, v118, v30
	v_mul_f32_e32 v119, v119, v31
	v_mov_b32_dpp v120, v112 quad_perm:[1,0,3,2] row_mask:0xf bank_mask:0xf
	v_mov_b32_dpp v121, v113 quad_perm:[1,0,3,2] row_mask:0xf bank_mask:0xf
	v_mov_b32_dpp v122, v114 quad_perm:[1,0,3,2] row_mask:0xf bank_mask:0xf
	v_mov_b32_dpp v123, v115 quad_perm:[1,0,3,2] row_mask:0xf bank_mask:0xf
	v_mov_b32_dpp v124, v116 quad_perm:[1,0,3,2] row_mask:0xf bank_mask:0xf
	v_mov_b32_dpp v125, v117 quad_perm:[1,0,3,2] row_mask:0xf bank_mask:0xf
	v_mov_b32_dpp v126, v118 quad_perm:[1,0,3,2] row_mask:0xf bank_mask:0xf
	v_mov_b32_dpp v127, v119 quad_perm:[1,0,3,2] row_mask:0xf bank_mask:0xf
	v_mul_f32_e32 v128, s28, v112
	v_mul_f32_e32 v129, s29, v113
	v_mul_f32_e32 v130, s30, v114
	v_mul_f32_e32 v131, s31, v115
	v_mul_f32_e32 v132, s34, v116
	v_mul_f32_e32 v133, s35, v117
	v_mul_f32_e32 v134, s36, v118
	v_mul_f32_e32 v135, s37, v119
	v_fmac_f32_e32 v128, v32, v120
	v_fmac_f32_e32 v129, v33, v121
	v_fmac_f32_e32 v130, v34, v122
	v_fmac_f32_e32 v131, v35, v123
	v_fmac_f32_e32 v132, v36, v124
	v_fmac_f32_e32 v133, v37, v125
	v_fmac_f32_e32 v134, v38, v126
	v_fmac_f32_e32 v135, v39, v127
	v_cndmask_b32_e32 v112, v112, v128, vcc
	v_cndmask_b32_e32 v113, v113, v129, vcc
	v_cndmask_b32_e32 v114, v114, v130, vcc
	v_cndmask_b32_e32 v115, v115, v131, vcc
	v_cndmask_b32_e32 v116, v116, v132, vcc
	v_cndmask_b32_e32 v117, v117, v133, vcc
	v_cndmask_b32_e32 v118, v118, v134, vcc
	v_cndmask_b32_e32 v119, v119, v135, vcc
	v_cvt_pk_bf16_f32 v136, v112, v113
	v_cvt_pk_bf16_f32 v137, v114, v115
	v_cvt_pk_bf16_f32 v138, v116, v117
	v_cvt_pk_bf16_f32 v139, v118, v119
	v_cndmask_b32_e64 v136, v136, v60, s[18:19]
	v_cndmask_b32_e64 v137, v137, v61, s[18:19]
	v_cndmask_b32_e64 v138, v138, v62, s[18:19]
	v_cndmask_b32_e64 v139, v139, v63, s[18:19]
	global_store_dwordx4 v8, v[136:139], s[12:13]
	s_add_u32 s6, s6, 0x200000
	s_addc_u32 s7, s7, 0
	s_add_u32 s12, s12, 0x80000
	s_addc_u32 s13, s13, 0
	s_waitcnt vmcnt(14)
	v_readlane_b32 s28, v11, 16
	v_readlane_b32 s38, v12, 16
	v_readlane_b32 s29, v11, 17
	v_readlane_b32 s39, v12, 17
	v_readlane_b32 s30, v11, 18
	v_readlane_b32 s40, v12, 18
	v_readlane_b32 s31, v11, 19
	v_readlane_b32 s41, v12, 19
	v_readlane_b32 s34, v11, 20
	v_readlane_b32 s42, v12, 20
	v_readlane_b32 s35, v11, 21
	v_readlane_b32 s43, v12, 21
	v_readlane_b32 s36, v11, 22
	v_readlane_b32 s44, v12, 22
	v_readlane_b32 s37, v11, 23
	v_readlane_b32 s45, v12, 23
	v_mul_f32_e32 v32, s38, v10
	v_mul_f32_e32 v33, s39, v10
	v_mul_f32_e32 v34, s40, v10
	v_mul_f32_e32 v35, s41, v10
	v_mul_f32_e32 v36, s42, v10
	v_mul_f32_e32 v37, s43, v10
	v_mul_f32_e32 v38, s44, v10
	v_mul_f32_e32 v39, s45, v10
	v_lshlrev_b32_e32 v112, 16, v64
	v_and_b32_e32 v113, 0xffff0000, v64
	v_lshlrev_b32_e32 v114, 16, v65
	v_and_b32_e32 v115, 0xffff0000, v65
	v_lshlrev_b32_e32 v116, 16, v66
	v_and_b32_e32 v117, 0xffff0000, v66
	v_lshlrev_b32_e32 v118, 16, v67
	v_and_b32_e32 v119, 0xffff0000, v67
	v_mul_f32_e32 v140, v112, v112
	v_mul_f32_e32 v141, v113, v113
	v_fmac_f32_e32 v140, v114, v114
	v_fmac_f32_e32 v141, v115, v115
	v_fmac_f32_e32 v140, v116, v116
	v_fmac_f32_e32 v141, v117, v117
	v_fmac_f32_e32 v140, v118, v118
	v_fmac_f32_e32 v141, v119, v119
	v_add_f32_e32 v140, v140, v141
	s_nop 1
	v_add_f32_dpp v140, v140, v140 quad_perm:[1,0,3,2] row_mask:0xf bank_mask:0xf bound_ctrl:1
	s_nop 1
	v_add_f32_dpp v140, v140, v140 quad_perm:[2,3,0,1] row_mask:0xf bank_mask:0xf bound_ctrl:1
	s_nop 1
	v_add_f32_dpp v140, v140, v140 row_half_mirror row_mask:0xf bank_mask:0xf bound_ctrl:1
	v_fma_f32 v141, v140, s10, v15
	v_rsq_f32_e32 v141, v141
	s_nop 0
	v_mul_f32_e32 v112, v112, v141
	v_mul_f32_e32 v113, v113, v141
	v_mul_f32_e32 v114, v114, v141
	v_mul_f32_e32 v115, v115, v141
	v_mul_f32_e32 v116, v116, v141
	v_mul_f32_e32 v117, v117, v141
	v_mul_f32_e32 v118, v118, v141
	v_mul_f32_e32 v119, v119, v141
	v_mul_f32_e32 v112, v112, v16
	v_mul_f32_e32 v113, v113, v17
	v_mul_f32_e32 v114, v114, v18
	v_mul_f32_e32 v115, v115, v19
	v_mul_f32_e32 v116, v116, v20
	v_mul_f32_e32 v117, v117, v21
	v_mul_f32_e32 v118, v118, v22
	v_mul_f32_e32 v119, v119, v23
	v_mov_b32_dpp v120, v112 quad_perm:[1,0,3,2] row_mask:0xf bank_mask:0xf
	v_mov_b32_dpp v121, v113 quad_perm:[1,0,3,2] row_mask:0xf bank_mask:0xf
	v_mov_b32_dpp v122, v114 quad_perm:[1,0,3,2] row_mask:0xf bank_mask:0xf
	v_mov_b32_dpp v123, v115 quad_perm:[1,0,3,2] row_mask:0xf bank_mask:0xf
	v_mov_b32_dpp v124, v116 quad_perm:[1,0,3,2] row_mask:0xf bank_mask:0xf
	v_mov_b32_dpp v125, v117 quad_perm:[1,0,3,2] row_mask:0xf bank_mask:0xf
	v_mov_b32_dpp v126, v118 quad_perm:[1,0,3,2] row_mask:0xf bank_mask:0xf
	v_mov_b32_dpp v127, v119 quad_perm:[1,0,3,2] row_mask:0xf bank_mask:0xf
	v_mul_f32_e32 v128, s28, v112
	v_mul_f32_e32 v129, s29, v113
	v_mul_f32_e32 v130, s30, v114
	v_mul_f32_e32 v131, s31, v115
	v_mul_f32_e32 v132, s34, v116
	v_mul_f32_e32 v133, s35, v117
	v_mul_f32_e32 v134, s36, v118
	v_mul_f32_e32 v135, s37, v119
	v_fmac_f32_e32 v128, v32, v120
	v_fmac_f32_e32 v129, v33, v121
	v_fmac_f32_e32 v130, v34, v122
	v_fmac_f32_e32 v131, v35, v123
	v_fmac_f32_e32 v132, v36, v124
	v_fmac_f32_e32 v133, v37, v125
	v_fmac_f32_e32 v134, v38, v126
	v_fmac_f32_e32 v135, v39, v127
	v_cndmask_b32_e32 v112, v112, v128, vcc
	v_cndmask_b32_e32 v113, v113, v129, vcc
	v_cndmask_b32_e32 v114, v114, v130, vcc
	v_cndmask_b32_e32 v115, v115, v131, vcc
	v_cndmask_b32_e32 v116, v116, v132, vcc
	v_cndmask_b32_e32 v117, v117, v133, vcc
	v_cndmask_b32_e32 v118, v118, v134, vcc
	v_cndmask_b32_e32 v119, v119, v135, vcc
	v_mul_f32_e32 v112, 0x3e38aa3b, v112
	v_mul_f32_e32 v113, 0x3e38aa3b, v113
	v_mul_f32_e32 v114, 0x3e38aa3b, v114
	v_mul_f32_e32 v115, 0x3e38aa3b, v115
	v_mul_f32_e32 v116, 0x3e38aa3b, v116
	v_mul_f32_e32 v117, 0x3e38aa3b, v117
	v_mul_f32_e32 v118, 0x3e38aa3b, v118
	v_mul_f32_e32 v119, 0x3e38aa3b, v119
	v_cvt_pk_bf16_f32 v136, v112, v113
	v_cvt_pk_bf16_f32 v137, v114, v115
	v_cvt_pk_bf16_f32 v138, v116, v117
	v_cvt_pk_bf16_f32 v139, v118, v119
	global_store_dwordx4 v7, v[136:139], s[6:7]
	s_nop 1
	v_lshlrev_b32_e32 v112, 16, v68
	v_and_b32_e32 v113, 0xffff0000, v68
	v_lshlrev_b32_e32 v114, 16, v69
	v_and_b32_e32 v115, 0xffff0000, v69
	v_lshlrev_b32_e32 v116, 16, v70
	v_and_b32_e32 v117, 0xffff0000, v70
	v_lshlrev_b32_e32 v118, 16, v71
	v_and_b32_e32 v119, 0xffff0000, v71
	v_mul_f32_e32 v140, v112, v112
	v_mul_f32_e32 v141, v113, v113
	v_fmac_f32_e32 v140, v114, v114
	v_fmac_f32_e32 v141, v115, v115
	v_fmac_f32_e32 v140, v116, v116
	v_fmac_f32_e32 v141, v117, v117
	v_fmac_f32_e32 v140, v118, v118
	v_fmac_f32_e32 v141, v119, v119
	v_add_f32_e32 v140, v140, v141
	s_nop 1
	v_add_f32_dpp v140, v140, v140 quad_perm:[1,0,3,2] row_mask:0xf bank_mask:0xf bound_ctrl:1
	s_nop 1
	v_add_f32_dpp v140, v140, v140 quad_perm:[2,3,0,1] row_mask:0xf bank_mask:0xf bound_ctrl:1
	s_nop 1
	v_add_f32_dpp v140, v140, v140 row_half_mirror row_mask:0xf bank_mask:0xf bound_ctrl:1
	v_fma_f32 v141, v140, s10, v15
	v_rsq_f32_e32 v141, v141
	s_nop 0
	v_mul_f32_e32 v112, v112, v141
	v_mul_f32_e32 v113, v113, v141
	v_mul_f32_e32 v114, v114, v141
	v_mul_f32_e32 v115, v115, v141
	v_mul_f32_e32 v116, v116, v141
	v_mul_f32_e32 v117, v117, v141
	v_mul_f32_e32 v118, v118, v141
	v_mul_f32_e32 v119, v119, v141
	v_mul_f32_e32 v112, v112, v24
	v_mul_f32_e32 v113, v113, v25
	v_mul_f32_e32 v114, v114, v26
	v_mul_f32_e32 v115, v115, v27
	v_mul_f32_e32 v116, v116, v28
	v_mul_f32_e32 v117, v117, v29
	v_mul_f32_e32 v118, v118, v30
	v_mul_f32_e32 v119, v119, v31
	v_mov_b32_dpp v120, v112 quad_perm:[1,0,3,2] row_mask:0xf bank_mask:0xf
	v_mov_b32_dpp v121, v113 quad_perm:[1,0,3,2] row_mask:0xf bank_mask:0xf
	v_mov_b32_dpp v122, v114 quad_perm:[1,0,3,2] row_mask:0xf bank_mask:0xf
	v_mov_b32_dpp v123, v115 quad_perm:[1,0,3,2] row_mask:0xf bank_mask:0xf
	v_mov_b32_dpp v124, v116 quad_perm:[1,0,3,2] row_mask:0xf bank_mask:0xf
	v_mov_b32_dpp v125, v117 quad_perm:[1,0,3,2] row_mask:0xf bank_mask:0xf
	v_mov_b32_dpp v126, v118 quad_perm:[1,0,3,2] row_mask:0xf bank_mask:0xf
	v_mov_b32_dpp v127, v119 quad_perm:[1,0,3,2] row_mask:0xf bank_mask:0xf
	v_mul_f32_e32 v128, s28, v112
	v_mul_f32_e32 v129, s29, v113
	v_mul_f32_e32 v130, s30, v114
	v_mul_f32_e32 v131, s31, v115
	v_mul_f32_e32 v132, s34, v116
	v_mul_f32_e32 v133, s35, v117
	v_mul_f32_e32 v134, s36, v118
	v_mul_f32_e32 v135, s37, v119
	v_fmac_f32_e32 v128, v32, v120
	v_fmac_f32_e32 v129, v33, v121
	v_fmac_f32_e32 v130, v34, v122
	v_fmac_f32_e32 v131, v35, v123
	v_fmac_f32_e32 v132, v36, v124
	v_fmac_f32_e32 v133, v37, v125
	v_fmac_f32_e32 v134, v38, v126
	v_fmac_f32_e32 v135, v39, v127
	v_cndmask_b32_e32 v112, v112, v128, vcc
	v_cndmask_b32_e32 v113, v113, v129, vcc
	v_cndmask_b32_e32 v114, v114, v130, vcc
	v_cndmask_b32_e32 v115, v115, v131, vcc
	v_cndmask_b32_e32 v116, v116, v132, vcc
	v_cndmask_b32_e32 v117, v117, v133, vcc
	v_cndmask_b32_e32 v118, v118, v134, vcc
	v_cndmask_b32_e32 v119, v119, v135, vcc
	v_cvt_pk_bf16_f32 v136, v112, v113
	v_cvt_pk_bf16_f32 v137, v114, v115
	v_cvt_pk_bf16_f32 v138, v116, v117
	v_cvt_pk_bf16_f32 v139, v118, v119
	v_cndmask_b32_e64 v136, v136, v68, s[18:19]
	v_cndmask_b32_e64 v137, v137, v69, s[18:19]
	v_cndmask_b32_e64 v138, v138, v70, s[18:19]
	v_cndmask_b32_e64 v139, v139, v71, s[18:19]
	global_store_dwordx4 v8, v[136:139], s[12:13]
	s_add_u32 s6, s6, 0x200000
	s_addc_u32 s7, s7, 0
	s_add_u32 s12, s12, 0x80000
	s_addc_u32 s13, s13, 0
	s_waitcnt vmcnt(14)
	v_readlane_b32 s28, v11, 24
	v_readlane_b32 s38, v12, 24
	v_readlane_b32 s29, v11, 25
	v_readlane_b32 s39, v12, 25
	v_readlane_b32 s30, v11, 26
	v_readlane_b32 s40, v12, 26
	v_readlane_b32 s31, v11, 27
	v_readlane_b32 s41, v12, 27
	v_readlane_b32 s34, v11, 28
	v_readlane_b32 s42, v12, 28
	v_readlane_b32 s35, v11, 29
	v_readlane_b32 s43, v12, 29
	v_readlane_b32 s36, v11, 30
	v_readlane_b32 s44, v12, 30
	v_readlane_b32 s37, v11, 31
	v_readlane_b32 s45, v12, 31
	v_mul_f32_e32 v32, s38, v10
	v_mul_f32_e32 v33, s39, v10
	v_mul_f32_e32 v34, s40, v10
	v_mul_f32_e32 v35, s41, v10
	v_mul_f32_e32 v36, s42, v10
	v_mul_f32_e32 v37, s43, v10
	v_mul_f32_e32 v38, s44, v10
	v_mul_f32_e32 v39, s45, v10
	v_lshlrev_b32_e32 v112, 16, v72
	v_and_b32_e32 v113, 0xffff0000, v72
	v_lshlrev_b32_e32 v114, 16, v73
	v_and_b32_e32 v115, 0xffff0000, v73
	v_lshlrev_b32_e32 v116, 16, v74
	v_and_b32_e32 v117, 0xffff0000, v74
	v_lshlrev_b32_e32 v118, 16, v75
	v_and_b32_e32 v119, 0xffff0000, v75
	v_mul_f32_e32 v140, v112, v112
	v_mul_f32_e32 v141, v113, v113
	v_fmac_f32_e32 v140, v114, v114
	v_fmac_f32_e32 v141, v115, v115
	v_fmac_f32_e32 v140, v116, v116
	v_fmac_f32_e32 v141, v117, v117
	v_fmac_f32_e32 v140, v118, v118
	v_fmac_f32_e32 v141, v119, v119
	v_add_f32_e32 v140, v140, v141
	s_nop 1
	v_add_f32_dpp v140, v140, v140 quad_perm:[1,0,3,2] row_mask:0xf bank_mask:0xf bound_ctrl:1
	s_nop 1
	v_add_f32_dpp v140, v140, v140 quad_perm:[2,3,0,1] row_mask:0xf bank_mask:0xf bound_ctrl:1
	s_nop 1
	v_add_f32_dpp v140, v140, v140 row_half_mirror row_mask:0xf bank_mask:0xf bound_ctrl:1
	v_fma_f32 v141, v140, s10, v15
	v_rsq_f32_e32 v141, v141
	s_nop 0
	v_mul_f32_e32 v112, v112, v141
	v_mul_f32_e32 v113, v113, v141
	v_mul_f32_e32 v114, v114, v141
	v_mul_f32_e32 v115, v115, v141
	v_mul_f32_e32 v116, v116, v141
	v_mul_f32_e32 v117, v117, v141
	v_mul_f32_e32 v118, v118, v141
	v_mul_f32_e32 v119, v119, v141
	v_mul_f32_e32 v112, v112, v16
	v_mul_f32_e32 v113, v113, v17
	v_mul_f32_e32 v114, v114, v18
	v_mul_f32_e32 v115, v115, v19
	v_mul_f32_e32 v116, v116, v20
	v_mul_f32_e32 v117, v117, v21
	v_mul_f32_e32 v118, v118, v22
	v_mul_f32_e32 v119, v119, v23
	v_mov_b32_dpp v120, v112 quad_perm:[1,0,3,2] row_mask:0xf bank_mask:0xf
	v_mov_b32_dpp v121, v113 quad_perm:[1,0,3,2] row_mask:0xf bank_mask:0xf
	v_mov_b32_dpp v122, v114 quad_perm:[1,0,3,2] row_mask:0xf bank_mask:0xf
	v_mov_b32_dpp v123, v115 quad_perm:[1,0,3,2] row_mask:0xf bank_mask:0xf
	v_mov_b32_dpp v124, v116 quad_perm:[1,0,3,2] row_mask:0xf bank_mask:0xf
	v_mov_b32_dpp v125, v117 quad_perm:[1,0,3,2] row_mask:0xf bank_mask:0xf
	v_mov_b32_dpp v126, v118 quad_perm:[1,0,3,2] row_mask:0xf bank_mask:0xf
	v_mov_b32_dpp v127, v119 quad_perm:[1,0,3,2] row_mask:0xf bank_mask:0xf
	v_mul_f32_e32 v128, s28, v112
	v_mul_f32_e32 v129, s29, v113
	v_mul_f32_e32 v130, s30, v114
	v_mul_f32_e32 v131, s31, v115
	v_mul_f32_e32 v132, s34, v116
	v_mul_f32_e32 v133, s35, v117
	v_mul_f32_e32 v134, s36, v118
	v_mul_f32_e32 v135, s37, v119
	v_fmac_f32_e32 v128, v32, v120
	v_fmac_f32_e32 v129, v33, v121
	v_fmac_f32_e32 v130, v34, v122
	v_fmac_f32_e32 v131, v35, v123
	v_fmac_f32_e32 v132, v36, v124
	v_fmac_f32_e32 v133, v37, v125
	v_fmac_f32_e32 v134, v38, v126
	v_fmac_f32_e32 v135, v39, v127
	v_cndmask_b32_e32 v112, v112, v128, vcc
	v_cndmask_b32_e32 v113, v113, v129, vcc
	v_cndmask_b32_e32 v114, v114, v130, vcc
	v_cndmask_b32_e32 v115, v115, v131, vcc
	v_cndmask_b32_e32 v116, v116, v132, vcc
	v_cndmask_b32_e32 v117, v117, v133, vcc
	v_cndmask_b32_e32 v118, v118, v134, vcc
	v_cndmask_b32_e32 v119, v119, v135, vcc
	v_mul_f32_e32 v112, 0x3e38aa3b, v112
	v_mul_f32_e32 v113, 0x3e38aa3b, v113
	v_mul_f32_e32 v114, 0x3e38aa3b, v114
	v_mul_f32_e32 v115, 0x3e38aa3b, v115
	v_mul_f32_e32 v116, 0x3e38aa3b, v116
	v_mul_f32_e32 v117, 0x3e38aa3b, v117
	v_mul_f32_e32 v118, 0x3e38aa3b, v118
	v_mul_f32_e32 v119, 0x3e38aa3b, v119
	v_cvt_pk_bf16_f32 v136, v112, v113
	v_cvt_pk_bf16_f32 v137, v114, v115
	v_cvt_pk_bf16_f32 v138, v116, v117
	v_cvt_pk_bf16_f32 v139, v118, v119
	global_store_dwordx4 v7, v[136:139], s[6:7]
	s_nop 1
	v_lshlrev_b32_e32 v112, 16, v76
	v_and_b32_e32 v113, 0xffff0000, v76
	v_lshlrev_b32_e32 v114, 16, v77
	v_and_b32_e32 v115, 0xffff0000, v77
	v_lshlrev_b32_e32 v116, 16, v78
	v_and_b32_e32 v117, 0xffff0000, v78
	v_lshlrev_b32_e32 v118, 16, v79
	v_and_b32_e32 v119, 0xffff0000, v79
	v_mul_f32_e32 v140, v112, v112
	v_mul_f32_e32 v141, v113, v113
	v_fmac_f32_e32 v140, v114, v114
	v_fmac_f32_e32 v141, v115, v115
	v_fmac_f32_e32 v140, v116, v116
	v_fmac_f32_e32 v141, v117, v117
	v_fmac_f32_e32 v140, v118, v118
	v_fmac_f32_e32 v141, v119, v119
	v_add_f32_e32 v140, v140, v141
	s_nop 1
	v_add_f32_dpp v140, v140, v140 quad_perm:[1,0,3,2] row_mask:0xf bank_mask:0xf bound_ctrl:1
	s_nop 1
	v_add_f32_dpp v140, v140, v140 quad_perm:[2,3,0,1] row_mask:0xf bank_mask:0xf bound_ctrl:1
	s_nop 1
	v_add_f32_dpp v140, v140, v140 row_half_mirror row_mask:0xf bank_mask:0xf bound_ctrl:1
	v_fma_f32 v141, v140, s10, v15
	v_rsq_f32_e32 v141, v141
	s_nop 0
	v_mul_f32_e32 v112, v112, v141
	v_mul_f32_e32 v113, v113, v141
	v_mul_f32_e32 v114, v114, v141
	v_mul_f32_e32 v115, v115, v141
	v_mul_f32_e32 v116, v116, v141
	v_mul_f32_e32 v117, v117, v141
	v_mul_f32_e32 v118, v118, v141
	v_mul_f32_e32 v119, v119, v141
	v_mul_f32_e32 v112, v112, v24
	v_mul_f32_e32 v113, v113, v25
	v_mul_f32_e32 v114, v114, v26
	v_mul_f32_e32 v115, v115, v27
	v_mul_f32_e32 v116, v116, v28
	v_mul_f32_e32 v117, v117, v29
	v_mul_f32_e32 v118, v118, v30
	v_mul_f32_e32 v119, v119, v31
	v_mov_b32_dpp v120, v112 quad_perm:[1,0,3,2] row_mask:0xf bank_mask:0xf
	v_mov_b32_dpp v121, v113 quad_perm:[1,0,3,2] row_mask:0xf bank_mask:0xf
	v_mov_b32_dpp v122, v114 quad_perm:[1,0,3,2] row_mask:0xf bank_mask:0xf
	v_mov_b32_dpp v123, v115 quad_perm:[1,0,3,2] row_mask:0xf bank_mask:0xf
	v_mov_b32_dpp v124, v116 quad_perm:[1,0,3,2] row_mask:0xf bank_mask:0xf
	v_mov_b32_dpp v125, v117 quad_perm:[1,0,3,2] row_mask:0xf bank_mask:0xf
	v_mov_b32_dpp v126, v118 quad_perm:[1,0,3,2] row_mask:0xf bank_mask:0xf
	v_mov_b32_dpp v127, v119 quad_perm:[1,0,3,2] row_mask:0xf bank_mask:0xf
	v_mul_f32_e32 v128, s28, v112
	v_mul_f32_e32 v129, s29, v113
	v_mul_f32_e32 v130, s30, v114
	v_mul_f32_e32 v131, s31, v115
	v_mul_f32_e32 v132, s34, v116
	v_mul_f32_e32 v133, s35, v117
	v_mul_f32_e32 v134, s36, v118
	v_mul_f32_e32 v135, s37, v119
	v_fmac_f32_e32 v128, v32, v120
	v_fmac_f32_e32 v129, v33, v121
	v_fmac_f32_e32 v130, v34, v122
	v_fmac_f32_e32 v131, v35, v123
	v_fmac_f32_e32 v132, v36, v124
	v_fmac_f32_e32 v133, v37, v125
	v_fmac_f32_e32 v134, v38, v126
	v_fmac_f32_e32 v135, v39, v127
	v_cndmask_b32_e32 v112, v112, v128, vcc
	v_cndmask_b32_e32 v113, v113, v129, vcc
	v_cndmask_b32_e32 v114, v114, v130, vcc
	v_cndmask_b32_e32 v115, v115, v131, vcc
	v_cndmask_b32_e32 v116, v116, v132, vcc
	v_cndmask_b32_e32 v117, v117, v133, vcc
	v_cndmask_b32_e32 v118, v118, v134, vcc
	v_cndmask_b32_e32 v119, v119, v135, vcc
	v_cvt_pk_bf16_f32 v136, v112, v113
	v_cvt_pk_bf16_f32 v137, v114, v115
	v_cvt_pk_bf16_f32 v138, v116, v117
	v_cvt_pk_bf16_f32 v139, v118, v119
	v_cndmask_b32_e64 v136, v136, v76, s[18:19]
	v_cndmask_b32_e64 v137, v137, v77, s[18:19]
	v_cndmask_b32_e64 v138, v138, v78, s[18:19]
	v_cndmask_b32_e64 v139, v139, v79, s[18:19]
	global_store_dwordx4 v8, v[136:139], s[12:13]
	s_add_u32 s6, s6, 0x200000
	s_addc_u32 s7, s7, 0
	s_add_u32 s12, s12, 0x80000
	s_addc_u32 s13, s13, 0
	s_waitcnt vmcnt(14)
	v_readlane_b32 s28, v11, 32
	v_readlane_b32 s38, v12, 32
	v_readlane_b32 s29, v11, 33
	v_readlane_b32 s39, v12, 33
	v_readlane_b32 s30, v11, 34
	v_readlane_b32 s40, v12, 34
	v_readlane_b32 s31, v11, 35
	v_readlane_b32 s41, v12, 35
	v_readlane_b32 s34, v11, 36
	v_readlane_b32 s42, v12, 36
	v_readlane_b32 s35, v11, 37
	v_readlane_b32 s43, v12, 37
	v_readlane_b32 s36, v11, 38
	v_readlane_b32 s44, v12, 38
	v_readlane_b32 s37, v11, 39
	v_readlane_b32 s45, v12, 39
	v_mul_f32_e32 v32, s38, v10
	v_mul_f32_e32 v33, s39, v10
	v_mul_f32_e32 v34, s40, v10
	v_mul_f32_e32 v35, s41, v10
	v_mul_f32_e32 v36, s42, v10
	v_mul_f32_e32 v37, s43, v10
	v_mul_f32_e32 v38, s44, v10
	v_mul_f32_e32 v39, s45, v10
	v_lshlrev_b32_e32 v112, 16, v80
	v_and_b32_e32 v113, 0xffff0000, v80
	v_lshlrev_b32_e32 v114, 16, v81
	v_and_b32_e32 v115, 0xffff0000, v81
	v_lshlrev_b32_e32 v116, 16, v82
	v_and_b32_e32 v117, 0xffff0000, v82
	v_lshlrev_b32_e32 v118, 16, v83
	v_and_b32_e32 v119, 0xffff0000, v83
	v_mul_f32_e32 v140, v112, v112
	v_mul_f32_e32 v141, v113, v113
	v_fmac_f32_e32 v140, v114, v114
	v_fmac_f32_e32 v141, v115, v115
	v_fmac_f32_e32 v140, v116, v116
	v_fmac_f32_e32 v141, v117, v117
	v_fmac_f32_e32 v140, v118, v118
	v_fmac_f32_e32 v141, v119, v119
	v_add_f32_e32 v140, v140, v141
	s_nop 1
	v_add_f32_dpp v140, v140, v140 quad_perm:[1,0,3,2] row_mask:0xf bank_mask:0xf bound_ctrl:1
	s_nop 1
	v_add_f32_dpp v140, v140, v140 quad_perm:[2,3,0,1] row_mask:0xf bank_mask:0xf bound_ctrl:1
	s_nop 1
	v_add_f32_dpp v140, v140, v140 row_half_mirror row_mask:0xf bank_mask:0xf bound_ctrl:1
	v_fma_f32 v141, v140, s10, v15
	v_rsq_f32_e32 v141, v141
	s_nop 0
	v_mul_f32_e32 v112, v112, v141
	v_mul_f32_e32 v113, v113, v141
	v_mul_f32_e32 v114, v114, v141
	v_mul_f32_e32 v115, v115, v141
	v_mul_f32_e32 v116, v116, v141
	v_mul_f32_e32 v117, v117, v141
	v_mul_f32_e32 v118, v118, v141
	v_mul_f32_e32 v119, v119, v141
	v_mul_f32_e32 v112, v112, v16
	v_mul_f32_e32 v113, v113, v17
	v_mul_f32_e32 v114, v114, v18
	v_mul_f32_e32 v115, v115, v19
	v_mul_f32_e32 v116, v116, v20
	v_mul_f32_e32 v117, v117, v21
	v_mul_f32_e32 v118, v118, v22
	v_mul_f32_e32 v119, v119, v23
	v_mov_b32_dpp v120, v112 quad_perm:[1,0,3,2] row_mask:0xf bank_mask:0xf
	v_mov_b32_dpp v121, v113 quad_perm:[1,0,3,2] row_mask:0xf bank_mask:0xf
	v_mov_b32_dpp v122, v114 quad_perm:[1,0,3,2] row_mask:0xf bank_mask:0xf
	v_mov_b32_dpp v123, v115 quad_perm:[1,0,3,2] row_mask:0xf bank_mask:0xf
	v_mov_b32_dpp v124, v116 quad_perm:[1,0,3,2] row_mask:0xf bank_mask:0xf
	v_mov_b32_dpp v125, v117 quad_perm:[1,0,3,2] row_mask:0xf bank_mask:0xf
	v_mov_b32_dpp v126, v118 quad_perm:[1,0,3,2] row_mask:0xf bank_mask:0xf
	v_mov_b32_dpp v127, v119 quad_perm:[1,0,3,2] row_mask:0xf bank_mask:0xf
	v_mul_f32_e32 v128, s28, v112
	v_mul_f32_e32 v129, s29, v113
	v_mul_f32_e32 v130, s30, v114
	v_mul_f32_e32 v131, s31, v115
	v_mul_f32_e32 v132, s34, v116
	v_mul_f32_e32 v133, s35, v117
	v_mul_f32_e32 v134, s36, v118
	v_mul_f32_e32 v135, s37, v119
	v_fmac_f32_e32 v128, v32, v120
	v_fmac_f32_e32 v129, v33, v121
	v_fmac_f32_e32 v130, v34, v122
	v_fmac_f32_e32 v131, v35, v123
	v_fmac_f32_e32 v132, v36, v124
	v_fmac_f32_e32 v133, v37, v125
	v_fmac_f32_e32 v134, v38, v126
	v_fmac_f32_e32 v135, v39, v127
	v_cndmask_b32_e32 v112, v112, v128, vcc
	v_cndmask_b32_e32 v113, v113, v129, vcc
	v_cndmask_b32_e32 v114, v114, v130, vcc
	v_cndmask_b32_e32 v115, v115, v131, vcc
	v_cndmask_b32_e32 v116, v116, v132, vcc
	v_cndmask_b32_e32 v117, v117, v133, vcc
	v_cndmask_b32_e32 v118, v118, v134, vcc
	v_cndmask_b32_e32 v119, v119, v135, vcc
	v_mul_f32_e32 v112, 0x3e38aa3b, v112
	v_mul_f32_e32 v113, 0x3e38aa3b, v113
	v_mul_f32_e32 v114, 0x3e38aa3b, v114
	v_mul_f32_e32 v115, 0x3e38aa3b, v115
	v_mul_f32_e32 v116, 0x3e38aa3b, v116
	v_mul_f32_e32 v117, 0x3e38aa3b, v117
	v_mul_f32_e32 v118, 0x3e38aa3b, v118
	v_mul_f32_e32 v119, 0x3e38aa3b, v119
	v_cvt_pk_bf16_f32 v136, v112, v113
	v_cvt_pk_bf16_f32 v137, v114, v115
	v_cvt_pk_bf16_f32 v138, v116, v117
	v_cvt_pk_bf16_f32 v139, v118, v119
	global_store_dwordx4 v7, v[136:139], s[6:7]
	s_nop 1
	v_lshlrev_b32_e32 v112, 16, v84
	v_and_b32_e32 v113, 0xffff0000, v84
	v_lshlrev_b32_e32 v114, 16, v85
	v_and_b32_e32 v115, 0xffff0000, v85
	v_lshlrev_b32_e32 v116, 16, v86
	v_and_b32_e32 v117, 0xffff0000, v86
	v_lshlrev_b32_e32 v118, 16, v87
	v_and_b32_e32 v119, 0xffff0000, v87
	v_mul_f32_e32 v140, v112, v112
	v_mul_f32_e32 v141, v113, v113
	v_fmac_f32_e32 v140, v114, v114
	v_fmac_f32_e32 v141, v115, v115
	v_fmac_f32_e32 v140, v116, v116
	v_fmac_f32_e32 v141, v117, v117
	v_fmac_f32_e32 v140, v118, v118
	v_fmac_f32_e32 v141, v119, v119
	v_add_f32_e32 v140, v140, v141
	s_nop 1
	v_add_f32_dpp v140, v140, v140 quad_perm:[1,0,3,2] row_mask:0xf bank_mask:0xf bound_ctrl:1
	s_nop 1
	v_add_f32_dpp v140, v140, v140 quad_perm:[2,3,0,1] row_mask:0xf bank_mask:0xf bound_ctrl:1
	s_nop 1
	v_add_f32_dpp v140, v140, v140 row_half_mirror row_mask:0xf bank_mask:0xf bound_ctrl:1
	v_fma_f32 v141, v140, s10, v15
	v_rsq_f32_e32 v141, v141
	s_nop 0
	v_mul_f32_e32 v112, v112, v141
	v_mul_f32_e32 v113, v113, v141
	v_mul_f32_e32 v114, v114, v141
	v_mul_f32_e32 v115, v115, v141
	v_mul_f32_e32 v116, v116, v141
	v_mul_f32_e32 v117, v117, v141
	v_mul_f32_e32 v118, v118, v141
	v_mul_f32_e32 v119, v119, v141
	v_mul_f32_e32 v112, v112, v24
	v_mul_f32_e32 v113, v113, v25
	v_mul_f32_e32 v114, v114, v26
	v_mul_f32_e32 v115, v115, v27
	v_mul_f32_e32 v116, v116, v28
	v_mul_f32_e32 v117, v117, v29
	v_mul_f32_e32 v118, v118, v30
	v_mul_f32_e32 v119, v119, v31
	v_mov_b32_dpp v120, v112 quad_perm:[1,0,3,2] row_mask:0xf bank_mask:0xf
	v_mov_b32_dpp v121, v113 quad_perm:[1,0,3,2] row_mask:0xf bank_mask:0xf
	v_mov_b32_dpp v122, v114 quad_perm:[1,0,3,2] row_mask:0xf bank_mask:0xf
	v_mov_b32_dpp v123, v115 quad_perm:[1,0,3,2] row_mask:0xf bank_mask:0xf
	v_mov_b32_dpp v124, v116 quad_perm:[1,0,3,2] row_mask:0xf bank_mask:0xf
	v_mov_b32_dpp v125, v117 quad_perm:[1,0,3,2] row_mask:0xf bank_mask:0xf
	v_mov_b32_dpp v126, v118 quad_perm:[1,0,3,2] row_mask:0xf bank_mask:0xf
	v_mov_b32_dpp v127, v119 quad_perm:[1,0,3,2] row_mask:0xf bank_mask:0xf
	v_mul_f32_e32 v128, s28, v112
	v_mul_f32_e32 v129, s29, v113
	v_mul_f32_e32 v130, s30, v114
	v_mul_f32_e32 v131, s31, v115
	v_mul_f32_e32 v132, s34, v116
	v_mul_f32_e32 v133, s35, v117
	v_mul_f32_e32 v134, s36, v118
	v_mul_f32_e32 v135, s37, v119
	v_fmac_f32_e32 v128, v32, v120
	v_fmac_f32_e32 v129, v33, v121
	v_fmac_f32_e32 v130, v34, v122
	v_fmac_f32_e32 v131, v35, v123
	v_fmac_f32_e32 v132, v36, v124
	v_fmac_f32_e32 v133, v37, v125
	v_fmac_f32_e32 v134, v38, v126
	v_fmac_f32_e32 v135, v39, v127
	v_cndmask_b32_e32 v112, v112, v128, vcc
	v_cndmask_b32_e32 v113, v113, v129, vcc
	v_cndmask_b32_e32 v114, v114, v130, vcc
	v_cndmask_b32_e32 v115, v115, v131, vcc
	v_cndmask_b32_e32 v116, v116, v132, vcc
	v_cndmask_b32_e32 v117, v117, v133, vcc
	v_cndmask_b32_e32 v118, v118, v134, vcc
	v_cndmask_b32_e32 v119, v119, v135, vcc
	v_cvt_pk_bf16_f32 v136, v112, v113
	v_cvt_pk_bf16_f32 v137, v114, v115
	v_cvt_pk_bf16_f32 v138, v116, v117
	v_cvt_pk_bf16_f32 v139, v118, v119
	v_cndmask_b32_e64 v136, v136, v84, s[18:19]
	v_cndmask_b32_e64 v137, v137, v85, s[18:19]
	v_cndmask_b32_e64 v138, v138, v86, s[18:19]
	v_cndmask_b32_e64 v139, v139, v87, s[18:19]
	global_store_dwordx4 v8, v[136:139], s[12:13]
	s_add_u32 s6, s6, 0x200000
	s_addc_u32 s7, s7, 0
	s_add_u32 s12, s12, 0x80000
	s_addc_u32 s13, s13, 0
	s_waitcnt vmcnt(14)
	v_readlane_b32 s28, v11, 40
	v_readlane_b32 s38, v12, 40
	v_readlane_b32 s29, v11, 41
	v_readlane_b32 s39, v12, 41
	v_readlane_b32 s30, v11, 42
	v_readlane_b32 s40, v12, 42
	v_readlane_b32 s31, v11, 43
	v_readlane_b32 s41, v12, 43
	v_readlane_b32 s34, v11, 44
	v_readlane_b32 s42, v12, 44
	v_readlane_b32 s35, v11, 45
	v_readlane_b32 s43, v12, 45
	v_readlane_b32 s36, v11, 46
	v_readlane_b32 s44, v12, 46
	v_readlane_b32 s37, v11, 47
	v_readlane_b32 s45, v12, 47
	v_mul_f32_e32 v32, s38, v10
	v_mul_f32_e32 v33, s39, v10
	v_mul_f32_e32 v34, s40, v10
	v_mul_f32_e32 v35, s41, v10
	v_mul_f32_e32 v36, s42, v10
	v_mul_f32_e32 v37, s43, v10
	v_mul_f32_e32 v38, s44, v10
	v_mul_f32_e32 v39, s45, v10
	v_lshlrev_b32_e32 v112, 16, v88
	v_and_b32_e32 v113, 0xffff0000, v88
	v_lshlrev_b32_e32 v114, 16, v89
	v_and_b32_e32 v115, 0xffff0000, v89
	v_lshlrev_b32_e32 v116, 16, v90
	v_and_b32_e32 v117, 0xffff0000, v90
	v_lshlrev_b32_e32 v118, 16, v91
	v_and_b32_e32 v119, 0xffff0000, v91
	v_mul_f32_e32 v140, v112, v112
	v_mul_f32_e32 v141, v113, v113
	v_fmac_f32_e32 v140, v114, v114
	v_fmac_f32_e32 v141, v115, v115
	v_fmac_f32_e32 v140, v116, v116
	v_fmac_f32_e32 v141, v117, v117
	v_fmac_f32_e32 v140, v118, v118
	v_fmac_f32_e32 v141, v119, v119
	v_add_f32_e32 v140, v140, v141
	s_nop 1
	v_add_f32_dpp v140, v140, v140 quad_perm:[1,0,3,2] row_mask:0xf bank_mask:0xf bound_ctrl:1
	s_nop 1
	v_add_f32_dpp v140, v140, v140 quad_perm:[2,3,0,1] row_mask:0xf bank_mask:0xf bound_ctrl:1
	s_nop 1
	v_add_f32_dpp v140, v140, v140 row_half_mirror row_mask:0xf bank_mask:0xf bound_ctrl:1
	v_fma_f32 v141, v140, s10, v15
	v_rsq_f32_e32 v141, v141
	s_nop 0
	v_mul_f32_e32 v112, v112, v141
	v_mul_f32_e32 v113, v113, v141
	v_mul_f32_e32 v114, v114, v141
	v_mul_f32_e32 v115, v115, v141
	v_mul_f32_e32 v116, v116, v141
	v_mul_f32_e32 v117, v117, v141
	v_mul_f32_e32 v118, v118, v141
	v_mul_f32_e32 v119, v119, v141
	v_mul_f32_e32 v112, v112, v16
	v_mul_f32_e32 v113, v113, v17
	v_mul_f32_e32 v114, v114, v18
	v_mul_f32_e32 v115, v115, v19
	v_mul_f32_e32 v116, v116, v20
	v_mul_f32_e32 v117, v117, v21
	v_mul_f32_e32 v118, v118, v22
	v_mul_f32_e32 v119, v119, v23
	v_mov_b32_dpp v120, v112 quad_perm:[1,0,3,2] row_mask:0xf bank_mask:0xf
	v_mov_b32_dpp v121, v113 quad_perm:[1,0,3,2] row_mask:0xf bank_mask:0xf
	v_mov_b32_dpp v122, v114 quad_perm:[1,0,3,2] row_mask:0xf bank_mask:0xf
	v_mov_b32_dpp v123, v115 quad_perm:[1,0,3,2] row_mask:0xf bank_mask:0xf
	v_mov_b32_dpp v124, v116 quad_perm:[1,0,3,2] row_mask:0xf bank_mask:0xf
	v_mov_b32_dpp v125, v117 quad_perm:[1,0,3,2] row_mask:0xf bank_mask:0xf
	v_mov_b32_dpp v126, v118 quad_perm:[1,0,3,2] row_mask:0xf bank_mask:0xf
	v_mov_b32_dpp v127, v119 quad_perm:[1,0,3,2] row_mask:0xf bank_mask:0xf
	v_mul_f32_e32 v128, s28, v112
	v_mul_f32_e32 v129, s29, v113
	v_mul_f32_e32 v130, s30, v114
	v_mul_f32_e32 v131, s31, v115
	v_mul_f32_e32 v132, s34, v116
	v_mul_f32_e32 v133, s35, v117
	v_mul_f32_e32 v134, s36, v118
	v_mul_f32_e32 v135, s37, v119
	v_fmac_f32_e32 v128, v32, v120
	v_fmac_f32_e32 v129, v33, v121
	v_fmac_f32_e32 v130, v34, v122
	v_fmac_f32_e32 v131, v35, v123
	v_fmac_f32_e32 v132, v36, v124
	v_fmac_f32_e32 v133, v37, v125
	v_fmac_f32_e32 v134, v38, v126
	v_fmac_f32_e32 v135, v39, v127
	v_cndmask_b32_e32 v112, v112, v128, vcc
	v_cndmask_b32_e32 v113, v113, v129, vcc
	v_cndmask_b32_e32 v114, v114, v130, vcc
	v_cndmask_b32_e32 v115, v115, v131, vcc
	v_cndmask_b32_e32 v116, v116, v132, vcc
	v_cndmask_b32_e32 v117, v117, v133, vcc
	v_cndmask_b32_e32 v118, v118, v134, vcc
	v_cndmask_b32_e32 v119, v119, v135, vcc
	v_mul_f32_e32 v112, 0x3e38aa3b, v112
	v_mul_f32_e32 v113, 0x3e38aa3b, v113
	v_mul_f32_e32 v114, 0x3e38aa3b, v114
	v_mul_f32_e32 v115, 0x3e38aa3b, v115
	v_mul_f32_e32 v116, 0x3e38aa3b, v116
	v_mul_f32_e32 v117, 0x3e38aa3b, v117
	v_mul_f32_e32 v118, 0x3e38aa3b, v118
	v_mul_f32_e32 v119, 0x3e38aa3b, v119
	v_cvt_pk_bf16_f32 v136, v112, v113
	v_cvt_pk_bf16_f32 v137, v114, v115
	v_cvt_pk_bf16_f32 v138, v116, v117
	v_cvt_pk_bf16_f32 v139, v118, v119
	global_store_dwordx4 v7, v[136:139], s[6:7]
	s_nop 1
	v_lshlrev_b32_e32 v112, 16, v92
	v_and_b32_e32 v113, 0xffff0000, v92
	v_lshlrev_b32_e32 v114, 16, v93
	v_and_b32_e32 v115, 0xffff0000, v93
	v_lshlrev_b32_e32 v116, 16, v94
	v_and_b32_e32 v117, 0xffff0000, v94
	v_lshlrev_b32_e32 v118, 16, v95
	v_and_b32_e32 v119, 0xffff0000, v95
	v_mul_f32_e32 v140, v112, v112
	v_mul_f32_e32 v141, v113, v113
	v_fmac_f32_e32 v140, v114, v114
	v_fmac_f32_e32 v141, v115, v115
	v_fmac_f32_e32 v140, v116, v116
	v_fmac_f32_e32 v141, v117, v117
	v_fmac_f32_e32 v140, v118, v118
	v_fmac_f32_e32 v141, v119, v119
	v_add_f32_e32 v140, v140, v141
	s_nop 1
	v_add_f32_dpp v140, v140, v140 quad_perm:[1,0,3,2] row_mask:0xf bank_mask:0xf bound_ctrl:1
	s_nop 1
	v_add_f32_dpp v140, v140, v140 quad_perm:[2,3,0,1] row_mask:0xf bank_mask:0xf bound_ctrl:1
	s_nop 1
	v_add_f32_dpp v140, v140, v140 row_half_mirror row_mask:0xf bank_mask:0xf bound_ctrl:1
	v_fma_f32 v141, v140, s10, v15
	v_rsq_f32_e32 v141, v141
	s_nop 0
	v_mul_f32_e32 v112, v112, v141
	v_mul_f32_e32 v113, v113, v141
	v_mul_f32_e32 v114, v114, v141
	v_mul_f32_e32 v115, v115, v141
	v_mul_f32_e32 v116, v116, v141
	v_mul_f32_e32 v117, v117, v141
	v_mul_f32_e32 v118, v118, v141
	v_mul_f32_e32 v119, v119, v141
	v_mul_f32_e32 v112, v112, v24
	v_mul_f32_e32 v113, v113, v25
	v_mul_f32_e32 v114, v114, v26
	v_mul_f32_e32 v115, v115, v27
	v_mul_f32_e32 v116, v116, v28
	v_mul_f32_e32 v117, v117, v29
	v_mul_f32_e32 v118, v118, v30
	v_mul_f32_e32 v119, v119, v31
	v_mov_b32_dpp v120, v112 quad_perm:[1,0,3,2] row_mask:0xf bank_mask:0xf
	v_mov_b32_dpp v121, v113 quad_perm:[1,0,3,2] row_mask:0xf bank_mask:0xf
	v_mov_b32_dpp v122, v114 quad_perm:[1,0,3,2] row_mask:0xf bank_mask:0xf
	v_mov_b32_dpp v123, v115 quad_perm:[1,0,3,2] row_mask:0xf bank_mask:0xf
	v_mov_b32_dpp v124, v116 quad_perm:[1,0,3,2] row_mask:0xf bank_mask:0xf
	v_mov_b32_dpp v125, v117 quad_perm:[1,0,3,2] row_mask:0xf bank_mask:0xf
	v_mov_b32_dpp v126, v118 quad_perm:[1,0,3,2] row_mask:0xf bank_mask:0xf
	v_mov_b32_dpp v127, v119 quad_perm:[1,0,3,2] row_mask:0xf bank_mask:0xf
	v_mul_f32_e32 v128, s28, v112
	v_mul_f32_e32 v129, s29, v113
	v_mul_f32_e32 v130, s30, v114
	v_mul_f32_e32 v131, s31, v115
	v_mul_f32_e32 v132, s34, v116
	v_mul_f32_e32 v133, s35, v117
	v_mul_f32_e32 v134, s36, v118
	v_mul_f32_e32 v135, s37, v119
	v_fmac_f32_e32 v128, v32, v120
	v_fmac_f32_e32 v129, v33, v121
	v_fmac_f32_e32 v130, v34, v122
	v_fmac_f32_e32 v131, v35, v123
	v_fmac_f32_e32 v132, v36, v124
	v_fmac_f32_e32 v133, v37, v125
	v_fmac_f32_e32 v134, v38, v126
	v_fmac_f32_e32 v135, v39, v127
	v_cndmask_b32_e32 v112, v112, v128, vcc
	v_cndmask_b32_e32 v113, v113, v129, vcc
	v_cndmask_b32_e32 v114, v114, v130, vcc
	v_cndmask_b32_e32 v115, v115, v131, vcc
	v_cndmask_b32_e32 v116, v116, v132, vcc
	v_cndmask_b32_e32 v117, v117, v133, vcc
	v_cndmask_b32_e32 v118, v118, v134, vcc
	v_cndmask_b32_e32 v119, v119, v135, vcc
	v_cvt_pk_bf16_f32 v136, v112, v113
	v_cvt_pk_bf16_f32 v137, v114, v115
	v_cvt_pk_bf16_f32 v138, v116, v117
	v_cvt_pk_bf16_f32 v139, v118, v119
	v_cndmask_b32_e64 v136, v136, v92, s[18:19]
	v_cndmask_b32_e64 v137, v137, v93, s[18:19]
	v_cndmask_b32_e64 v138, v138, v94, s[18:19]
	v_cndmask_b32_e64 v139, v139, v95, s[18:19]
	global_store_dwordx4 v8, v[136:139], s[12:13]
	s_add_u32 s6, s6, 0x200000
	s_addc_u32 s7, s7, 0
	s_add_u32 s12, s12, 0x80000
	s_addc_u32 s13, s13, 0
	s_waitcnt vmcnt(14)
	v_readlane_b32 s28, v11, 48
	v_readlane_b32 s38, v12, 48
	v_readlane_b32 s29, v11, 49
	v_readlane_b32 s39, v12, 49
	v_readlane_b32 s30, v11, 50
	v_readlane_b32 s40, v12, 50
	v_readlane_b32 s31, v11, 51
	v_readlane_b32 s41, v12, 51
	v_readlane_b32 s34, v11, 52
	v_readlane_b32 s42, v12, 52
	v_readlane_b32 s35, v11, 53
	v_readlane_b32 s43, v12, 53
	v_readlane_b32 s36, v11, 54
	v_readlane_b32 s44, v12, 54
	v_readlane_b32 s37, v11, 55
	v_readlane_b32 s45, v12, 55
	v_mul_f32_e32 v32, s38, v10
	v_mul_f32_e32 v33, s39, v10
	v_mul_f32_e32 v34, s40, v10
	v_mul_f32_e32 v35, s41, v10
	v_mul_f32_e32 v36, s42, v10
	v_mul_f32_e32 v37, s43, v10
	v_mul_f32_e32 v38, s44, v10
	v_mul_f32_e32 v39, s45, v10
	v_lshlrev_b32_e32 v112, 16, v96
	v_and_b32_e32 v113, 0xffff0000, v96
	v_lshlrev_b32_e32 v114, 16, v97
	v_and_b32_e32 v115, 0xffff0000, v97
	v_lshlrev_b32_e32 v116, 16, v98
	v_and_b32_e32 v117, 0xffff0000, v98
	v_lshlrev_b32_e32 v118, 16, v99
	v_and_b32_e32 v119, 0xffff0000, v99
	v_mul_f32_e32 v140, v112, v112
	v_mul_f32_e32 v141, v113, v113
	v_fmac_f32_e32 v140, v114, v114
	v_fmac_f32_e32 v141, v115, v115
	v_fmac_f32_e32 v140, v116, v116
	v_fmac_f32_e32 v141, v117, v117
	v_fmac_f32_e32 v140, v118, v118
	v_fmac_f32_e32 v141, v119, v119
	v_add_f32_e32 v140, v140, v141
	s_nop 1
	v_add_f32_dpp v140, v140, v140 quad_perm:[1,0,3,2] row_mask:0xf bank_mask:0xf bound_ctrl:1
	s_nop 1
	v_add_f32_dpp v140, v140, v140 quad_perm:[2,3,0,1] row_mask:0xf bank_mask:0xf bound_ctrl:1
	s_nop 1
	v_add_f32_dpp v140, v140, v140 row_half_mirror row_mask:0xf bank_mask:0xf bound_ctrl:1
	v_fma_f32 v141, v140, s10, v15
	v_rsq_f32_e32 v141, v141
	s_nop 0
	v_mul_f32_e32 v112, v112, v141
	v_mul_f32_e32 v113, v113, v141
	v_mul_f32_e32 v114, v114, v141
	v_mul_f32_e32 v115, v115, v141
	v_mul_f32_e32 v116, v116, v141
	v_mul_f32_e32 v117, v117, v141
	v_mul_f32_e32 v118, v118, v141
	v_mul_f32_e32 v119, v119, v141
	v_mul_f32_e32 v112, v112, v16
	v_mul_f32_e32 v113, v113, v17
	v_mul_f32_e32 v114, v114, v18
	v_mul_f32_e32 v115, v115, v19
	v_mul_f32_e32 v116, v116, v20
	v_mul_f32_e32 v117, v117, v21
	v_mul_f32_e32 v118, v118, v22
	v_mul_f32_e32 v119, v119, v23
	v_mov_b32_dpp v120, v112 quad_perm:[1,0,3,2] row_mask:0xf bank_mask:0xf
	v_mov_b32_dpp v121, v113 quad_perm:[1,0,3,2] row_mask:0xf bank_mask:0xf
	v_mov_b32_dpp v122, v114 quad_perm:[1,0,3,2] row_mask:0xf bank_mask:0xf
	v_mov_b32_dpp v123, v115 quad_perm:[1,0,3,2] row_mask:0xf bank_mask:0xf
	v_mov_b32_dpp v124, v116 quad_perm:[1,0,3,2] row_mask:0xf bank_mask:0xf
	v_mov_b32_dpp v125, v117 quad_perm:[1,0,3,2] row_mask:0xf bank_mask:0xf
	v_mov_b32_dpp v126, v118 quad_perm:[1,0,3,2] row_mask:0xf bank_mask:0xf
	v_mov_b32_dpp v127, v119 quad_perm:[1,0,3,2] row_mask:0xf bank_mask:0xf
	v_mul_f32_e32 v128, s28, v112
	v_mul_f32_e32 v129, s29, v113
	v_mul_f32_e32 v130, s30, v114
	v_mul_f32_e32 v131, s31, v115
	v_mul_f32_e32 v132, s34, v116
	v_mul_f32_e32 v133, s35, v117
	v_mul_f32_e32 v134, s36, v118
	v_mul_f32_e32 v135, s37, v119
	v_fmac_f32_e32 v128, v32, v120
	v_fmac_f32_e32 v129, v33, v121
	v_fmac_f32_e32 v130, v34, v122
	v_fmac_f32_e32 v131, v35, v123
	v_fmac_f32_e32 v132, v36, v124
	v_fmac_f32_e32 v133, v37, v125
	v_fmac_f32_e32 v134, v38, v126
	v_fmac_f32_e32 v135, v39, v127
	v_cndmask_b32_e32 v112, v112, v128, vcc
	v_cndmask_b32_e32 v113, v113, v129, vcc
	v_cndmask_b32_e32 v114, v114, v130, vcc
	v_cndmask_b32_e32 v115, v115, v131, vcc
	v_cndmask_b32_e32 v116, v116, v132, vcc
	v_cndmask_b32_e32 v117, v117, v133, vcc
	v_cndmask_b32_e32 v118, v118, v134, vcc
	v_cndmask_b32_e32 v119, v119, v135, vcc
	v_mul_f32_e32 v112, 0x3e38aa3b, v112
	v_mul_f32_e32 v113, 0x3e38aa3b, v113
	v_mul_f32_e32 v114, 0x3e38aa3b, v114
	v_mul_f32_e32 v115, 0x3e38aa3b, v115
	v_mul_f32_e32 v116, 0x3e38aa3b, v116
	v_mul_f32_e32 v117, 0x3e38aa3b, v117
	v_mul_f32_e32 v118, 0x3e38aa3b, v118
	v_mul_f32_e32 v119, 0x3e38aa3b, v119
	v_cvt_pk_bf16_f32 v136, v112, v113
	v_cvt_pk_bf16_f32 v137, v114, v115
	v_cvt_pk_bf16_f32 v138, v116, v117
	v_cvt_pk_bf16_f32 v139, v118, v119
	global_store_dwordx4 v7, v[136:139], s[6:7]
	s_nop 1
	v_lshlrev_b32_e32 v112, 16, v100
	v_and_b32_e32 v113, 0xffff0000, v100
	v_lshlrev_b32_e32 v114, 16, v101
	v_and_b32_e32 v115, 0xffff0000, v101
	v_lshlrev_b32_e32 v116, 16, v102
	v_and_b32_e32 v117, 0xffff0000, v102
	v_lshlrev_b32_e32 v118, 16, v103
	v_and_b32_e32 v119, 0xffff0000, v103
	v_mul_f32_e32 v140, v112, v112
	v_mul_f32_e32 v141, v113, v113
	v_fmac_f32_e32 v140, v114, v114
	v_fmac_f32_e32 v141, v115, v115
	v_fmac_f32_e32 v140, v116, v116
	v_fmac_f32_e32 v141, v117, v117
	v_fmac_f32_e32 v140, v118, v118
	v_fmac_f32_e32 v141, v119, v119
	v_add_f32_e32 v140, v140, v141
	s_nop 1
	v_add_f32_dpp v140, v140, v140 quad_perm:[1,0,3,2] row_mask:0xf bank_mask:0xf bound_ctrl:1
	s_nop 1
	v_add_f32_dpp v140, v140, v140 quad_perm:[2,3,0,1] row_mask:0xf bank_mask:0xf bound_ctrl:1
	s_nop 1
	v_add_f32_dpp v140, v140, v140 row_half_mirror row_mask:0xf bank_mask:0xf bound_ctrl:1
	v_fma_f32 v141, v140, s10, v15
	v_rsq_f32_e32 v141, v141
	s_nop 0
	v_mul_f32_e32 v112, v112, v141
	v_mul_f32_e32 v113, v113, v141
	v_mul_f32_e32 v114, v114, v141
	v_mul_f32_e32 v115, v115, v141
	v_mul_f32_e32 v116, v116, v141
	v_mul_f32_e32 v117, v117, v141
	v_mul_f32_e32 v118, v118, v141
	v_mul_f32_e32 v119, v119, v141
	v_mul_f32_e32 v112, v112, v24
	v_mul_f32_e32 v113, v113, v25
	v_mul_f32_e32 v114, v114, v26
	v_mul_f32_e32 v115, v115, v27
	v_mul_f32_e32 v116, v116, v28
	v_mul_f32_e32 v117, v117, v29
	v_mul_f32_e32 v118, v118, v30
	v_mul_f32_e32 v119, v119, v31
	v_mov_b32_dpp v120, v112 quad_perm:[1,0,3,2] row_mask:0xf bank_mask:0xf
	v_mov_b32_dpp v121, v113 quad_perm:[1,0,3,2] row_mask:0xf bank_mask:0xf
	v_mov_b32_dpp v122, v114 quad_perm:[1,0,3,2] row_mask:0xf bank_mask:0xf
	v_mov_b32_dpp v123, v115 quad_perm:[1,0,3,2] row_mask:0xf bank_mask:0xf
	v_mov_b32_dpp v124, v116 quad_perm:[1,0,3,2] row_mask:0xf bank_mask:0xf
	v_mov_b32_dpp v125, v117 quad_perm:[1,0,3,2] row_mask:0xf bank_mask:0xf
	v_mov_b32_dpp v126, v118 quad_perm:[1,0,3,2] row_mask:0xf bank_mask:0xf
	v_mov_b32_dpp v127, v119 quad_perm:[1,0,3,2] row_mask:0xf bank_mask:0xf
	v_mul_f32_e32 v128, s28, v112
	v_mul_f32_e32 v129, s29, v113
	v_mul_f32_e32 v130, s30, v114
	v_mul_f32_e32 v131, s31, v115
	v_mul_f32_e32 v132, s34, v116
	v_mul_f32_e32 v133, s35, v117
	v_mul_f32_e32 v134, s36, v118
	v_mul_f32_e32 v135, s37, v119
	v_fmac_f32_e32 v128, v32, v120
	v_fmac_f32_e32 v129, v33, v121
	v_fmac_f32_e32 v130, v34, v122
	v_fmac_f32_e32 v131, v35, v123
	v_fmac_f32_e32 v132, v36, v124
	v_fmac_f32_e32 v133, v37, v125
	v_fmac_f32_e32 v134, v38, v126
	v_fmac_f32_e32 v135, v39, v127
	v_cndmask_b32_e32 v112, v112, v128, vcc
	v_cndmask_b32_e32 v113, v113, v129, vcc
	v_cndmask_b32_e32 v114, v114, v130, vcc
	v_cndmask_b32_e32 v115, v115, v131, vcc
	v_cndmask_b32_e32 v116, v116, v132, vcc
	v_cndmask_b32_e32 v117, v117, v133, vcc
	v_cndmask_b32_e32 v118, v118, v134, vcc
	v_cndmask_b32_e32 v119, v119, v135, vcc
	v_cvt_pk_bf16_f32 v136, v112, v113
	v_cvt_pk_bf16_f32 v137, v114, v115
	v_cvt_pk_bf16_f32 v138, v116, v117
	v_cvt_pk_bf16_f32 v139, v118, v119
	v_cndmask_b32_e64 v136, v136, v100, s[18:19]
	v_cndmask_b32_e64 v137, v137, v101, s[18:19]
	v_cndmask_b32_e64 v138, v138, v102, s[18:19]
	v_cndmask_b32_e64 v139, v139, v103, s[18:19]
	global_store_dwordx4 v8, v[136:139], s[12:13]
	s_add_u32 s6, s6, 0x200000
	s_addc_u32 s7, s7, 0
	s_add_u32 s12, s12, 0x80000
	s_addc_u32 s13, s13, 0
	s_waitcnt vmcnt(14)
	v_readlane_b32 s28, v11, 56
	v_readlane_b32 s38, v12, 56
	v_readlane_b32 s29, v11, 57
	v_readlane_b32 s39, v12, 57
	v_readlane_b32 s30, v11, 58
	v_readlane_b32 s40, v12, 58
	v_readlane_b32 s31, v11, 59
	v_readlane_b32 s41, v12, 59
	v_readlane_b32 s34, v11, 60
	v_readlane_b32 s42, v12, 60
	v_readlane_b32 s35, v11, 61
	v_readlane_b32 s43, v12, 61
	v_readlane_b32 s36, v11, 62
	v_readlane_b32 s44, v12, 62
	v_readlane_b32 s37, v11, 63
	v_readlane_b32 s45, v12, 63
	v_mul_f32_e32 v32, s38, v10
	v_mul_f32_e32 v33, s39, v10
	v_mul_f32_e32 v34, s40, v10
	v_mul_f32_e32 v35, s41, v10
	v_mul_f32_e32 v36, s42, v10
	v_mul_f32_e32 v37, s43, v10
	v_mul_f32_e32 v38, s44, v10
	v_mul_f32_e32 v39, s45, v10
	v_lshlrev_b32_e32 v112, 16, v104
	v_and_b32_e32 v113, 0xffff0000, v104
	v_lshlrev_b32_e32 v114, 16, v105
	v_and_b32_e32 v115, 0xffff0000, v105
	v_lshlrev_b32_e32 v116, 16, v106
	v_and_b32_e32 v117, 0xffff0000, v106
	v_lshlrev_b32_e32 v118, 16, v107
	v_and_b32_e32 v119, 0xffff0000, v107
	v_mul_f32_e32 v140, v112, v112
	v_mul_f32_e32 v141, v113, v113
	v_fmac_f32_e32 v140, v114, v114
	v_fmac_f32_e32 v141, v115, v115
	v_fmac_f32_e32 v140, v116, v116
	v_fmac_f32_e32 v141, v117, v117
	v_fmac_f32_e32 v140, v118, v118
	v_fmac_f32_e32 v141, v119, v119
	v_add_f32_e32 v140, v140, v141
	s_nop 1
	v_add_f32_dpp v140, v140, v140 quad_perm:[1,0,3,2] row_mask:0xf bank_mask:0xf bound_ctrl:1
	s_nop 1
	v_add_f32_dpp v140, v140, v140 quad_perm:[2,3,0,1] row_mask:0xf bank_mask:0xf bound_ctrl:1
	s_nop 1
	v_add_f32_dpp v140, v140, v140 row_half_mirror row_mask:0xf bank_mask:0xf bound_ctrl:1
	v_fma_f32 v141, v140, s10, v15
	v_rsq_f32_e32 v141, v141
	s_nop 0
	v_mul_f32_e32 v112, v112, v141
	v_mul_f32_e32 v113, v113, v141
	v_mul_f32_e32 v114, v114, v141
	v_mul_f32_e32 v115, v115, v141
	v_mul_f32_e32 v116, v116, v141
	v_mul_f32_e32 v117, v117, v141
	v_mul_f32_e32 v118, v118, v141
	v_mul_f32_e32 v119, v119, v141
	v_mul_f32_e32 v112, v112, v16
	v_mul_f32_e32 v113, v113, v17
	v_mul_f32_e32 v114, v114, v18
	v_mul_f32_e32 v115, v115, v19
	v_mul_f32_e32 v116, v116, v20
	v_mul_f32_e32 v117, v117, v21
	v_mul_f32_e32 v118, v118, v22
	v_mul_f32_e32 v119, v119, v23
	v_mov_b32_dpp v120, v112 quad_perm:[1,0,3,2] row_mask:0xf bank_mask:0xf
	v_mov_b32_dpp v121, v113 quad_perm:[1,0,3,2] row_mask:0xf bank_mask:0xf
	v_mov_b32_dpp v122, v114 quad_perm:[1,0,3,2] row_mask:0xf bank_mask:0xf
	v_mov_b32_dpp v123, v115 quad_perm:[1,0,3,2] row_mask:0xf bank_mask:0xf
	v_mov_b32_dpp v124, v116 quad_perm:[1,0,3,2] row_mask:0xf bank_mask:0xf
	v_mov_b32_dpp v125, v117 quad_perm:[1,0,3,2] row_mask:0xf bank_mask:0xf
	v_mov_b32_dpp v126, v118 quad_perm:[1,0,3,2] row_mask:0xf bank_mask:0xf
	v_mov_b32_dpp v127, v119 quad_perm:[1,0,3,2] row_mask:0xf bank_mask:0xf
	v_mul_f32_e32 v128, s28, v112
	v_mul_f32_e32 v129, s29, v113
	v_mul_f32_e32 v130, s30, v114
	v_mul_f32_e32 v131, s31, v115
	v_mul_f32_e32 v132, s34, v116
	v_mul_f32_e32 v133, s35, v117
	v_mul_f32_e32 v134, s36, v118
	v_mul_f32_e32 v135, s37, v119
	v_fmac_f32_e32 v128, v32, v120
	v_fmac_f32_e32 v129, v33, v121
	v_fmac_f32_e32 v130, v34, v122
	v_fmac_f32_e32 v131, v35, v123
	v_fmac_f32_e32 v132, v36, v124
	v_fmac_f32_e32 v133, v37, v125
	v_fmac_f32_e32 v134, v38, v126
	v_fmac_f32_e32 v135, v39, v127
	v_cndmask_b32_e32 v112, v112, v128, vcc
	v_cndmask_b32_e32 v113, v113, v129, vcc
	v_cndmask_b32_e32 v114, v114, v130, vcc
	v_cndmask_b32_e32 v115, v115, v131, vcc
	v_cndmask_b32_e32 v116, v116, v132, vcc
	v_cndmask_b32_e32 v117, v117, v133, vcc
	v_cndmask_b32_e32 v118, v118, v134, vcc
	v_cndmask_b32_e32 v119, v119, v135, vcc
	v_mul_f32_e32 v112, 0x3e38aa3b, v112
	v_mul_f32_e32 v113, 0x3e38aa3b, v113
	v_mul_f32_e32 v114, 0x3e38aa3b, v114
	v_mul_f32_e32 v115, 0x3e38aa3b, v115
	v_mul_f32_e32 v116, 0x3e38aa3b, v116
	v_mul_f32_e32 v117, 0x3e38aa3b, v117
	v_mul_f32_e32 v118, 0x3e38aa3b, v118
	v_mul_f32_e32 v119, 0x3e38aa3b, v119
	v_cvt_pk_bf16_f32 v136, v112, v113
	v_cvt_pk_bf16_f32 v137, v114, v115
	v_cvt_pk_bf16_f32 v138, v116, v117
	v_cvt_pk_bf16_f32 v139, v118, v119
	global_store_dwordx4 v7, v[136:139], s[6:7]
	s_nop 1
	v_lshlrev_b32_e32 v112, 16, v108
	v_and_b32_e32 v113, 0xffff0000, v108
	v_lshlrev_b32_e32 v114, 16, v109
	v_and_b32_e32 v115, 0xffff0000, v109
	v_lshlrev_b32_e32 v116, 16, v110
	v_and_b32_e32 v117, 0xffff0000, v110
	v_lshlrev_b32_e32 v118, 16, v111
	v_and_b32_e32 v119, 0xffff0000, v111
	v_mul_f32_e32 v140, v112, v112
	v_mul_f32_e32 v141, v113, v113
	v_fmac_f32_e32 v140, v114, v114
	v_fmac_f32_e32 v141, v115, v115
	v_fmac_f32_e32 v140, v116, v116
	v_fmac_f32_e32 v141, v117, v117
	v_fmac_f32_e32 v140, v118, v118
	v_fmac_f32_e32 v141, v119, v119
	v_add_f32_e32 v140, v140, v141
	s_nop 1
	v_add_f32_dpp v140, v140, v140 quad_perm:[1,0,3,2] row_mask:0xf bank_mask:0xf bound_ctrl:1
	s_nop 1
	v_add_f32_dpp v140, v140, v140 quad_perm:[2,3,0,1] row_mask:0xf bank_mask:0xf bound_ctrl:1
	s_nop 1
	v_add_f32_dpp v140, v140, v140 row_half_mirror row_mask:0xf bank_mask:0xf bound_ctrl:1
	v_fma_f32 v141, v140, s10, v15
	v_rsq_f32_e32 v141, v141
	s_nop 0
	v_mul_f32_e32 v112, v112, v141
	v_mul_f32_e32 v113, v113, v141
	v_mul_f32_e32 v114, v114, v141
	v_mul_f32_e32 v115, v115, v141
	v_mul_f32_e32 v116, v116, v141
	v_mul_f32_e32 v117, v117, v141
	v_mul_f32_e32 v118, v118, v141
	v_mul_f32_e32 v119, v119, v141
	v_mul_f32_e32 v112, v112, v24
	v_mul_f32_e32 v113, v113, v25
	v_mul_f32_e32 v114, v114, v26
	v_mul_f32_e32 v115, v115, v27
	v_mul_f32_e32 v116, v116, v28
	v_mul_f32_e32 v117, v117, v29
	v_mul_f32_e32 v118, v118, v30
	v_mul_f32_e32 v119, v119, v31
	v_mov_b32_dpp v120, v112 quad_perm:[1,0,3,2] row_mask:0xf bank_mask:0xf
	v_mov_b32_dpp v121, v113 quad_perm:[1,0,3,2] row_mask:0xf bank_mask:0xf
	v_mov_b32_dpp v122, v114 quad_perm:[1,0,3,2] row_mask:0xf bank_mask:0xf
	v_mov_b32_dpp v123, v115 quad_perm:[1,0,3,2] row_mask:0xf bank_mask:0xf
	v_mov_b32_dpp v124, v116 quad_perm:[1,0,3,2] row_mask:0xf bank_mask:0xf
	v_mov_b32_dpp v125, v117 quad_perm:[1,0,3,2] row_mask:0xf bank_mask:0xf
	v_mov_b32_dpp v126, v118 quad_perm:[1,0,3,2] row_mask:0xf bank_mask:0xf
	v_mov_b32_dpp v127, v119 quad_perm:[1,0,3,2] row_mask:0xf bank_mask:0xf
	v_mul_f32_e32 v128, s28, v112
	v_mul_f32_e32 v129, s29, v113
	v_mul_f32_e32 v130, s30, v114
	v_mul_f32_e32 v131, s31, v115
	v_mul_f32_e32 v132, s34, v116
	v_mul_f32_e32 v133, s35, v117
	v_mul_f32_e32 v134, s36, v118
	v_mul_f32_e32 v135, s37, v119
	v_fmac_f32_e32 v128, v32, v120
	v_fmac_f32_e32 v129, v33, v121
	v_fmac_f32_e32 v130, v34, v122
	v_fmac_f32_e32 v131, v35, v123
	v_fmac_f32_e32 v132, v36, v124
	v_fmac_f32_e32 v133, v37, v125
	v_fmac_f32_e32 v134, v38, v126
	v_fmac_f32_e32 v135, v39, v127
	v_cndmask_b32_e32 v112, v112, v128, vcc
	v_cndmask_b32_e32 v113, v113, v129, vcc
	v_cndmask_b32_e32 v114, v114, v130, vcc
	v_cndmask_b32_e32 v115, v115, v131, vcc
	v_cndmask_b32_e32 v116, v116, v132, vcc
	v_cndmask_b32_e32 v117, v117, v133, vcc
	v_cndmask_b32_e32 v118, v118, v134, vcc
	v_cndmask_b32_e32 v119, v119, v135, vcc
	v_cvt_pk_bf16_f32 v136, v112, v113
	v_cvt_pk_bf16_f32 v137, v114, v115
	v_cvt_pk_bf16_f32 v138, v116, v117
	v_cvt_pk_bf16_f32 v139, v118, v119
	v_cndmask_b32_e64 v136, v136, v108, s[18:19]
	v_cndmask_b32_e64 v137, v137, v109, s[18:19]
	v_cndmask_b32_e64 v138, v138, v110, s[18:19]
	v_cndmask_b32_e64 v139, v139, v111, s[18:19]
	global_store_dwordx4 v8, v[136:139], s[12:13]
	s_add_u32 s6, s6, 0x200000
	s_addc_u32 s7, s7, 0
	s_add_u32 s12, s12, 0x80000
	s_addc_u32 s13, s13, 0
	s_branch .LBB0_278
	s_nop 0
	s_nop 0
	s_nop 0
	s_nop 0
	s_nop 0
	s_nop 0
	s_nop 0
	s_nop 0
	s_nop 0
	s_nop 0
	s_nop 0
	s_nop 0
	s_nop 0
	s_nop 0
	s_nop 0
	s_nop 0
	s_nop 0
	s_nop 0
	s_nop 0
	s_nop 0
	s_nop 0
	s_nop 0
	s_nop 0
	s_nop 0
	s_nop 0
	s_nop 0
	s_nop 0
	s_nop 0
	s_nop 0
	s_nop 0
	s_nop 0
	s_nop 0
	s_nop 0
	s_nop 0
	s_nop 0
	s_nop 0
	s_nop 0
	s_nop 0
	s_nop 0
	s_nop 0
	s_nop 0
	s_nop 0
	s_nop 0
	s_nop 0
	s_nop 0
	s_nop 0
	s_nop 0
	s_nop 0
	s_nop 0
	s_nop 0
	s_nop 0
	s_nop 0
	s_nop 0
	s_nop 0
	s_nop 0
	s_nop 0
	s_nop 0
	s_nop 0
	s_nop 0
	s_nop 0
	s_nop 0
	s_nop 0
	s_nop 0
	s_nop 0
	s_nop 0
	s_nop 0
	s_nop 0
	s_nop 0
	s_nop 0
	s_nop 0
	s_nop 0
	s_nop 0
	s_nop 0
	s_nop 0
	s_nop 0
	s_nop 0
	s_nop 0
	s_nop 0
	s_nop 0
	s_nop 0
	s_nop 0
	s_nop 0
	s_nop 0
	s_nop 0
	s_nop 0
	s_nop 0
	s_nop 0
	s_nop 0
	s_nop 0
	s_nop 0
	s_nop 0
	s_nop 0
	s_nop 0
	s_nop 0
	s_nop 0
	s_nop 0
	s_nop 0
	s_nop 0
	s_nop 0
	s_nop 0
	s_nop 0
	s_nop 0
	s_nop 0
	s_nop 0
	s_nop 0
	s_nop 0
	s_nop 0
	s_nop 0
	s_nop 0
	s_nop 0
	s_nop 0
	s_nop 0
	s_nop 0
	s_nop 0
	s_nop 0
	s_nop 0
	s_nop 0
	s_nop 0
	s_nop 0
	s_nop 0
	s_nop 0
	s_nop 0
	s_nop 0
	s_nop 0
	s_nop 0
	s_nop 0
	s_nop 0
	s_nop 0
	s_nop 0
	s_nop 0
	s_nop 0
	s_nop 0
	s_nop 0
	s_nop 0
	s_nop 0
	s_nop 0
	s_nop 0
	s_nop 0
	s_nop 0
	s_nop 0
	s_nop 0
	s_nop 0
	s_nop 0
	s_nop 0
	s_nop 0
	s_nop 0
	s_nop 0
	s_nop 0
	s_nop 0
	s_nop 0
	s_nop 0
	s_nop 0
	s_nop 0
	s_nop 0
	s_nop 0
	s_nop 0
	s_nop 0
	s_nop 0
	s_nop 0
	s_nop 0
	s_nop 0
	s_nop 0
	s_nop 0
	s_nop 0
	s_nop 0
	s_nop 0
	s_nop 0
	s_nop 0
	s_nop 0
	s_nop 0
	s_nop 0
	s_nop 0
	s_nop 0
	s_nop 0
	s_nop 0
	s_nop 0
	s_nop 0
	s_nop 0
	s_nop 0
	s_nop 0
	s_nop 0
	s_nop 0
	s_nop 0
	s_nop 0
	s_nop 0
	s_nop 0
	s_nop 0
	s_nop 0
	s_nop 0
	s_nop 0
	s_nop 0
	s_nop 0
	s_nop 0
	s_nop 0
	s_nop 0
	s_nop 0
	s_nop 0
	s_nop 0
	s_nop 0
	s_nop 0
	s_nop 0
	s_nop 0
	s_nop 0
	s_nop 0
	s_nop 0
	s_nop 0
	s_nop 0
	s_nop 0
	s_nop 0
	s_nop 0
	s_nop 0
	s_nop 0
	s_nop 0
	s_nop 0
	s_nop 0
	s_nop 0
	s_nop 0
	s_nop 0
	s_nop 0
	s_nop 0
	s_nop 0
	s_nop 0
	s_nop 0
	s_nop 0
	s_nop 0
	s_nop 0
	s_nop 0
	s_nop 0
	s_nop 0
	s_nop 0
	s_nop 0
	s_nop 0
	s_nop 0
	s_nop 0
	s_nop 0
	s_nop 0

.LBB0_278:
	v_writelane_b32 v247, s76, 14
	s_cmpk_gt_i32 s84, 0x3ff
	s_nop 0
	v_writelane_b32 v247, s77, 15
	v_writelane_b32 v247, s75, 16
	v_writelane_b32 v247, s68, 17
	s_nop 1
	v_writelane_b32 v247, s69, 18
	v_writelane_b32 v247, s67, 19
	v_writelane_b32 v247, s71, 20
	s_cmpk_lg_i32 s76, 0x100
	s_cbranch_scc1 .Lntr_generic
	s_lshr_b32 s0, s84, 1
	s_and_b32 s1, s84, 1
	s_and_b32 s6, s0, 31
	s_lshr_b32 s7, s0, 7
	s_lshl_b32 s12, s7, 11
	s_lshl_b32 s13, s6, 6
	s_add_i32 s12, s12, s13
	s_lshl_b32 s13, s1, 5
	s_add_i32 s12, s12, s13
	s_mul_i32 s12, s12, 0x1c00
	s_add_u32 s2, s21, s12
	s_addc_u32 s3, s24, 0
	s_bfe_u32 s14, s0, 0x10006
	s_lshl_b32 s13, s14, 7
	s_bitcmp0_b32 s0, 5
	s_movk_i32 s15, 0x1900
	s_mov_b32 s16, 0xe100000
	s_cselect_b32 s15, 0x1700, s15
	s_cselect_b32 s16, 0xd700000, s16
	s_add_i32 s13, s13, s15
	s_add_u32 s2, s2, s13
	s_addc_u32 s3, s3, 0
	s_lshl_b32 s7, s7, 1
	s_add_i32 s7, s7, s14
	s_lshl_b32 s7, s7, 18
	s_lshl_b32 s6, s6, 7
	s_add_i32 s7, s7, s6
	s_lshl_b32 s1, s1, 6
	s_add_i32 s7, s7, s1
	s_add_i32 s7, s7, s16
	s_add_u32 s4, s11, s7
	s_addc_u32 s5, s20, 0
	v_lshlrev_b32_e32 v5, 12, v4
	global_load_ushort v32, v0, s[2:3]
	s_add_u32 s2, s2, 0x1c00
	s_addc_u32 s3, s3, 0
	global_load_ushort v33, v0, s[2:3]
	s_add_u32 s2, s2, 0x1c00
	s_addc_u32 s3, s3, 0
	global_load_ushort v34, v0, s[2:3]
	s_add_u32 s2, s2, 0x1c00
	s_addc_u32 s3, s3, 0
	global_load_ushort v35, v0, s[2:3]
	s_add_u32 s2, s2, 0x1c00
	s_addc_u32 s3, s3, 0
	global_load_ushort v36, v0, s[2:3]
	s_add_u32 s2, s2, 0x1c00
	s_addc_u32 s3, s3, 0
	global_load_ushort v37, v0, s[2:3]
	s_add_u32 s2, s2, 0x1c00
	s_addc_u32 s3, s3, 0
	global_load_ushort v38, v0, s[2:3]
	s_add_u32 s2, s2, 0x1c00
	s_addc_u32 s3, s3, 0
	global_load_ushort v39, v0, s[2:3]
	s_add_u32 s2, s2, 0x1c00
	s_addc_u32 s3, s3, 0
	global_load_ushort v40, v0, s[2:3]
	s_add_u32 s2, s2, 0x1c00
	s_addc_u32 s3, s3, 0
	global_load_ushort v41, v0, s[2:3]
	s_add_u32 s2, s2, 0x1c00
	s_addc_u32 s3, s3, 0
	global_load_ushort v42, v0, s[2:3]
	s_add_u32 s2, s2, 0x1c00
	s_addc_u32 s3, s3, 0
	global_load_ushort v43, v0, s[2:3]
	s_add_u32 s2, s2, 0x1c00
	s_addc_u32 s3, s3, 0
	global_load_ushort v44, v0, s[2:3]
	s_add_u32 s2, s2, 0x1c00
	s_addc_u32 s3, s3, 0
	global_load_ushort v45, v0, s[2:3]
	s_add_u32 s2, s2, 0x1c00
	s_addc_u32 s3, s3, 0
	global_load_ushort v46, v0, s[2:3]
	s_add_u32 s2, s2, 0x1c00
	s_addc_u32 s3, s3, 0
	global_load_ushort v47, v0, s[2:3]
	s_add_u32 s2, s2, 0x1c00
	s_addc_u32 s3, s3, 0
	global_load_ushort v48, v0, s[2:3]
	s_add_u32 s2, s2, 0x1c00
	s_addc_u32 s3, s3, 0
	global_load_ushort v49, v0, s[2:3]
	s_add_u32 s2, s2, 0x1c00
	s_addc_u32 s3, s3, 0
	global_load_ushort v50, v0, s[2:3]
	s_add_u32 s2, s2, 0x1c00
	s_addc_u32 s3, s3, 0
	global_load_ushort v51, v0, s[2:3]
	s_add_u32 s2, s2, 0x1c00
	s_addc_u32 s3, s3, 0
	global_load_ushort v52, v0, s[2:3]
	s_add_u32 s2, s2, 0x1c00
	s_addc_u32 s3, s3, 0
	global_load_ushort v53, v0, s[2:3]
	s_add_u32 s2, s2, 0x1c00
	s_addc_u32 s3, s3, 0
	global_load_ushort v54, v0, s[2:3]
	s_add_u32 s2, s2, 0x1c00
	s_addc_u32 s3, s3, 0
	global_load_ushort v55, v0, s[2:3]
	s_add_u32 s2, s2, 0x1c00
	s_addc_u32 s3, s3, 0
	global_load_ushort v56, v0, s[2:3]
	s_add_u32 s2, s2, 0x1c00
	s_addc_u32 s3, s3, 0
	global_load_ushort v57, v0, s[2:3]
	s_add_u32 s2, s2, 0x1c00
	s_addc_u32 s3, s3, 0
	global_load_ushort v58, v0, s[2:3]
	s_add_u32 s2, s2, 0x1c00
	s_addc_u32 s3, s3, 0
	global_load_ushort v59, v0, s[2:3]
	s_add_u32 s2, s2, 0x1c00
	s_addc_u32 s3, s3, 0
	global_load_ushort v60, v0, s[2:3]
	s_add_u32 s2, s2, 0x1c00
	s_addc_u32 s3, s3, 0
	global_load_ushort v61, v0, s[2:3]
	s_add_u32 s2, s2, 0x1c00
	s_addc_u32 s3, s3, 0
	global_load_ushort v62, v0, s[2:3]
	s_add_u32 s2, s2, 0x1c00
	s_addc_u32 s3, s3, 0
	global_load_ushort v63, v0, s[2:3]
	s_add_u32 s2, s2, 0x1c00
	s_addc_u32 s3, s3, 0
	s_waitcnt vmcnt(24)
	v_lshl_or_b32 v64, v33, 16, v32
	v_lshl_or_b32 v65, v35, 16, v34
	v_lshl_or_b32 v66, v37, 16, v36
	v_lshl_or_b32 v67, v39, 16, v38
	global_store_dwordx4 v5, v[64:67], s[4:5]
	s_waitcnt vmcnt(17)
	v_lshl_or_b32 v68, v41, 16, v40
	v_lshl_or_b32 v69, v43, 16, v42
	v_lshl_or_b32 v70, v45, 16, v44
	v_lshl_or_b32 v71, v47, 16, v46
	global_store_dwordx4 v5, v[68:71], s[4:5] offset:16
	s_waitcnt vmcnt(10)
	v_lshl_or_b32 v72, v49, 16, v48
	v_lshl_or_b32 v73, v51, 16, v50
	v_lshl_or_b32 v74, v53, 16, v52
	v_lshl_or_b32 v75, v55, 16, v54
	global_store_dwordx4 v5, v[72:75], s[4:5] offset:32
	s_waitcnt vmcnt(3)
	v_lshl_or_b32 v76, v57, 16, v56
	v_lshl_or_b32 v77, v59, 16, v58
	v_lshl_or_b32 v78, v61, 16, v60
	v_lshl_or_b32 v79, v63, 16, v62
	global_store_dwordx4 v5, v[76:79], s[4:5] offset:48
	s_branch .LBB0_282
	s_nop 0
	s_nop 0
	s_nop 0
	s_nop 0
	s_nop 0
	s_nop 0
	s_nop 0
	s_nop 0
	s_nop 0
	s_nop 0
.Lntr_generic:
	s_cmpk_gt_i32 s84, 0x3ff
	s_cbranch_scc1 .LBB0_282
	v_mov_b32_e32 v3, 0
	v_lshlrev_b32_e32 v2, 12, v4
	s_lshl_b32 s2, s76, 9
	s_mov_b32 s1, 0
	v_mov_b32_e32 v1, v3
	s_mov_b32 s3, 0xf000
	s_mov_b32 s4, 0x11000
	s_mov_b32 s5, 0x13000
	s_mov_b32 s6, 0x15000
	s_mov_b32 s7, 0x16000
	s_mov_b32 s10, 0x18000
	s_mov_b32 s12, 0x1a000
	s_mov_b32 s13, 0x1c000
	s_mov_b32 s14, 0x1d000
	s_mov_b32 s15, 0x1f000
	s_mov_b32 s16, 0x21000
	s_mov_b32 s17, 0x23000
	s_mov_b32 s18, 0x24000
	s_mov_b32 s19, 0x26000
	s_mov_b32 s25, 0x28000
	s_mov_b32 s26, 0x2a000
	s_mov_b32 s27, 0x2b000
	s_mov_b32 s28, 0x2d000
	s_mov_b32 s29, 0x2f000
	s_mov_b32 s30, 0x31000
	s_mov_b32 s31, 0x32000
	s_mov_b32 s34, 0x34000
	s_mov_b32 s35, 0x36000
	s_mov_b32 s36, 0x38000
	s_mov_b32 s37, 0x39000
	s_mov_b32 s38, 0x3b000
	s_mov_b32 s39, 0x3d000
	s_mov_b32 s40, 0x3f000
	s_mov_b32 s41, 0x40000
	s_mov_b32 s42, 0x42000
	s_mov_b32 s43, 0x44000
	s_mov_b32 s44, 0x46000
	s_mov_b32 s45, 0x47000
	s_mov_b32 s46, 0x49000
	s_mov_b32 s47, 0x4b000
	s_mov_b32 s48, 0x4d000
	s_mov_b32 s49, 0x4e000
	s_mov_b32 s51, 0x50000
	s_mov_b32 s52, 0x52000
	s_mov_b32 s53, 0x54000
	s_mov_b32 s54, 0x55000
	s_mov_b32 s55, 0x57000
	s_mov_b32 s56, 0x59000
	s_mov_b32 s57, 0x5b000
	s_mov_b32 s58, 0x5c000
	s_mov_b32 s59, 0x5e000
	s_mov_b32 s60, 0x60000
	s_mov_b32 s61, 0x62000
	s_mov_b32 s62, 0x63000
	s_mov_b32 s63, 0x65000
	s_mov_b32 s64, 0x67000
	s_mov_b32 s65, 0x69000
	s_mov_b32 s66, 0x6a000
	s_mov_b32 s67, 0x6c000
	s_mov_b32 s68, s84

.LBB0_496:
	v_readlane_b32 s0, v247, 60
	v_mov_b32_e32 v61, v105
	v_readlane_b32 s1, v247, 61
	s_waitcnt lgkmcnt(0)
	s_barrier
	v_lshl_add_u64 v[0:1], v[60:61], 1, s[0:1]
	global_load_dwordx4 v[210:213], v[0:1], off
	v_add_u32_e32 v4, 0, v167
	v_add_u32_e32 v226, v4, v166
	v_cmp_lt_u32_e32 vcc, 30, v163
	v_add3_u32 v48, 0, v124, v56
	v_or_b32_e32 v17, 1, v125
	s_mov_b32 s85, 0
	v_add_u32_e32 v5, 64, v165
	v_lshl_or_b32 v104, v5, 6, v57
	v_lshl_add_u64 v[0:1], v[104:105], 1, s[0:1]
	global_load_dwordx4 v[214:217], v[0:1], off
	v_mul_lo_u32 v5, v5, s79
	v_add3_u32 v227, 0, v5, v166
	v_readlane_b32 s0, v247, 62
	v_readlane_b32 s1, v247, 63
	v_lshlrev_b32_e32 v5, 7, v165
	v_or_b32_e32 v104, v5, v57
	s_nop 0
	v_lshl_add_u64 v[0:1], v[104:105], 1, s[0:1]
	global_load_dwordx4 v[218:221], v[0:1], off
	v_add_u32_e32 v4, v4, v5
	v_add_u32_e32 v228, v4, v166
	v_or_b32_e32 v6, 8, v164
	v_lshl_or_b32 v104, v6, 3, v5
	v_lshl_add_u64 v[0:1], v[104:105], 1, s[0:1]
	global_load_dwordx4 v[222:225], v[0:1], off
	v_lshl_add_u32 v4, v6, 4, v4
	s_waitcnt vmcnt(3)
	ds_write_b128 v226, v[210:213]
	s_waitcnt vmcnt(2)
	ds_write_b128 v227, v[214:217]
	s_waitcnt vmcnt(1)
	ds_write_b128 v228, v[218:221] offset:18432
	s_waitcnt vmcnt(0)
	ds_write_b128 v4, v[222:225] offset:18432
	v_subrev_u32_e32 v0, 31, v163
	v_ashrrev_i32_e32 v0, 4, v0
	v_add_u32_e32 v0, 1, v0
	s_waitcnt lgkmcnt(0)
	s_barrier
	v_cndmask_b32_e32 v16, 0, v0, vcc
	ds_read_b128 v[0:3], v48
	ds_read_b128 v[18:21], v48 offset:32
	s_waitcnt lgkmcnt(1)
	v_mfma_f32_32x32x16_bf16 v[0:15], v[0:3], v[64:67], 0
	v_cmp_lt_i32_e64 s[0:1], v125, v16
	s_nop 1
	v_writelane_b32 v246, s0, 14
	s_nop 1
	v_writelane_b32 v246, s1, 15
	s_waitcnt lgkmcnt(0)
	v_mfma_f32_32x32x16_bf16 v[0:15], v[18:21], v[68:71], v[0:15]
	ds_read_b128 v[18:21], v48 offset:64
	s_waitcnt lgkmcnt(0)
	v_mfma_f32_32x32x16_bf16 v[0:15], v[18:21], v[72:75], v[0:15]
	ds_read_b128 v[18:21], v48 offset:96
	s_waitcnt lgkmcnt(0)
	v_mfma_f32_32x32x16_bf16 v[0:15], v[18:21], v[76:79], v[0:15]
	s_nop 11
	v_max_f32_e32 v0, v0, v0
	v_max_f32_e32 v0, 0xf149f2ca, v0
	v_cndmask_b32_e64 v0, v121, v0, s[0:1]
	v_cmp_lt_i32_e64 s[0:1], v17, v16
	s_nop 1
	v_writelane_b32 v246, s0, 16
	s_nop 1
	v_writelane_b32 v246, s1, 17
	v_cndmask_b32_e64 v1, v120, v1, s[0:1]
	v_cmp_lt_i32_e64 s[0:1], v155, v16
	v_max_f32_e32 v1, v1, v1
	v_max_f32_e32 v0, v0, v1
	v_writelane_b32 v246, s0, 18
	s_nop 1
	v_writelane_b32 v246, s1, 19
	v_cndmask_b32_e64 v1, v120, v2, s[0:1]
	v_cmp_lt_i32_e64 s[0:1], v156, v16
	s_nop 1
	v_writelane_b32 v246, s0, 20
	s_nop 1
	v_cndmask_b32_e64 v2, v120, v3, s[0:1]
	v_max3_f32 v0, v0, v1, v2
	v_add_u32_e32 v1, 8, v125
	v_writelane_b32 v246, s1, 21
	v_cmp_lt_i32_e64 s[0:1], v1, v16
	v_add_u32_e32 v2, 9, v125
	s_nop 0
	v_writelane_b32 v246, s0, 22
	s_nop 1
	v_writelane_b32 v246, s1, 23
	v_cndmask_b32_e64 v1, v120, v4, s[0:1]
	v_cmp_lt_i32_e64 s[0:1], v2, v16
	s_nop 1
	v_writelane_b32 v246, s0, 24
	s_nop 1
	v_cndmask_b32_e64 v2, v120, v5, s[0:1]
	v_max3_f32 v0, v0, v1, v2
	v_add_u32_e32 v1, 10, v125
	v_writelane_b32 v246, s1, 25
	v_cmp_lt_i32_e64 s[0:1], v1, v16
	v_add_u32_e32 v2, 11, v125
	s_nop 0
	v_writelane_b32 v246, s0, 26
	s_nop 1
	v_writelane_b32 v246, s1, 27
	v_cndmask_b32_e64 v1, v120, v6, s[0:1]
	v_cmp_lt_i32_e64 s[0:1], v2, v16
	s_nop 1
	v_writelane_b32 v246, s0, 28
	s_nop 1
	v_cndmask_b32_e64 v2, v120, v7, s[0:1]
	v_max3_f32 v0, v0, v1, v2
	v_or_b32_e32 v1, 16, v125
	v_writelane_b32 v246, s1, 29
	v_cmp_lt_i32_e64 s[0:1], v1, v16
	v_add_u32_e32 v2, 17, v125
	s_nop 0
	v_writelane_b32 v246, s0, 30
	s_nop 1
	v_writelane_b32 v246, s1, 31
	v_cndmask_b32_e64 v1, v120, v8, s[0:1]
	v_cmp_lt_i32_e64 s[0:1], v2, v16
	s_nop 1
	v_writelane_b32 v246, s0, 32
	s_nop 1
	v_cndmask_b32_e64 v2, v120, v9, s[0:1]
	v_max3_f32 v0, v0, v1, v2
	v_add_u32_e32 v1, 18, v125
	v_writelane_b32 v246, s1, 33
	v_cmp_lt_i32_e64 s[0:1], v1, v16
	v_add_u32_e32 v2, 19, v125
	s_nop 0
	v_writelane_b32 v246, s0, 34
	s_nop 1
	v_writelane_b32 v246, s1, 35
	v_cndmask_b32_e64 v1, v120, v10, s[0:1]
	v_cmp_lt_i32_e64 s[0:1], v2, v16
	s_nop 1
	v_writelane_b32 v246, s0, 36
	s_nop 1
	v_cndmask_b32_e64 v2, v120, v11, s[0:1]
	v_max3_f32 v0, v0, v1, v2
	v_add_u32_e32 v1, 24, v125
	v_writelane_b32 v246, s1, 37
	v_cmp_lt_i32_e64 s[0:1], v1, v16
	v_add_u32_e32 v2, 25, v125
	s_nop 0
	v_writelane_b32 v246, s0, 38
	s_nop 1
	v_writelane_b32 v246, s1, 39
	v_cndmask_b32_e64 v1, v120, v12, s[0:1]
	v_cmp_lt_i32_e64 s[0:1], v2, v16
	s_nop 1
	v_writelane_b32 v246, s0, 40
	s_nop 1
	v_cndmask_b32_e64 v2, v120, v13, s[0:1]
	v_max3_f32 v0, v0, v1, v2
	v_add_u32_e32 v1, 26, v125
	v_add_u32_e32 v2, 27, v125
	v_cmp_lt_i32_e64 s[58:59], v1, v16
	v_cmp_lt_i32_e64 s[8:9], v2, v16
	v_writelane_b32 v246, s1, 41
	v_cndmask_b32_e64 v1, v120, v14, s[58:59]
	v_cndmask_b32_e64 v2, v120, v15, s[8:9]
	v_max3_f32 v17, v0, v1, v2
	v_or_b32_e32 v0, 32, v161
	v_mul_u32_u24_e32 v0, 0x90, v0
	v_add3_u32 v52, 0, v0, v56
	ds_read_b128 v[0:3], v52
	ds_read_b128 v[18:21], v52 offset:32
	v_cmp_lt_i32_e64 s[0:1], v157, v16
	v_cmp_lt_i32_e64 s[60:61], v158, v16
	v_cmp_lt_i32_e64 s[62:63], v159, v16
	s_waitcnt lgkmcnt(1)
	v_mfma_f32_32x32x16_bf16 v[0:15], v[0:3], v[64:67], 0
	v_writelane_b32 v246, s0, 42
	s_nop 1
	v_writelane_b32 v246, s1, 43
	s_waitcnt lgkmcnt(0)
	v_mfma_f32_32x32x16_bf16 v[0:15], v[18:21], v[68:71], v[0:15]
	ds_read_b128 v[18:21], v52 offset:64
	s_waitcnt lgkmcnt(0)
	v_mfma_f32_32x32x16_bf16 v[0:15], v[18:21], v[72:75], v[0:15]
	ds_read_b128 v[18:21], v52 offset:96
	s_waitcnt lgkmcnt(0)
	v_mfma_f32_32x32x16_bf16 v[0:15], v[18:21], v[76:79], v[0:15]
	v_or_b32_e32 v18, 1, v157
	v_cmp_lt_i32_e64 s[56:57], v18, v16
	s_nop 9
	v_cndmask_b32_e64 v0, v120, v0, s[0:1]
	v_cndmask_b32_e64 v1, v120, v1, s[56:57]
	v_max3_f32 v0, v17, v0, v1
	v_cndmask_b32_e64 v1, v120, v2, s[60:61]
	v_cndmask_b32_e64 v2, v120, v3, s[62:63]
	v_max3_f32 v0, v0, v1, v2
	v_add_u32_e32 v1, 40, v125
	v_add_u32_e32 v2, 41, v125
	v_cmp_lt_i32_e64 s[50:51], v1, v16
	v_cmp_lt_i32_e64 s[80:81], v2, v16
	s_nop 0
	v_cndmask_b32_e64 v1, v120, v4, s[50:51]
	v_cndmask_b32_e64 v2, v120, v5, s[80:81]
	v_max3_f32 v0, v0, v1, v2
	v_add_u32_e32 v1, 42, v125
	v_add_u32_e32 v2, 43, v125
	v_cmp_lt_i32_e64 s[88:89], v1, v16
	v_cmp_lt_i32_e64 s[94:95], v2, v16
	s_nop 0
	v_cndmask_b32_e64 v1, v120, v6, s[88:89]
	v_cndmask_b32_e64 v2, v120, v7, s[94:95]
	v_max3_f32 v0, v0, v1, v2
	v_or_b32_e32 v1, 48, v125
	v_add_u32_e32 v2, 49, v125
	v_cmp_lt_i32_e64 s[44:45], v1, v16
	v_cmp_lt_i32_e64 s[40:41], v2, v16
	s_nop 0
	v_cndmask_b32_e64 v1, v120, v8, s[44:45]
	v_cndmask_b32_e64 v2, v120, v9, s[40:41]
	v_max3_f32 v0, v0, v1, v2
	v_add_u32_e32 v1, 50, v125
	v_add_u32_e32 v2, 51, v125
	v_cmp_lt_i32_e64 s[36:37], v1, v16
	v_cmp_lt_i32_e64 s[34:35], v2, v16
	s_nop 0
	v_cndmask_b32_e64 v1, v120, v10, s[36:37]
	v_cndmask_b32_e64 v2, v120, v11, s[34:35]
	v_max3_f32 v0, v0, v1, v2
	v_add_u32_e32 v1, 56, v125
	v_add_u32_e32 v2, 57, v125
	v_cmp_lt_i32_e32 vcc, v1, v16
	v_cmp_lt_i32_e64 s[2:3], v2, v16
	s_nop 0
	v_cndmask_b32_e32 v1, v120, v12, vcc
	v_cndmask_b32_e64 v2, v120, v13, s[2:3]
	v_max3_f32 v0, v0, v1, v2
	v_add_u32_e32 v1, 58, v125
	v_add_u32_e32 v2, 59, v125
	v_cmp_lt_i32_e64 s[0:1], v1, v16
	v_cmp_lt_i32_e64 s[4:5], v2, v16
	s_nop 0
	v_cndmask_b32_e64 v1, v120, v14, s[0:1]
	v_cndmask_b32_e64 v2, v120, v15, s[4:5]
	v_max3_f32 v17, v0, v1, v2
	ds_read_b128 v[0:3], v48 offset:9216
	ds_read_b128 v[18:21], v48 offset:9248
	s_waitcnt lgkmcnt(1)
	v_mfma_f32_32x32x16_bf16 v[0:15], v[0:3], v[64:67], 0
	s_waitcnt lgkmcnt(0)
	v_mfma_f32_32x32x16_bf16 v[0:15], v[18:21], v[68:71], v[0:15]
	ds_read_b128 v[18:21], v48 offset:9280
	s_waitcnt lgkmcnt(0)
	v_mfma_f32_32x32x16_bf16 v[0:15], v[18:21], v[72:75], v[0:15]
	ds_read_b128 v[18:21], v48 offset:9312
	s_waitcnt lgkmcnt(0)
	v_mfma_f32_32x32x16_bf16 v[0:15], v[18:21], v[76:79], v[0:15]
	v_or_b32_e32 v18, 64, v125
	v_cmp_lt_i32_e64 s[6:7], v18, v16
	v_add_u32_e32 v18, 0x41, v125
	v_cmp_lt_i32_e64 s[54:55], v18, v16
	v_writelane_b32 v246, s6, 44
	s_nop 6
	v_cndmask_b32_e64 v1, v120, v1, s[54:55]
	v_cndmask_b32_e64 v0, v120, v0, s[6:7]
	v_max3_f32 v0, v17, v0, v1
	v_add_u32_e32 v1, 0x42, v125
	v_cmp_lt_i32_e64 s[66:67], v1, v16
	v_writelane_b32 v246, s7, 45
	s_nop 0
	v_cndmask_b32_e64 v1, v120, v2, s[66:67]
	v_add_u32_e32 v2, 0x43, v125
	v_cmp_lt_i32_e64 s[70:71], v2, v16
	s_nop 1
	v_cndmask_b32_e64 v2, v120, v3, s[70:71]
	v_max3_f32 v0, v0, v1, v2
	v_add_u32_e32 v1, 0x48, v125
	v_add_u32_e32 v2, 0x49, v125
	v_cmp_lt_i32_e64 s[74:75], v1, v16
	v_cmp_lt_i32_e64 s[82:83], v2, v16
	s_nop 0
	v_cndmask_b32_e64 v1, v120, v4, s[74:75]
	v_cndmask_b32_e64 v2, v120, v5, s[82:83]
	v_max3_f32 v0, v0, v1, v2
	v_add_u32_e32 v1, 0x4a, v125
	v_add_u32_e32 v2, 0x4b, v125
	v_cmp_lt_i32_e64 s[86:87], v1, v16
	v_cmp_lt_i32_e64 s[92:93], v2, v16
	s_nop 0
	v_cndmask_b32_e64 v1, v120, v6, s[86:87]
	v_cndmask_b32_e64 v2, v120, v7, s[92:93]
	v_max3_f32 v0, v0, v1, v2
	v_or_b32_e32 v1, 0x50, v125
	v_add_u32_e32 v2, 0x51, v125
	v_cmp_lt_i32_e64 s[46:47], v1, v16
	v_cmp_lt_i32_e64 s[42:43], v2, v16
	s_nop 0
	v_cndmask_b32_e64 v1, v120, v8, s[46:47]
	v_cndmask_b32_e64 v2, v120, v9, s[42:43]
	v_max3_f32 v0, v0, v1, v2
	v_add_u32_e32 v1, 0x52, v125
	v_add_u32_e32 v2, 0x53, v125
	v_cmp_lt_i32_e64 s[38:39], v1, v16
	v_cmp_lt_i32_e64 s[6:7], v2, v16
	s_nop 0
	v_cndmask_b32_e64 v1, v120, v10, s[38:39]
	v_cndmask_b32_e64 v2, v120, v11, s[6:7]
	v_max3_f32 v0, v0, v1, v2
	v_add_u32_e32 v1, 0x58, v125
	v_add_u32_e32 v2, 0x59, v125
	v_cmp_lt_i32_e64 s[14:15], v1, v16
	v_cmp_lt_i32_e64 s[20:21], v2, v16
	s_nop 0
	v_cndmask_b32_e64 v1, v120, v12, s[14:15]
	v_cndmask_b32_e64 v2, v120, v13, s[20:21]
	v_max3_f32 v0, v0, v1, v2
	v_add_u32_e32 v1, 0x5a, v125
	v_add_u32_e32 v2, 0x5b, v125
	v_cmp_lt_i32_e64 s[16:17], v1, v16
	v_cmp_lt_i32_e64 s[18:19], v2, v16
	s_nop 0
	v_cndmask_b32_e64 v1, v120, v14, s[16:17]
	v_cndmask_b32_e64 v2, v120, v15, s[18:19]
	v_max3_f32 v17, v0, v1, v2
	ds_read_b128 v[0:3], v48 offset:13824
	ds_read_b128 v[18:21], v48 offset:13856
	s_waitcnt lgkmcnt(1)
	v_mfma_f32_32x32x16_bf16 v[0:15], v[0:3], v[64:67], 0
	s_waitcnt lgkmcnt(0)
	v_mfma_f32_32x32x16_bf16 v[0:15], v[18:21], v[68:71], v[0:15]
	ds_read_b128 v[18:21], v48 offset:13888
	s_waitcnt lgkmcnt(0)
	v_mfma_f32_32x32x16_bf16 v[0:15], v[18:21], v[72:75], v[0:15]
	ds_read_b128 v[18:21], v48 offset:13920
	s_waitcnt lgkmcnt(0)
	v_mfma_f32_32x32x16_bf16 v[0:15], v[18:21], v[76:79], v[0:15]
	v_or_b32_e32 v18, 0x60, v125
	v_cmp_lt_i32_e64 s[22:23], v18, v16
	v_add_u32_e32 v18, 0x61, v125
	s_nop 0
	v_writelane_b32 v246, s22, 46
	s_nop 1
	v_writelane_b32 v246, s23, 47
	s_nop 3
	v_cndmask_b32_e64 v0, v120, v0, s[22:23]
	v_cmp_lt_i32_e64 s[22:23], v18, v16
	s_nop 1
	v_writelane_b32 v246, s22, 48
	s_nop 1
	v_cndmask_b32_e64 v1, v120, v1, s[22:23]
	v_max3_f32 v0, v17, v0, v1
	v_add_u32_e32 v1, 0x62, v125
	v_writelane_b32 v246, s23, 49
	v_cmp_lt_i32_e64 s[22:23], v1, v16
	s_nop 1
	v_writelane_b32 v246, s22, 50
	s_nop 1
	v_cndmask_b32_e64 v1, v120, v2, s[22:23]
	v_add_u32_e32 v2, 0x63, v125
	v_writelane_b32 v246, s23, 51
	v_cmp_lt_i32_e64 s[22:23], v2, v16
	s_nop 1
	v_writelane_b32 v246, s22, 52
	s_nop 1
	v_cndmask_b32_e64 v2, v120, v3, s[22:23]
	v_max3_f32 v0, v0, v1, v2
	v_add_u32_e32 v1, 0x68, v125
	v_add_u32_e32 v2, 0x69, v125
	v_cmp_lt_i32_e64 s[64:65], v1, v16
	v_cmp_lt_i32_e64 s[68:69], v2, v16
	v_writelane_b32 v246, s23, 53
	v_cndmask_b32_e64 v1, v120, v4, s[64:65]
	v_cndmask_b32_e64 v2, v120, v5, s[68:69]
	v_max3_f32 v0, v0, v1, v2
	v_add_u32_e32 v1, 0x6a, v125
	v_add_u32_e32 v2, 0x6b, v125
	v_cmp_lt_i32_e64 s[72:73], v1, v16
	v_cmp_lt_i32_e64 s[78:79], v2, v16
	s_nop 0
	v_cndmask_b32_e64 v1, v120, v6, s[72:73]
	v_cndmask_b32_e64 v2, v120, v7, s[78:79]
	v_max3_f32 v0, v0, v1, v2
	v_or_b32_e32 v1, 0x70, v125
	v_add_u32_e32 v2, 0x71, v125
	v_cmp_lt_i32_e64 s[48:49], v1, v16
	v_cmp_lt_i32_e64 s[90:91], v2, v16
	s_nop 0
	v_cndmask_b32_e64 v1, v120, v8, s[48:49]
	v_cndmask_b32_e64 v2, v120, v9, s[90:91]
	v_max3_f32 v0, v0, v1, v2
	v_add_u32_e32 v1, 0x72, v125
	v_add_u32_e32 v2, 0x73, v125
	v_cmp_lt_i32_e64 s[96:97], v1, v16
	v_cmp_lt_i32_e64 s[22:23], v2, v16
	s_nop 0
	v_cndmask_b32_e64 v1, v120, v10, s[96:97]
	v_cndmask_b32_e64 v2, v120, v11, s[22:23]
	v_max3_f32 v0, v0, v1, v2
	v_add_u32_e32 v1, 0x78, v125
	v_add_u32_e32 v2, 0x79, v125
	v_cmp_lt_i32_e64 s[24:25], v1, v16
	v_cmp_lt_i32_e64 s[28:29], v2, v16
	s_nop 0
	v_cndmask_b32_e64 v1, v120, v12, s[24:25]
	v_cndmask_b32_e64 v2, v120, v13, s[28:29]
	v_max3_f32 v0, v0, v1, v2
	v_add_u32_e32 v1, 0x7a, v125
	v_add_u32_e32 v2, 0x7b, v125
	v_cmp_lt_i32_e64 s[26:27], v1, v16
	v_cmp_lt_i32_e64 s[30:31], v2, v16
	s_nop 0
	v_cndmask_b32_e64 v1, v120, v14, s[26:27]
	v_cndmask_b32_e64 v2, v120, v15, s[30:31]
	v_max3_f32 v24, v0, v1, v2
	ds_read_b128 v[0:3], v48
	ds_read_b128 v[16:19], v48 offset:32
	v_readlane_b32 s52, v246, 14
	v_readlane_b32 s53, v246, 15
	s_waitcnt lgkmcnt(1)
	v_mfma_f32_32x32x16_bf16 v[0:15], v[0:3], v[64:67], 0
	s_waitcnt lgkmcnt(0)
	v_mfma_f32_32x32x16_bf16 v[0:15], v[16:19], v[68:71], v[0:15]
	ds_read_b128 v[16:19], v48 offset:64
	ds_read_b128 v[20:23], v48 offset:96
	s_waitcnt lgkmcnt(1)
	v_mfma_f32_32x32x16_bf16 v[0:15], v[16:19], v[72:75], v[0:15]
	ds_bpermute_b32 v16, v113, v24
	s_waitcnt lgkmcnt(0)
	v_max_f32_e32 v16, v16, v16
	v_max_f32_e32 v54, v24, v16
	v_mfma_f32_32x32x16_bf16 v[0:15], v[20:23], v[76:79], v[0:15]
	s_nop 11
	v_sub_f32_e32 v0, v0, v54
	v_exp_f32_e32 v0, v0
	v_sub_f32_e32 v1, v1, v54
	v_exp_f32_e32 v1, v1
	v_sub_f32_e32 v2, v2, v54
	v_exp_f32_e32 v2, v2
	v_cndmask_b32_e64 v24, 0, v0, s[52:53]
	v_readlane_b32 s52, v246, 16
	v_sub_f32_e32 v3, v3, v54
	v_readlane_b32 s53, v246, 17
	v_exp_f32_e32 v3, v3
	v_sub_f32_e32 v4, v4, v54
	v_cndmask_b32_e64 v25, 0, v1, s[52:53]
	v_readlane_b32 s52, v246, 18
	v_readlane_b32 s53, v246, 19
	v_exp_f32_e32 v4, v4
	v_sub_f32_e32 v5, v5, v54
	v_cndmask_b32_e64 v26, 0, v2, s[52:53]
	v_readlane_b32 s52, v246, 20
	v_readlane_b32 s53, v246, 21
	v_exp_f32_e32 v5, v5
	v_sub_f32_e32 v6, v6, v54
	v_cndmask_b32_e64 v27, 0, v3, s[52:53]
	v_readlane_b32 s52, v246, 22
	v_readlane_b32 s53, v246, 23
	v_exp_f32_e32 v6, v6
	v_sub_f32_e32 v7, v7, v54
	v_cndmask_b32_e64 v28, 0, v4, s[52:53]
	v_readlane_b32 s52, v246, 24
	v_readlane_b32 s53, v246, 25
	v_exp_f32_e32 v7, v7
	v_sub_f32_e32 v8, v8, v54
	v_cndmask_b32_e64 v29, 0, v5, s[52:53]
	v_readlane_b32 s52, v246, 26
	v_readlane_b32 s53, v246, 27
	v_exp_f32_e32 v8, v8
	v_sub_f32_e32 v9, v9, v54
	v_cndmask_b32_e64 v36, 0, v6, s[52:53]
	v_readlane_b32 s52, v246, 28
	v_readlane_b32 s53, v246, 29
	v_exp_f32_e32 v9, v9
	v_sub_f32_e32 v10, v10, v54
	v_cndmask_b32_e64 v37, 0, v7, s[52:53]
	v_readlane_b32 s52, v246, 30
	v_readlane_b32 s53, v246, 31
	v_exp_f32_e32 v10, v10
	v_sub_f32_e32 v11, v11, v54
	v_cndmask_b32_e64 v44, 0, v8, s[52:53]
	v_readlane_b32 s52, v246, 32
	v_readlane_b32 s53, v246, 33
	v_exp_f32_e32 v11, v11
	v_sub_f32_e32 v12, v12, v54
	v_cndmask_b32_e64 v45, 0, v9, s[52:53]
	v_readlane_b32 s52, v246, 34
	v_readlane_b32 s53, v246, 35
	v_exp_f32_e32 v12, v12
	v_sub_f32_e32 v0, v13, v54
	v_cndmask_b32_e64 v46, 0, v10, s[52:53]
	v_readlane_b32 s52, v246, 36
	v_readlane_b32 s53, v246, 37
	v_exp_f32_e32 v0, v0
	v_sub_f32_e32 v1, v14, v54
	v_cndmask_b32_e64 v47, 0, v11, s[52:53]
	v_readlane_b32 s52, v246, 38
	v_readlane_b32 s53, v246, 39
	v_exp_f32_e32 v1, v1
	v_sub_f32_e32 v2, v15, v54
	v_cndmask_b32_e64 v63, 0, v12, s[52:53]
	v_readlane_b32 s52, v246, 40
	v_readlane_b32 s53, v246, 41
	v_exp_f32_e32 v2, v2
	v_cndmask_b32_e64 v81, 0, v1, s[58:59]
	v_cndmask_b32_e64 v80, 0, v0, s[52:53]
	ds_bpermute_b32 v0, v113, v27
	v_add_f32_e32 v1, v24, v25
	ds_bpermute_b32 v3, v113, v37
	v_cndmask_b32_e64 v82, 0, v2, s[8:9]
	v_add_f32_e32 v1, v26, v1
	s_waitcnt lgkmcnt(1)
	v_mul_f32_e32 v2, 0.5, v0
	v_cmp_gt_u32_e64 s[8:9], 32, v59
	v_fmac_f32_e32 v1, 0.5, v27
	ds_bpermute_b32 v4, v113, v47
	v_cndmask_b32_e64 v2, v2, 0, s[8:9]
	v_add_f32_e32 v53, v2, v1
	v_add_f32_e32 v1, v28, v29
	v_add_f32_e32 v49, v36, v1
	v_fmac_f32_e32 v49, 0.5, v37
	s_waitcnt lgkmcnt(1)
	v_cndmask_b32_e64 v0, v3, v0, s[8:9]
	v_fmac_f32_e32 v49, 0.5, v0
	v_add_f32_e32 v0, v44, v45
	v_add_f32_e32 v50, v46, v0
	v_fmac_f32_e32 v50, 0.5, v47
	s_waitcnt lgkmcnt(0)
	v_cndmask_b32_e64 v0, v4, v3, s[8:9]
	v_fmac_f32_e32 v50, 0.5, v0
	v_add_f32_e32 v0, v63, v80
	v_add_f32_e32 v51, v81, v0
	v_mul_u32_u24_e32 v0, 0x110, v161
	v_add3_u32 v5, 0, v123, v0
	v_add_u32_e32 v62, 0x4800, v5
	ds_read2_b64 v[0:3], v62 offset1:2
	ds_bpermute_b32 v84, v113, v82
	v_add_u32_e32 v55, 0x6800, v5
	v_fmac_f32_e32 v51, 0.5, v82
	v_cvt_pk_bf16_f32 v16, v24, v25
	v_cvt_pk_bf16_f32 v17, v26, v27
	s_waitcnt lgkmcnt(0)
	v_cndmask_b32_e64 v4, v84, v4, s[8:9]
	v_cvt_pk_bf16_f32 v18, v28, v29
	v_cvt_pk_bf16_f32 v19, v36, v37
	ds_read2_b64 v[20:23], v55 offset0:64 offset1:66
	ds_read2_b64 v[32:35], v62 offset0:4 offset1:6
	v_fmac_f32_e32 v51, 0.5, v4
	v_mfma_f32_32x32x16_bf16 v[0:15], v[0:3], v[16:19], 0
	v_add_f32_e32 v24, 0, v24
	v_add_f32_e32 v24, v25, v24
	v_add_f32_e32 v24, v26, v24
	v_add_f32_e32 v24, v27, v24
	v_add_f32_e32 v24, v28, v24
	v_add_f32_e32 v38, v29, v24
	v_add_f32_e32 v36, v36, v38
	v_add_f32_e32 v83, v37, v36
	v_cvt_pk_bf16_f32 v36, v44, v45
	v_cvt_pk_bf16_f32 v37, v46, v47
	v_cvt_pk_bf16_f32 v38, v63, v80
	v_cvt_pk_bf16_f32 v39, v81, v82
	ds_read2_b64 v[40:43], v55 offset0:68 offset1:70
	s_waitcnt lgkmcnt(2)
	v_mfma_f32_32x32x16_bf16 v[16:31], v[20:23], v[16:19], 0
	s_waitcnt lgkmcnt(1)
	v_mfma_f32_32x32x16_bf16 v[0:15], v[32:35], v[36:39], v[0:15]
	v_add_f32_e32 v32, v44, v83
	v_add_f32_e32 v32, v45, v32
	v_add_f32_e32 v32, v46, v32
	v_add_f32_e32 v32, v47, v32
	v_add_f32_e32 v32, v63, v32
	v_add_f32_e32 v32, v80, v32
	v_add_f32_e32 v32, v81, v32
	s_waitcnt lgkmcnt(0)
	v_mfma_f32_32x32x16_bf16 v[16:31], v[40:43], v[36:39], v[16:31]
	v_add_f32_e32 v85, v82, v32
	ds_read_b128 v[32:35], v52
	ds_read_b128 v[80:83], v52 offset:32
	v_readlane_b32 s52, v246, 42
	v_readlane_b32 s53, v246, 43
	s_waitcnt lgkmcnt(1)
	v_mfma_f32_32x32x16_bf16 v[32:47], v[32:35], v[64:67], 0
	s_waitcnt lgkmcnt(0)
	v_mfma_f32_32x32x16_bf16 v[32:47], v[80:83], v[68:71], v[32:47]
	ds_read_b128 v[80:83], v52 offset:64
	s_waitcnt lgkmcnt(0)
	v_mfma_f32_32x32x16_bf16 v[32:47], v[80:83], v[72:75], v[32:47]
	ds_read_b128 v[80:83], v52 offset:96
	s_waitcnt lgkmcnt(0)
	v_mfma_f32_32x32x16_bf16 v[32:47], v[80:83], v[76:79], v[32:47]
	s_nop 11
	v_sub_f32_e32 v32, v32, v54
	v_exp_f32_e32 v32, v32
	v_sub_f32_e32 v33, v33, v54
	v_sub_f32_e32 v34, v34, v54
	v_sub_f32_e32 v35, v35, v54
	v_exp_f32_e32 v33, v33
	v_exp_f32_e32 v34, v34
	v_exp_f32_e32 v35, v35
	v_cndmask_b32_e64 v82, 0, v32, s[52:53]
	v_sub_f32_e32 v32, v45, v54
	v_exp_f32_e32 v32, v32
	v_sub_f32_e32 v39, v39, v54
	v_exp_f32_e32 v39, v39
	v_cndmask_b32_e64 v83, 0, v33, s[56:57]
	v_cndmask_b32_e64 v86, 0, v34, s[60:61]
	v_sub_f32_e32 v33, v46, v54
	v_sub_f32_e32 v34, v47, v54
	v_cndmask_b32_e64 v87, 0, v35, s[62:63]
	v_exp_f32_e32 v33, v33
	v_exp_f32_e32 v34, v34
	v_sub_f32_e32 v36, v36, v54
	v_sub_f32_e32 v37, v37, v54
	v_sub_f32_e32 v43, v43, v54
	v_cndmask_b32_e64 v45, 0, v32, s[2:3]
	ds_bpermute_b32 v32, v113, v87
	v_sub_f32_e32 v38, v38, v54
	v_exp_f32_e32 v36, v36
	v_exp_f32_e32 v37, v37
	v_exp_f32_e32 v43, v43
	v_exp_f32_e32 v38, v38
	v_cndmask_b32_e64 v91, 0, v39, s[94:95]
	v_sub_f32_e32 v40, v40, v54
	v_sub_f32_e32 v41, v41, v54
	v_cndmask_b32_e64 v46, 0, v33, s[0:1]
	v_cndmask_b32_e64 v47, 0, v34, s[4:5]
	v_add_f32_e32 v33, v82, v83
	ds_bpermute_b32 v34, v113, v91
	v_sub_f32_e32 v42, v42, v54
	v_exp_f32_e32 v40, v40
	v_exp_f32_e32 v41, v41
	v_add_f32_e32 v52, v86, v33
	v_exp_f32_e32 v42, v42
	v_cndmask_b32_e64 v88, 0, v36, s[50:51]
	v_cndmask_b32_e64 v89, 0, v37, s[80:81]
	v_cndmask_b32_e64 v95, 0, v43, s[34:35]
	v_fmac_f32_e32 v52, 0.5, v87
	s_waitcnt lgkmcnt(1)
	v_cndmask_b32_e64 v33, v32, v84, s[8:9]
	v_sub_f32_e32 v44, v44, v54
	v_cndmask_b32_e64 v90, 0, v38, s[88:89]
	v_fmac_f32_e32 v52, 0.5, v33
	v_add_f32_e32 v33, v88, v89
	ds_bpermute_b32 v36, v113, v95
	v_exp_f32_e32 v44, v44
	v_add_f32_e32 v63, v90, v33
	v_cndmask_b32_e64 v92, 0, v40, s[44:45]
	v_cndmask_b32_e64 v93, 0, v41, s[40:41]
	v_fmac_f32_e32 v63, 0.5, v91
	s_waitcnt lgkmcnt(1)
	v_cndmask_b32_e64 v32, v34, v32, s[8:9]
	v_cndmask_b32_e64 v94, 0, v42, s[36:37]
	v_fmac_f32_e32 v63, 0.5, v32
	v_add_f32_e32 v32, v92, v93
	v_add_f32_e32 v80, v94, v32
	v_cndmask_b32_e32 v44, 0, v44, vcc
	v_fmac_f32_e32 v80, 0.5, v95
	s_waitcnt lgkmcnt(0)
	v_cndmask_b32_e64 v32, v36, v34, s[8:9]
	v_fmac_f32_e32 v80, 0.5, v32
	v_add_f32_e32 v32, v44, v45
	v_add_f32_e32 v81, v46, v32
	ds_read2_b64 v[32:35], v62 offset0:8 offset1:10
	ds_bpermute_b32 v96, v113, v47
	v_fmac_f32_e32 v81, 0.5, v47
	v_cvt_pk_bf16_f32 v37, v86, v87
	v_cvt_pk_bf16_f32 v38, v88, v89
	v_cvt_pk_bf16_f32 v39, v90, v91
	s_waitcnt lgkmcnt(0)
	v_cndmask_b32_e64 v36, v96, v36, s[8:9]
	v_fmac_f32_e32 v81, 0.5, v36
	v_cvt_pk_bf16_f32 v36, v82, v83
	ds_read2_b64 v[40:43], v55 offset0:72 offset1:74
	s_nop 0
	v_mfma_f32_32x32x16_bf16 v[0:15], v[32:35], v[36:39], v[0:15]
	v_add_f32_e32 v32, v82, v85
	v_add_f32_e32 v32, v83, v32
	v_add_f32_e32 v32, v86, v32
	v_add_f32_e32 v32, v87, v32
	v_add_f32_e32 v32, v88, v32
	v_add_f32_e32 v82, v89, v32
	ds_read2_b64 v[32:35], v62 offset0:12 offset1:14
	s_waitcnt lgkmcnt(1)
	v_mfma_f32_32x32x16_bf16 v[16:31], v[40:43], v[36:39], v[16:31]
	v_add_f32_e32 v36, v90, v82
	v_add_f32_e32 v82, v91, v36
	v_cvt_pk_bf16_f32 v36, v92, v93
	v_cvt_pk_bf16_f32 v37, v94, v95
	v_cvt_pk_bf16_f32 v38, v44, v45
	v_cvt_pk_bf16_f32 v39, v46, v47
	ds_read2_b64 v[40:43], v55 offset0:76 offset1:78
	s_waitcnt lgkmcnt(1)
	v_mfma_f32_32x32x16_bf16 v[0:15], v[32:35], v[36:39], v[0:15]
	v_add_f32_e32 v32, v92, v82
	v_add_f32_e32 v32, v93, v32
	v_add_f32_e32 v32, v94, v32
	v_add_f32_e32 v32, v95, v32
	v_add_f32_e32 v32, v44, v32
	v_add_f32_e32 v32, v45, v32
	v_add_f32_e32 v32, v46, v32
	s_waitcnt lgkmcnt(0)
	v_mfma_f32_32x32x16_bf16 v[16:31], v[40:43], v[36:39], v[16:31]
	v_add_f32_e32 v86, v47, v32
	ds_read_b128 v[32:35], v48 offset:9216
	ds_read_b128 v[82:85], v48 offset:9248
	v_readlane_b32 s0, v246, 44
	v_readlane_b32 s1, v246, 45
	s_waitcnt lgkmcnt(1)
	v_mfma_f32_32x32x16_bf16 v[32:47], v[32:35], v[64:67], 0
	s_waitcnt lgkmcnt(0)
	v_mfma_f32_32x32x16_bf16 v[32:47], v[82:85], v[68:71], v[32:47]
	ds_read_b128 v[82:85], v48 offset:9280
	s_waitcnt lgkmcnt(0)
	v_mfma_f32_32x32x16_bf16 v[32:47], v[82:85], v[72:75], v[32:47]
	ds_read_b128 v[82:85], v48 offset:9312
	s_waitcnt lgkmcnt(0)
	v_mfma_f32_32x32x16_bf16 v[32:47], v[82:85], v[76:79], v[32:47]
	s_nop 11
	v_sub_f32_e32 v32, v32, v54
	v_exp_f32_e32 v32, v32
	v_sub_f32_e32 v33, v33, v54
	v_sub_f32_e32 v34, v34, v54
	v_sub_f32_e32 v35, v35, v54
	v_exp_f32_e32 v33, v33
	v_exp_f32_e32 v34, v34
	v_exp_f32_e32 v35, v35
	v_cndmask_b32_e64 v87, 0, v32, s[0:1]
	v_sub_f32_e32 v32, v45, v54
	v_exp_f32_e32 v32, v32
	v_sub_f32_e32 v39, v39, v54
	v_exp_f32_e32 v39, v39
	v_cndmask_b32_e64 v88, 0, v33, s[54:55]
	v_cndmask_b32_e64 v89, 0, v34, s[66:67]
	v_sub_f32_e32 v33, v46, v54
	v_sub_f32_e32 v34, v47, v54
	v_cndmask_b32_e64 v90, 0, v35, s[70:71]
	v_exp_f32_e32 v33, v33
	v_exp_f32_e32 v34, v34
	v_sub_f32_e32 v36, v36, v54
	v_sub_f32_e32 v37, v37, v54
	v_sub_f32_e32 v43, v43, v54
	v_cndmask_b32_e64 v45, 0, v32, s[20:21]
	ds_bpermute_b32 v32, v113, v90
	v_sub_f32_e32 v38, v38, v54
	v_exp_f32_e32 v36, v36
	v_exp_f32_e32 v37, v37
	v_exp_f32_e32 v43, v43
	v_exp_f32_e32 v38, v38
	v_cndmask_b32_e64 v94, 0, v39, s[92:93]
	v_sub_f32_e32 v40, v40, v54
	v_sub_f32_e32 v41, v41, v54
	v_cndmask_b32_e64 v46, 0, v33, s[16:17]
	v_cndmask_b32_e64 v47, 0, v34, s[18:19]
	v_add_f32_e32 v33, v87, v88
	ds_bpermute_b32 v34, v113, v94
	v_sub_f32_e32 v42, v42, v54
	v_exp_f32_e32 v40, v40
	v_exp_f32_e32 v41, v41
	v_add_f32_e32 v82, v89, v33
	v_exp_f32_e32 v42, v42
	v_cndmask_b32_e64 v91, 0, v36, s[74:75]
	v_cndmask_b32_e64 v92, 0, v37, s[82:83]
	v_cndmask_b32_e64 v99, 0, v43, s[6:7]
	v_fmac_f32_e32 v82, 0.5, v90
	s_waitcnt lgkmcnt(1)
	v_cndmask_b32_e64 v33, v32, v96, s[8:9]
	v_sub_f32_e32 v44, v44, v54
	v_cndmask_b32_e64 v93, 0, v38, s[86:87]
	v_fmac_f32_e32 v82, 0.5, v33
	v_add_f32_e32 v33, v91, v92
	ds_bpermute_b32 v36, v113, v99
	v_exp_f32_e32 v44, v44
	v_add_f32_e32 v83, v93, v33
	v_cndmask_b32_e64 v95, 0, v40, s[46:47]
	v_cndmask_b32_e64 v97, 0, v41, s[42:43]
	v_fmac_f32_e32 v83, 0.5, v94
	s_waitcnt lgkmcnt(1)
	v_cndmask_b32_e64 v32, v34, v32, s[8:9]
	v_cndmask_b32_e64 v98, 0, v42, s[38:39]
	v_fmac_f32_e32 v83, 0.5, v32
	v_add_f32_e32 v32, v95, v97
	v_add_f32_e32 v84, v98, v32
	v_cndmask_b32_e64 v44, 0, v44, s[14:15]
	v_fmac_f32_e32 v84, 0.5, v99
	s_waitcnt lgkmcnt(0)
	v_cndmask_b32_e64 v32, v36, v34, s[8:9]
	v_fmac_f32_e32 v84, 0.5, v32
	v_add_f32_e32 v32, v44, v45
	v_add_f32_e32 v85, v46, v32
	ds_read2_b64 v[32:35], v62 offset0:16 offset1:18
	ds_bpermute_b32 v96, v113, v47
	v_fmac_f32_e32 v85, 0.5, v47
	v_cvt_pk_bf16_f32 v37, v89, v90
	v_cvt_pk_bf16_f32 v38, v91, v92
	v_cvt_pk_bf16_f32 v39, v93, v94
	s_waitcnt lgkmcnt(0)
	v_cndmask_b32_e64 v36, v96, v36, s[8:9]
	v_fmac_f32_e32 v85, 0.5, v36
	v_cvt_pk_bf16_f32 v36, v87, v88
	ds_read2_b64 v[40:43], v55 offset0:80 offset1:82
	s_nop 0
	v_mfma_f32_32x32x16_bf16 v[0:15], v[32:35], v[36:39], v[0:15]
	v_add_f32_e32 v32, v87, v86
	v_add_f32_e32 v32, v88, v32
	v_add_f32_e32 v32, v89, v32
	v_add_f32_e32 v32, v90, v32
	v_add_f32_e32 v32, v91, v32
	v_add_f32_e32 v86, v92, v32
	ds_read2_b64 v[32:35], v62 offset0:20 offset1:22
	s_waitcnt lgkmcnt(1)
	v_mfma_f32_32x32x16_bf16 v[16:31], v[40:43], v[36:39], v[16:31]
	v_add_f32_e32 v36, v93, v86
	v_add_f32_e32 v86, v94, v36
	v_cvt_pk_bf16_f32 v36, v95, v97
	v_cvt_pk_bf16_f32 v37, v98, v99
	v_cvt_pk_bf16_f32 v38, v44, v45
	v_cvt_pk_bf16_f32 v39, v46, v47
	ds_read2_b64 v[40:43], v55 offset0:84 offset1:86
	s_waitcnt lgkmcnt(1)
	v_mfma_f32_32x32x16_bf16 v[0:15], v[32:35], v[36:39], v[0:15]
	v_add_f32_e32 v32, v95, v86
	v_add_f32_e32 v32, v97, v32
	v_add_f32_e32 v32, v98, v32
	v_add_f32_e32 v32, v99, v32
	v_add_f32_e32 v32, v44, v32
	v_add_f32_e32 v32, v45, v32
	v_add_f32_e32 v32, v46, v32
	s_waitcnt lgkmcnt(0)
	v_mfma_f32_32x32x16_bf16 v[16:31], v[40:43], v[36:39], v[16:31]
	v_add_f32_e32 v90, v47, v32
	ds_read_b128 v[32:35], v48 offset:13824
	ds_read_b128 v[86:89], v48 offset:13856
	v_readlane_b32 s0, v246, 46
	v_readlane_b32 s1, v246, 47
	s_waitcnt lgkmcnt(1)
	v_mfma_f32_32x32x16_bf16 v[32:47], v[32:35], v[64:67], 0
	s_waitcnt lgkmcnt(0)
	v_mfma_f32_32x32x16_bf16 v[32:47], v[86:89], v[68:71], v[32:47]
	ds_read_b128 v[86:89], v48 offset:13888
	s_waitcnt lgkmcnt(0)
	v_mfma_f32_32x32x16_bf16 v[32:47], v[86:89], v[72:75], v[32:47]
	ds_read_b128 v[86:89], v48 offset:13920
	s_waitcnt lgkmcnt(0)
	v_mfma_f32_32x32x16_bf16 v[32:47], v[86:89], v[76:79], v[32:47]
	s_nop 11
	v_sub_f32_e32 v32, v32, v54
	v_exp_f32_e32 v32, v32
	v_sub_f32_e32 v33, v33, v54
	v_exp_f32_e32 v33, v33
	v_sub_f32_e32 v34, v34, v54
	v_exp_f32_e32 v34, v34
	v_cndmask_b32_e64 v48, 0, v32, s[0:1]
	v_readlane_b32 s0, v246, 48
	v_sub_f32_e32 v35, v35, v54
	v_readlane_b32 s1, v246, 49
	v_exp_f32_e32 v35, v35
	v_sub_f32_e32 v32, v45, v54
	v_cndmask_b32_e64 v86, 0, v33, s[0:1]
	v_readlane_b32 s0, v246, 50
	v_readlane_b32 s1, v246, 51
	v_exp_f32_e32 v32, v32
	v_sub_f32_e32 v39, v39, v54
	v_cndmask_b32_e64 v87, 0, v34, s[0:1]
	v_readlane_b32 s0, v246, 52
	v_exp_f32_e32 v39, v39
	v_readlane_b32 s1, v246, 53
	v_sub_f32_e32 v33, v46, v54
	v_sub_f32_e32 v34, v47, v54
	v_cndmask_b32_e64 v88, 0, v35, s[0:1]
	v_exp_f32_e32 v33, v33
	v_exp_f32_e32 v34, v34
	v_sub_f32_e32 v36, v36, v54
	v_sub_f32_e32 v37, v37, v54
	v_sub_f32_e32 v43, v43, v54
	v_cndmask_b32_e64 v45, 0, v32, s[28:29]
	ds_bpermute_b32 v32, v113, v88
	v_sub_f32_e32 v38, v38, v54
	v_exp_f32_e32 v36, v36
	v_exp_f32_e32 v37, v37
	v_exp_f32_e32 v43, v43
	v_exp_f32_e32 v38, v38
	v_cndmask_b32_e64 v93, 0, v39, s[78:79]
	v_sub_f32_e32 v40, v40, v54
	v_sub_f32_e32 v41, v41, v54
	v_cndmask_b32_e64 v46, 0, v33, s[26:27]
	v_cndmask_b32_e64 v47, 0, v34, s[30:31]
	v_add_f32_e32 v33, v48, v86
	ds_bpermute_b32 v34, v113, v93
	v_sub_f32_e32 v42, v42, v54
	v_sub_f32_e32 v44, v44, v54
	v_exp_f32_e32 v40, v40
	v_exp_f32_e32 v41, v41
	v_add_f32_e32 v54, v87, v33
	v_exp_f32_e32 v42, v42
	v_cndmask_b32_e64 v89, 0, v36, s[64:65]
	v_cndmask_b32_e64 v91, 0, v37, s[68:69]
	v_cndmask_b32_e64 v98, 0, v43, s[22:23]
	v_fmac_f32_e32 v54, 0.5, v88
	s_waitcnt lgkmcnt(1)
	v_cndmask_b32_e64 v33, v32, v96, s[8:9]
	v_cndmask_b32_e64 v92, 0, v38, s[72:73]
	v_fmac_f32_e32 v54, 0.5, v33
	v_add_f32_e32 v33, v89, v91
	ds_bpermute_b32 v36, v113, v98
	v_exp_f32_e32 v44, v44
	v_add_f32_e32 v96, v92, v33
	v_cndmask_b32_e64 v94, 0, v40, s[48:49]
	v_cndmask_b32_e64 v95, 0, v41, s[90:91]
	v_fmac_f32_e32 v96, 0.5, v93
	s_waitcnt lgkmcnt(1)
	v_cndmask_b32_e64 v32, v34, v32, s[8:9]
	v_cndmask_b32_e64 v97, 0, v42, s[96:97]
	v_fmac_f32_e32 v96, 0.5, v32
	v_add_f32_e32 v32, v94, v95
	v_add_f32_e32 v99, v97, v32
	v_cndmask_b32_e64 v44, 0, v44, s[24:25]
	v_fmac_f32_e32 v99, 0.5, v98
	s_waitcnt lgkmcnt(0)
	v_cndmask_b32_e64 v32, v36, v34, s[8:9]
	v_fmac_f32_e32 v99, 0.5, v32
	v_add_f32_e32 v32, v44, v45
	v_add_f32_e32 v100, v46, v32
	ds_read2_b64 v[32:35], v62 offset0:24 offset1:26
	ds_bpermute_b32 v37, v113, v47
	v_fmac_f32_e32 v100, 0.5, v47
	v_cvt_pk_bf16_f32 v38, v89, v91
	v_cvt_pk_bf16_f32 v39, v92, v93
	ds_read2_b64 v[40:43], v55 offset0:88 offset1:90
	s_waitcnt lgkmcnt(1)
	v_cndmask_b32_e64 v36, v37, v36, s[8:9]
	v_fmac_f32_e32 v100, 0.5, v36
	v_cvt_pk_bf16_f32 v36, v48, v86
	v_cvt_pk_bf16_f32 v37, v87, v88
	s_nop 1
	v_mfma_f32_32x32x16_bf16 v[0:15], v[32:35], v[36:39], v[0:15]
	v_add_f32_e32 v32, v48, v90
	v_add_f32_e32 v32, v86, v32
	v_add_f32_e32 v32, v87, v32
	v_add_f32_e32 v32, v88, v32
	v_add_f32_e32 v32, v89, v32
	v_add_f32_e32 v48, v91, v32
	ds_read2_b64 v[32:35], v62 offset0:28 offset1:30
	s_waitcnt lgkmcnt(1)
	v_mfma_f32_32x32x16_bf16 v[16:31], v[40:43], v[36:39], v[16:31]
	v_add_f32_e32 v36, v92, v48
	v_add_f32_e32 v48, v93, v36
	v_cvt_pk_bf16_f32 v36, v94, v95
	v_cvt_pk_bf16_f32 v37, v97, v98
	v_cvt_pk_bf16_f32 v38, v44, v45
	v_cvt_pk_bf16_f32 v39, v46, v47
	ds_read2_b64 v[40:43], v55 offset0:92 offset1:94
	s_waitcnt lgkmcnt(1)
	v_mfma_f32_32x32x16_bf16 v[0:15], v[32:35], v[36:39], v[0:15]
	v_add_f32_e32 v32, v94, v48
	v_add_f32_e32 v32, v95, v32
	v_add_f32_e32 v32, v97, v32
	v_add_f32_e32 v32, v98, v32
	v_add_f32_e32 v32, v44, v32
	v_add_f32_e32 v32, v45, v32
	v_add_f32_e32 v32, v46, v32
	s_waitcnt lgkmcnt(0)
	v_mfma_f32_32x32x16_bf16 v[16:31], v[40:43], v[36:39], v[16:31]
	v_add_f32_e32 v32, v47, v32
	ds_bpermute_b32 v33, v113, v32
	v_cmp_ne_u32_e64 s[4:5], 0, v161
	v_cmp_lt_u32_e64 s[6:7], 1, v161
	v_cmp_lt_u32_e64 s[8:9], 2, v161
	v_cmp_lt_u32_e64 s[14:15], 3, v161
	s_waitcnt lgkmcnt(0)
	v_add_f32_e32 v32, v32, v33
	v_div_scale_f32 v33, s[2:3], v32, v32, 1.0
	v_rcp_f32_e32 v34, v33
	v_cmp_lt_f32_e64 s[0:1], 0, v32
	v_cmp_eq_u32_e64 s[2:3], s84, v161
	v_cmp_lt_u32_e64 s[16:17], 4, v161
	v_fma_f32 v35, -v33, v34, 1.0
	v_fmac_f32_e32 v34, v35, v34
	v_div_scale_f32 v35, vcc, 1.0, v32, 1.0
	v_mul_f32_e32 v36, v35, v34
	v_fma_f32 v37, -v33, v36, v35
	v_fmac_f32_e32 v36, v37, v34
	v_fma_f32 v33, -v33, v36, v35
	v_div_fmas_f32 v33, v33, v34, v36
	v_div_fixup_f32 v32, v33, v32, 1.0
	v_cndmask_b32_e64 v32, 0, v32, s[0:1]
	v_lshlrev_b32_e32 v33, 7, v128
	v_readlane_b32 s0, v247, 45
	v_mul_f32_e32 v34, v53, v32
	v_mul_f32_e32 v35, v49, v32
	v_add3_u32 v33, s0, v33, v125
	v_add_u32_e32 v33, 0x9000, v33
	ds_write2_b32 v33, v34, v35 offset1:2
	v_mul_f32_e32 v34, v50, v32
	v_mul_f32_e32 v35, v51, v32
	ds_write2_b32 v33, v34, v35 offset0:4 offset1:6
	v_mul_f32_e32 v34, v52, v32
	v_mul_f32_e32 v35, v63, v32
	ds_write2_b32 v33, v34, v35 offset0:8 offset1:10
	v_mul_f32_e32 v34, v80, v32
	v_mul_f32_e32 v35, v81, v32
	ds_write2_b32 v33, v34, v35 offset0:12 offset1:14
	v_mul_f32_e32 v34, v82, v32
	v_mul_f32_e32 v35, v83, v32
	ds_write2_b32 v33, v34, v35 offset0:16 offset1:18
	v_mul_f32_e32 v34, v84, v32
	v_mul_f32_e32 v35, v85, v32
	ds_write2_b32 v33, v34, v35 offset0:20 offset1:22
	v_mul_f32_e32 v34, v54, v32
	v_mul_f32_e32 v35, v96, v32
	ds_write2_b32 v33, v34, v35 offset0:24 offset1:26
	v_mul_f32_e32 v34, v99, v32
	v_mul_f32_e32 v35, v100, v32
	ds_write2_b32 v33, v34, v35 offset0:28 offset1:30
	v_mul_f32_e32 v36, v162, v32
	ds_read2st64_b32 v[32:33], v112 offset1:1
	ds_read2st64_b32 v[34:35], v112 offset0:16 offset1:17
	v_cmp_eq_u32_e64 s[0:1], 0, v161
	s_or_b64 s[2:3], s[0:1], s[2:3]
	s_add_i32 s0, s84, -1
	s_waitcnt lgkmcnt(1)
	v_fma_f32 v0, v0, v36, v32
	s_waitcnt lgkmcnt(0)
	v_fma_f32 v16, v16, v36, v34
	v_fmac_f32_e32 v33, v1, v36
	v_fmac_f32_e32 v35, v17, v36
	ds_write2st64_b32 v112, v0, v33 offset1:1
	ds_write2st64_b32 v112, v16, v35 offset0:16 offset1:17
	ds_read2st64_b32 v[0:1], v112 offset0:2 offset1:3
	ds_read2st64_b32 v[16:17], v112 offset0:18 offset1:19
	v_cmp_eq_u32_e64 s[0:1], s0, v161
	v_cmp_ge_u32_e32 vcc, s84, v161
	s_or_b64 s[0:1], s[2:3], s[0:1]
	s_waitcnt lgkmcnt(1)
	v_fma_f32 v0, v2, v36, v0
	s_waitcnt lgkmcnt(0)
	v_fma_f32 v2, v18, v36, v16
	v_fmac_f32_e32 v1, v3, v36
	v_fmac_f32_e32 v17, v19, v36
	ds_write2st64_b32 v112, v0, v1 offset0:2 offset1:3
	ds_write2st64_b32 v112, v2, v17 offset0:18 offset1:19
	ds_read2st64_b32 v[0:1], v112 offset0:4 offset1:5
	ds_read2st64_b32 v[2:3], v112 offset0:20 offset1:21
	v_cmp_gt_i32_e64 s[2:3], 32, v59
	v_cmp_lt_u32_e64 s[18:19], 5, v161
	v_cmp_lt_u32_e64 s[20:21], 6, v161
	s_waitcnt lgkmcnt(1)
	v_fma_f32 v0, v4, v36, v0
	s_waitcnt lgkmcnt(0)
	v_fma_f32 v2, v20, v36, v2
	v_fmac_f32_e32 v1, v5, v36
	v_fmac_f32_e32 v3, v21, v36
	ds_write2st64_b32 v112, v0, v1 offset0:4 offset1:5
	ds_write2st64_b32 v112, v2, v3 offset0:20 offset1:21
	ds_read2st64_b32 v[0:1], v112 offset0:6 offset1:7
	ds_read2st64_b32 v[2:3], v112 offset0:22 offset1:23
	v_cmp_lt_u32_e64 s[22:23], 7, v161
	v_cmp_lt_u32_e64 s[24:25], 8, v161
	v_cmp_lt_u32_e64 s[26:27], 9, v161
	s_waitcnt lgkmcnt(1)
	v_fma_f32 v0, v6, v36, v0
	s_waitcnt lgkmcnt(0)
	v_fma_f32 v2, v22, v36, v2
	v_fmac_f32_e32 v1, v7, v36
	v_fmac_f32_e32 v3, v23, v36
	ds_write2st64_b32 v112, v0, v1 offset0:6 offset1:7
	ds_write2st64_b32 v112, v2, v3 offset0:22 offset1:23
	ds_read2st64_b32 v[0:1], v112 offset0:8 offset1:9
	ds_read2st64_b32 v[2:3], v112 offset0:24 offset1:25
	v_cmp_lt_u32_e64 s[28:29], 10, v161
	v_cmp_lt_u32_e64 s[30:31], 11, v161
	v_cmp_lt_u32_e64 s[34:35], 12, v161
	s_waitcnt lgkmcnt(1)
	v_fma_f32 v0, v8, v36, v0
	s_waitcnt lgkmcnt(0)
	v_fma_f32 v2, v24, v36, v2
	v_fmac_f32_e32 v1, v9, v36
	v_fmac_f32_e32 v3, v25, v36
	ds_write2st64_b32 v112, v0, v1 offset0:8 offset1:9
	ds_write2st64_b32 v112, v2, v3 offset0:24 offset1:25
	ds_read2st64_b32 v[0:1], v112 offset0:10 offset1:11
	ds_read2st64_b32 v[2:3], v112 offset0:26 offset1:27
	v_cmp_lt_u32_e64 s[36:37], 13, v161
	v_cmp_lt_u32_e64 s[38:39], 14, v161
	v_cmp_lt_u32_e64 s[40:41], 15, v161
	s_waitcnt lgkmcnt(1)
	v_fma_f32 v0, v10, v36, v0
	s_waitcnt lgkmcnt(0)
	v_fma_f32 v2, v26, v36, v2
	v_fmac_f32_e32 v1, v11, v36
	v_fmac_f32_e32 v3, v27, v36
	ds_write2st64_b32 v112, v0, v1 offset0:10 offset1:11
	ds_write2st64_b32 v112, v2, v3 offset0:26 offset1:27
	ds_read2st64_b32 v[0:1], v112 offset0:12 offset1:13
	ds_read2st64_b32 v[2:3], v112 offset0:28 offset1:29
	v_cmp_lt_u32_e64 s[42:43], 16, v161
	v_cmp_lt_u32_e64 s[44:45], 17, v161
	v_cmp_lt_u32_e64 s[46:47], 18, v161
	s_waitcnt lgkmcnt(1)
	v_fma_f32 v0, v12, v36, v0
	s_waitcnt lgkmcnt(0)
	v_fma_f32 v2, v28, v36, v2
	v_fmac_f32_e32 v1, v13, v36
	v_fmac_f32_e32 v3, v29, v36
	ds_write2st64_b32 v112, v0, v1 offset0:12 offset1:13
	ds_write2st64_b32 v112, v2, v3 offset0:28 offset1:29
	ds_read2st64_b32 v[0:1], v112 offset0:14 offset1:15
	ds_read2st64_b32 v[2:3], v112 offset0:30 offset1:31
	v_cmp_lt_u32_e64 s[48:49], 19, v161
	v_cmp_lt_u32_e64 s[50:51], 20, v161
	v_cmp_lt_u32_e64 s[52:53], 21, v161
	s_waitcnt lgkmcnt(1)
	v_fma_f32 v0, v14, v36, v0
	s_waitcnt lgkmcnt(0)
	v_fma_f32 v2, v30, v36, v2
	v_fmac_f32_e32 v3, v31, v36
	v_fmac_f32_e32 v1, v15, v36
	ds_write2st64_b32 v112, v2, v3 offset0:30 offset1:31
	v_cmp_lt_u32_e64 s[54:55], 22, v161
	v_cmp_lt_u32_e64 s[56:57], 23, v161
	v_cmp_lt_u32_e64 s[58:59], 24, v161
	v_cmp_lt_u32_e64 s[60:61], 25, v161
	v_cmp_lt_u32_e64 s[62:63], 26, v161
	v_cmp_lt_u32_e64 s[64:65], 27, v161
	v_cmp_lt_u32_e64 s[66:67], 28, v161
	v_cmp_lt_u32_e64 s[68:69], 29, v161
	v_cmp_eq_u32_e64 s[70:71], 31, v161
	v_lshl_add_u32 v2, v161, 2, 0
	ds_write2st64_b32 v112, v0, v1 offset0:14 offset1:15
	s_waitcnt lgkmcnt(0)
	s_barrier
	s_branch .LBB0_498
